# tile-boundary barrier realignment plus removal of the per-phase s_setprio flips in all twelve GEMM K-loops
# speedup vs baseline: 1.0060x; 1.0060x over previous
; #define PG8_STAGE(bufoff, gbase, voff) do { _Pragma("unroll") for (int _i = 0; _i < 2; ++_i) \
;     __builtin_amdgcn_global_load_lds((const unsigned*)((const char*)(gbase) + (voff)[_i]), (LAS unsigned*)(lds + (bufoff) + ldsw + _i * 8192), 16, 0, 0); } while (0)
; #define PG8_LDA(dst, b, h) do { _Pragma("unroll") for (int m = 0; m < 4; ++m) _Pragma("unroll") for (int k = 0; k < 2; ++k) dst[m][k] = *(const LAS bf16x8*)(lds + PG8_SA(b, h) + aoff + m * 2048 + k * 1024); } while (0)
; #define PG8_LDB(dst, b, h) do { _Pragma("unroll") for (int n = 0; n < 2; ++n) _Pragma("unroll") for (int k = 0; k < 2; ++k) dst[n][k] = *(const LAS bf16x8*)(lds + PG8_SB(b, h) + boff + n * 2048 + k * 1024); } while (0)
; #define PG8_MMA(ai, bj, At, Bt) do { __builtin_amdgcn_s_setprio(1); _Pragma("unroll") for (int m = 0; m < 4; ++m) _Pragma("unroll") for (int n = 0; n < 2; ++n) _Pragma("unroll") for (int k = 0; k < 2; ++k) \
;     acc[ai][bj][m][n] = __builtin_amdgcn_mfma_f32_16x16x32_bf16(Bt[n][k], At[m][k], acc[ai][bj][m][n], 0, 0, 0); __builtin_amdgcn_s_setprio(0); } while (0)
; #define PG8_WAIT_L(n) asm volatile("s_waitcnt lgkmcnt(" #n ")" ::: "memory")
; #define PG8_BAR __builtin_amdgcn_s_barrier()
; #define PG8_SCHED __builtin_amdgcn_sched_barrier(0)
; template <class Epi, class Sched>
; __device__ __forceinline__ void gemm_phase(LAS unsigned char* lds, const Gemm g, const Sched& S, const Epi& E) {
;     ...
;     for (int t = 0; t < nt; t += 2) {
;       const bool last = (t == nt - 2);
;       const char* a1 = cA + (size_t)(t + 1) * kstep;
;       const char* a2 = last ? nA : cA + (size_t)(t + 2) * kstep; const char* b2 = last ? nB : cB + (size_t)(t + 2) * kstep;
;       const char* a3 = a2 + kstep; const char* b3 = b2 + kstep;
;       if (last && has_next) S.a_ready(nxt);
;       PG8_LDB(B0, 0, 0); PG8_SCHED; PG8_LDA(At, 0, 0); PG8_STAGE(PG8_SA(1, 1), a1 + hstep, voffA);
;       PG8_WAIT_L(8); PG8_BAR; PG8_WAIT_L(0); PG8_MMA(0, 0, At, B0); PG8_BAR; PG8_SCHED;
;       PG8_LDB(B1, 0, 1); PG8_STAGE(PG8_SB(0, 0), b2, voffB);
;       PG8_BAR; PG8_WAIT_L(0); PG8_MMA(0, 1, At, B1); PG8_BAR;
;       PG8_LDA(At, 0, 1); PG8_STAGE(PG8_SA(0, 0), a2, voffA);
;       PG8_BAR; PG8_WAIT_L(0); PG8_MMA(1, 0, At, B0); PG8_BAR; PG8_SCHED;
.Lxs_e0:
.LBB0_208:
	s_add_u32 s44, s42, 0xfffc0080
	s_addc_u32 s45, s43, -1
	s_add_i32 s73, 0, 0x10000
	v_add_u32_e32 v151, s73, v141
	ds_read_b128 v[152:155], v151
	ds_read_b128 v[156:159], v151 offset:1024
	ds_read_b128 v[174:177], v151 offset:2048
	ds_read_b128 v[178:181], v151 offset:3072
	s_cmp_eq_u32 s72, 12
	s_cselect_b32 vcc_hi, s35, s45
	s_cselect_b32 vcc_lo, s69, s44
	s_cselect_b32 s45, s23, s52
	s_cselect_b32 s44, s70, s71
	v_lshl_add_u64 v[226:227], s[42:43], 0, v[136:137]
	s_add_i32 m0, s12, 0xc000
	ds_read_b128 v[182:185], v150
	ds_read_b128 v[186:189], v150 offset:1024
	ds_read_b128 v[190:193], v150 offset:2048
	ds_read_b128 v[194:197], v150 offset:3072
	ds_read_b128 v[198:201], v150 offset:4096
	ds_read_b128 v[202:205], v150 offset:5120
	ds_read_b128 v[206:209], v150 offset:6144
	ds_read_b128 v[210:213], v150 offset:7168
	global_load_lds_dwordx4 v[226:227], off
	v_lshl_add_u64 v[226:227], s[42:43], 0, v[138:139]
	s_add_i32 m0, s12, 0xe000
	s_nop 0
	global_load_lds_dwordx4 v[226:227], off
	s_waitcnt lgkmcnt(8)
	s_barrier
	s_waitcnt lgkmcnt(0)
	s_waitcnt lgkmcnt(0)
	v_mfma_f32_16x16x32_bf16 v[124:127], v[152:155], v[182:185], v[124:127]
	v_mfma_f32_16x16x32_bf16 v[116:119], v[174:177], v[182:185], v[116:119]
	v_mfma_f32_16x16x32_bf16 v[108:111], v[152:155], v[190:193], v[108:111]
	v_mfma_f32_16x16x32_bf16 v[100:103], v[174:177], v[190:193], v[100:103]
	v_mfma_f32_16x16x32_bf16 v[92:95], v[152:155], v[198:201], v[92:95]
	v_mfma_f32_16x16x32_bf16 v[84:87], v[174:177], v[198:201], v[84:87]
	v_mfma_f32_16x16x32_bf16 v[76:79], v[152:155], v[206:209], v[76:79]
	v_mfma_f32_16x16x32_bf16 v[68:71], v[174:177], v[206:209], v[68:71]
	v_mfma_f32_16x16x32_bf16 v[124:127], v[156:159], v[186:189], v[124:127]
	v_mfma_f32_16x16x32_bf16 v[116:119], v[178:181], v[186:189], v[116:119]
	v_mfma_f32_16x16x32_bf16 v[108:111], v[156:159], v[194:197], v[108:111]
	v_mfma_f32_16x16x32_bf16 v[100:103], v[178:181], v[194:197], v[100:103]
	v_mfma_f32_16x16x32_bf16 v[92:95], v[156:159], v[202:205], v[92:95]
	v_mfma_f32_16x16x32_bf16 v[84:87], v[178:181], v[202:205], v[84:87]
	v_mfma_f32_16x16x32_bf16 v[76:79], v[156:159], v[210:213], v[76:79]
	v_mfma_f32_16x16x32_bf16 v[68:71], v[178:181], v[210:213], v[68:71]
	s_barrier
	s_add_i32 s76, 0, 0x14000
	s_add_i32 s73, s73, s7
	v_add_u32_e32 v151, s76, v141
	v_lshl_add_u64 v[244:245], s[44:45], 0, v[132:133]
	s_mov_b32 m0, s73
	ds_read_b128 v[226:229], v151
	ds_read_b128 v[232:235], v151 offset:1024
	ds_read_b128 v[236:239], v151 offset:2048
	ds_read_b128 v[240:243], v151 offset:3072
	global_load_lds_dwordx4 v[244:245], off
	v_lshl_add_u64 v[246:247], s[44:45], 0, v[128:129]
	s_add_i32 m0, s73, 0x2000
	s_nop 0
	global_load_lds_dwordx4 v[246:247], off
	s_barrier
	s_waitcnt lgkmcnt(0)
	s_waitcnt lgkmcnt(0)
	v_mfma_f32_16x16x32_bf16 v[120:123], v[226:229], v[182:185], v[120:123]
	v_mfma_f32_16x16x32_bf16 v[112:115], v[236:239], v[182:185], v[112:115]
	v_mfma_f32_16x16x32_bf16 v[104:107], v[226:229], v[190:193], v[104:107]
	v_mfma_f32_16x16x32_bf16 v[96:99], v[236:239], v[190:193], v[96:99]
	v_mfma_f32_16x16x32_bf16 v[88:91], v[226:229], v[198:201], v[88:91]
	v_mfma_f32_16x16x32_bf16 v[80:83], v[236:239], v[198:201], v[80:83]
	v_mfma_f32_16x16x32_bf16 v[72:75], v[226:229], v[206:209], v[72:75]
	v_mfma_f32_16x16x32_bf16 v[64:67], v[236:239], v[206:209], v[64:67]
	v_mfma_f32_16x16x32_bf16 v[120:123], v[232:235], v[186:189], v[120:123]
	v_mfma_f32_16x16x32_bf16 v[112:115], v[240:243], v[186:189], v[112:115]
	v_mfma_f32_16x16x32_bf16 v[104:107], v[232:235], v[194:197], v[104:107]
	v_mfma_f32_16x16x32_bf16 v[96:99], v[240:243], v[194:197], v[96:99]
	v_mfma_f32_16x16x32_bf16 v[88:91], v[232:235], v[202:205], v[88:91]
	v_mfma_f32_16x16x32_bf16 v[80:83], v[240:243], v[202:205], v[80:83]
	v_mfma_f32_16x16x32_bf16 v[72:75], v[232:235], v[210:213], v[72:75]
	v_mfma_f32_16x16x32_bf16 v[64:67], v[240:243], v[210:213], v[64:67]
	s_mov_b32 m0, s12
	v_lshl_add_u64 v[248:249], vcc, 0, v[134:135]
	s_barrier
	ds_read_b128 v[182:185], v150 offset:16384
	ds_read_b128 v[186:189], v150 offset:17408
	ds_read_b128 v[190:193], v150 offset:18432
	ds_read_b128 v[194:197], v150 offset:19456
	ds_read_b128 v[198:201], v150 offset:20480
	ds_read_b128 v[202:205], v150 offset:21504
	ds_read_b128 v[206:209], v150 offset:22528
	ds_read_b128 v[210:213], v150 offset:23552
	global_load_lds_dwordx4 v[248:249], off
	v_lshl_add_u64 v[222:223], vcc, 0, v[130:131]
	s_mov_b32 m0, s13
	s_nop 0
	global_load_lds_dwordx4 v[222:223], off
	s_barrier
	s_waitcnt lgkmcnt(0)
	s_waitcnt lgkmcnt(0)
	v_mfma_f32_16x16x32_bf16 v[60:63], v[152:155], v[182:185], v[60:63]
	v_mfma_f32_16x16x32_bf16 v[52:55], v[174:177], v[182:185], v[52:55]
	v_mfma_f32_16x16x32_bf16 v[44:47], v[152:155], v[190:193], v[44:47]
	v_mfma_f32_16x16x32_bf16 v[36:39], v[174:177], v[190:193], v[36:39]
	v_mfma_f32_16x16x32_bf16 v[28:31], v[152:155], v[198:201], v[28:31]
	v_mfma_f32_16x16x32_bf16 v[20:23], v[174:177], v[198:201], v[20:23]
	v_mfma_f32_16x16x32_bf16 v[12:15], v[152:155], v[206:209], v[12:15]
	v_mfma_f32_16x16x32_bf16 v[4:7], v[174:177], v[206:209], v[4:7]
	v_mfma_f32_16x16x32_bf16 v[60:63], v[156:159], v[186:189], v[60:63]
	v_mfma_f32_16x16x32_bf16 v[52:55], v[178:181], v[186:189], v[52:55]
	v_mfma_f32_16x16x32_bf16 v[44:47], v[156:159], v[194:197], v[44:47]
	v_mfma_f32_16x16x32_bf16 v[36:39], v[178:181], v[194:197], v[36:39]
	v_mfma_f32_16x16x32_bf16 v[28:31], v[156:159], v[202:205], v[28:31]
	v_mfma_f32_16x16x32_bf16 v[20:23], v[178:181], v[202:205], v[20:23]
	v_mfma_f32_16x16x32_bf16 v[12:15], v[156:159], v[210:213], v[12:15]
	v_mfma_f32_16x16x32_bf16 v[4:7], v[178:181], v[210:213], v[4:7]
	s_barrier
; #define PG8_STAGE(bufoff, gbase, voff) do { _Pragma("unroll") for (int _i = 0; _i < 2; ++_i) \
;     __builtin_amdgcn_global_load_lds((const unsigned*)((const char*)(gbase) + (voff)[_i]), (LAS unsigned*)(lds + (bufoff) + ldsw + _i * 8192), 16, 0, 0); } while (0)
; #define PG8_LDA(dst, b, h) do { _Pragma("unroll") for (int m = 0; m < 4; ++m) _Pragma("unroll") for (int k = 0; k < 2; ++k) dst[m][k] = *(const LAS bf16x8*)(lds + PG8_SA(b, h) + aoff + m * 2048 + k * 1024); } while (0)
; #define PG8_LDB(dst, b, h) do { _Pragma("unroll") for (int n = 0; n < 2; ++n) _Pragma("unroll") for (int k = 0; k < 2; ++k) dst[n][k] = *(const LAS bf16x8*)(lds + PG8_SB(b, h) + boff + n * 2048 + k * 1024); } while (0)
; #define PG8_MMA(ai, bj, At, Bt) do { __builtin_amdgcn_s_setprio(1); _Pragma("unroll") for (int m = 0; m < 4; ++m) _Pragma("unroll") for (int n = 0; n < 2; ++n) _Pragma("unroll") for (int k = 0; k < 2; ++k) \
;     acc[ai][bj][m][n] = __builtin_amdgcn_mfma_f32_16x16x32_bf16(Bt[n][k], At[m][k], acc[ai][bj][m][n], 0, 0, 0); __builtin_amdgcn_s_setprio(0); } while (0)
; #define PG8_WAIT_V(n) asm volatile("s_waitcnt vmcnt(" #n ")" ::: "memory")
; #define PG8_WAIT_L(n) asm volatile("s_waitcnt lgkmcnt(" #n ")" ::: "memory")
; #define PG8_BAR __builtin_amdgcn_s_barrier()
; #define PG8_SCHED __builtin_amdgcn_sched_barrier(0)
; template <class Epi, class Sched>
; __device__ __forceinline__ void gemm_phase(LAS unsigned char* lds, const Gemm g, const Sched& S, const Epi& E) {
;     ...
;       PG8_STAGE(PG8_SB(0, 1), b2 + hstep, voffB);
;       PG8_WAIT_V(6); PG8_BAR; PG8_MMA(1, 1, At, B1); PG8_BAR;
;       PG8_LDB(B0, 1, 0); PG8_SCHED; PG8_LDA(At, 1, 0); PG8_STAGE(PG8_SA(0, 1), a2 + hstep, voffA);
;       PG8_WAIT_L(8); PG8_BAR; PG8_WAIT_L(0); PG8_MMA(0, 0, At, B0); PG8_BAR; PG8_SCHED;
;       PG8_LDB(B1, 1, 1); PG8_STAGE(PG8_SB(1, 0), b3, voffB);
	s_add_u32 s74, s44, 0x40000
	s_addc_u32 s75, s45, 0
	s_add_i32 s73, s76, s7
	v_lshl_add_u64 v[152:153], s[74:75], 0, v[132:133]
	s_mov_b32 m0, s73
	s_nop 0
	global_load_lds_dwordx4 v[152:153], off
	v_lshl_add_u64 v[152:153], s[74:75], 0, v[128:129]
	s_add_i32 m0, s73, 0x2000
	s_nop 0
	global_load_lds_dwordx4 v[152:153], off
	s_waitcnt vmcnt(6)
	s_barrier
	v_mfma_f32_16x16x32_bf16 v[56:59], v[226:229], v[182:185], v[56:59]
	v_mfma_f32_16x16x32_bf16 v[48:51], v[236:239], v[182:185], v[48:51]
	v_mfma_f32_16x16x32_bf16 v[40:43], v[226:229], v[190:193], v[40:43]
	v_mfma_f32_16x16x32_bf16 v[32:35], v[236:239], v[190:193], v[32:35]
	v_mfma_f32_16x16x32_bf16 v[24:27], v[226:229], v[198:201], v[24:27]
	v_mfma_f32_16x16x32_bf16 v[16:19], v[236:239], v[198:201], v[16:19]
	v_mfma_f32_16x16x32_bf16 v[8:11], v[226:229], v[206:209], v[8:11]
	v_mfma_f32_16x16x32_bf16 v[0:3], v[236:239], v[206:209], v[0:3]
	v_mfma_f32_16x16x32_bf16 v[56:59], v[232:235], v[186:189], v[56:59]
	v_mfma_f32_16x16x32_bf16 v[48:51], v[240:243], v[186:189], v[48:51]
	v_mfma_f32_16x16x32_bf16 v[40:43], v[232:235], v[194:197], v[40:43]
	v_mfma_f32_16x16x32_bf16 v[32:35], v[240:243], v[194:197], v[32:35]
	v_mfma_f32_16x16x32_bf16 v[24:27], v[232:235], v[202:205], v[24:27]
	v_mfma_f32_16x16x32_bf16 v[16:19], v[240:243], v[202:205], v[16:19]
	v_mfma_f32_16x16x32_bf16 v[8:11], v[232:235], v[210:213], v[8:11]
	v_mfma_f32_16x16x32_bf16 v[0:3], v[240:243], v[210:213], v[0:3]
	s_add_i32 s73, 0, 0x18000
	v_add_u32_e32 v151, s73, v141
	s_barrier
	ds_read_b128 v[152:155], v151
	ds_read_b128 v[156:159], v151 offset:1024
	ds_read_b128 v[174:177], v151 offset:2048
	ds_read_b128 v[178:181], v151 offset:3072
	s_add_u32 s74, vcc_lo, 0x40000
	s_addc_u32 s75, vcc_hi, 0
	s_mov_b32 m0, s48
	v_lshl_add_u64 v[226:227], s[74:75], 0, v[134:135]
	ds_read_b128 v[182:185], v150 offset:32768
	ds_read_b128 v[186:189], v150 offset:33792
	ds_read_b128 v[190:193], v150 offset:34816
	ds_read_b128 v[194:197], v150 offset:35840
	ds_read_b128 v[198:201], v150 offset:36864
	ds_read_b128 v[202:205], v150 offset:37888
	ds_read_b128 v[206:209], v150 offset:38912
	ds_read_b128 v[210:213], v150 offset:39936
	global_load_lds_dwordx4 v[226:227], off
	v_lshl_add_u64 v[226:227], s[74:75], 0, v[130:131]
	s_mov_b32 m0, s49
	s_nop 0
	global_load_lds_dwordx4 v[226:227], off
	s_waitcnt lgkmcnt(8)
	s_barrier
	s_waitcnt lgkmcnt(0)
	s_waitcnt lgkmcnt(0)
	v_mfma_f32_16x16x32_bf16 v[124:127], v[152:155], v[182:185], v[124:127]
	v_mfma_f32_16x16x32_bf16 v[116:119], v[174:177], v[182:185], v[116:119]
	v_mfma_f32_16x16x32_bf16 v[108:111], v[152:155], v[190:193], v[108:111]
	v_mfma_f32_16x16x32_bf16 v[100:103], v[174:177], v[190:193], v[100:103]
	v_mfma_f32_16x16x32_bf16 v[92:95], v[152:155], v[198:201], v[92:95]
	v_mfma_f32_16x16x32_bf16 v[84:87], v[174:177], v[198:201], v[84:87]
	v_mfma_f32_16x16x32_bf16 v[76:79], v[152:155], v[206:209], v[76:79]
	v_mfma_f32_16x16x32_bf16 v[68:71], v[174:177], v[206:209], v[68:71]
	v_mfma_f32_16x16x32_bf16 v[124:127], v[156:159], v[186:189], v[124:127]
	v_mfma_f32_16x16x32_bf16 v[116:119], v[178:181], v[186:189], v[116:119]
	v_mfma_f32_16x16x32_bf16 v[108:111], v[156:159], v[194:197], v[108:111]
	v_mfma_f32_16x16x32_bf16 v[100:103], v[178:181], v[194:197], v[100:103]
	v_mfma_f32_16x16x32_bf16 v[92:95], v[156:159], v[202:205], v[92:95]
	v_mfma_f32_16x16x32_bf16 v[84:87], v[178:181], v[202:205], v[84:87]
	v_mfma_f32_16x16x32_bf16 v[76:79], v[156:159], v[210:213], v[76:79]
	v_mfma_f32_16x16x32_bf16 v[68:71], v[178:181], v[210:213], v[68:71]
	s_barrier
	s_add_i32 s74, 0, 0x1c000
	s_add_i32 s73, s73, s7
	v_add_u32_e32 v151, s74, v141
	v_lshl_add_u64 v[244:245], v[244:245], 0, s[80:81]
	s_mov_b32 m0, s73
	ds_read_b128 v[226:229], v151
	ds_read_b128 v[232:235], v151 offset:1024
	ds_read_b128 v[236:239], v151 offset:2048
	ds_read_b128 v[240:243], v151 offset:3072
	global_load_lds_dwordx4 v[244:245], off
	v_lshl_add_u64 v[244:245], v[246:247], 0, s[80:81]
	s_add_i32 m0, s73, 0x2000
	s_nop 0
	global_load_lds_dwordx4 v[244:245], off
	s_barrier
; #define PG8_STAGE(bufoff, gbase, voff) do { _Pragma("unroll") for (int _i = 0; _i < 2; ++_i) \
;     __builtin_amdgcn_global_load_lds((const unsigned*)((const char*)(gbase) + (voff)[_i]), (LAS unsigned*)(lds + (bufoff) + ldsw + _i * 8192), 16, 0, 0); } while (0)
; #define PG8_LDA(dst, b, h) do { _Pragma("unroll") for (int m = 0; m < 4; ++m) _Pragma("unroll") for (int k = 0; k < 2; ++k) dst[m][k] = *(const LAS bf16x8*)(lds + PG8_SA(b, h) + aoff + m * 2048 + k * 1024); } while (0)
; #define PG8_MMA(ai, bj, At, Bt) do { __builtin_amdgcn_s_setprio(1); _Pragma("unroll") for (int m = 0; m < 4; ++m) _Pragma("unroll") for (int n = 0; n < 2; ++n) _Pragma("unroll") for (int k = 0; k < 2; ++k) \
;     acc[ai][bj][m][n] = __builtin_amdgcn_mfma_f32_16x16x32_bf16(Bt[n][k], At[m][k], acc[ai][bj][m][n], 0, 0, 0); __builtin_amdgcn_s_setprio(0); } while (0)
; #define PG8_WAIT_V(n) asm volatile("s_waitcnt vmcnt(" #n ")" ::: "memory")
; #define PG8_WAIT_L(n) asm volatile("s_waitcnt lgkmcnt(" #n ")" ::: "memory")
; #define PG8_BAR __builtin_amdgcn_s_barrier()
; #define PG8_SCHED __builtin_amdgcn_sched_barrier(0)
; template <class Epi, class Sched>
; __device__ __forceinline__ void gemm_phase(LAS unsigned char* lds, const Gemm g, const Sched& S, const Epi& E) {
;     ...
;       PG8_BAR; PG8_WAIT_L(0); PG8_MMA(0, 1, At, B1); PG8_BAR;
;       PG8_LDA(At, 1, 1); PG8_STAGE(PG8_SA(1, 0), a3, voffA);
;       PG8_BAR; PG8_WAIT_L(0); PG8_MMA(1, 0, At, B0); PG8_BAR; PG8_SCHED;
;       PG8_STAGE(PG8_SB(1, 1), b3 + hstep, voffB);
;       PG8_WAIT_V(6); PG8_BAR; PG8_MMA(1, 1, At, B1); PG8_BAR;
;     }
	s_waitcnt lgkmcnt(0)
	s_waitcnt lgkmcnt(0)
	v_mfma_f32_16x16x32_bf16 v[120:123], v[226:229], v[182:185], v[120:123]
	v_mfma_f32_16x16x32_bf16 v[112:115], v[236:239], v[182:185], v[112:115]
	v_mfma_f32_16x16x32_bf16 v[104:107], v[226:229], v[190:193], v[104:107]
	v_mfma_f32_16x16x32_bf16 v[96:99], v[236:239], v[190:193], v[96:99]
	v_mfma_f32_16x16x32_bf16 v[88:91], v[226:229], v[198:201], v[88:91]
	v_mfma_f32_16x16x32_bf16 v[80:83], v[236:239], v[198:201], v[80:83]
	v_mfma_f32_16x16x32_bf16 v[72:75], v[226:229], v[206:209], v[72:75]
	v_mfma_f32_16x16x32_bf16 v[64:67], v[236:239], v[206:209], v[64:67]
	v_mfma_f32_16x16x32_bf16 v[120:123], v[232:235], v[186:189], v[120:123]
	v_mfma_f32_16x16x32_bf16 v[112:115], v[240:243], v[186:189], v[112:115]
	v_mfma_f32_16x16x32_bf16 v[104:107], v[232:235], v[194:197], v[104:107]
	v_mfma_f32_16x16x32_bf16 v[96:99], v[240:243], v[194:197], v[96:99]
	v_mfma_f32_16x16x32_bf16 v[88:91], v[232:235], v[202:205], v[88:91]
	v_mfma_f32_16x16x32_bf16 v[80:83], v[240:243], v[202:205], v[80:83]
	v_mfma_f32_16x16x32_bf16 v[72:75], v[232:235], v[210:213], v[72:75]
	v_mfma_f32_16x16x32_bf16 v[64:67], v[240:243], v[210:213], v[64:67]
	s_mov_b32 m0, s51
	v_lshl_add_u64 v[244:245], v[248:249], 0, s[80:81]
	s_barrier
	ds_read_b128 v[182:185], v150 offset:49152
	ds_read_b128 v[186:189], v150 offset:50176
	ds_read_b128 v[190:193], v150 offset:51200
	ds_read_b128 v[194:197], v150 offset:52224
	ds_read_b128 v[198:201], v150 offset:53248
	ds_read_b128 v[202:205], v150 offset:54272
	ds_read_b128 v[206:209], v150 offset:55296
	ds_read_b128 v[210:213], v150 offset:56320
	global_load_lds_dwordx4 v[244:245], off
	v_lshl_add_u64 v[222:223], v[222:223], 0, s[80:81]
	s_mov_b32 m0, s62
	s_nop 0
	global_load_lds_dwordx4 v[222:223], off
	s_barrier
	s_waitcnt lgkmcnt(0)
	s_waitcnt lgkmcnt(0)
	v_mfma_f32_16x16x32_bf16 v[60:63], v[152:155], v[182:185], v[60:63]
	v_mfma_f32_16x16x32_bf16 v[52:55], v[174:177], v[182:185], v[52:55]
	v_mfma_f32_16x16x32_bf16 v[44:47], v[152:155], v[190:193], v[44:47]
	v_mfma_f32_16x16x32_bf16 v[36:39], v[174:177], v[190:193], v[36:39]
	v_mfma_f32_16x16x32_bf16 v[28:31], v[152:155], v[198:201], v[28:31]
	v_mfma_f32_16x16x32_bf16 v[20:23], v[174:177], v[198:201], v[20:23]
	v_mfma_f32_16x16x32_bf16 v[12:15], v[152:155], v[206:209], v[12:15]
	v_mfma_f32_16x16x32_bf16 v[4:7], v[174:177], v[206:209], v[4:7]
	v_mfma_f32_16x16x32_bf16 v[60:63], v[156:159], v[186:189], v[60:63]
	v_mfma_f32_16x16x32_bf16 v[52:55], v[178:181], v[186:189], v[52:55]
	v_mfma_f32_16x16x32_bf16 v[44:47], v[156:159], v[194:197], v[44:47]
	v_mfma_f32_16x16x32_bf16 v[36:39], v[178:181], v[194:197], v[36:39]
	v_mfma_f32_16x16x32_bf16 v[28:31], v[156:159], v[202:205], v[28:31]
	v_mfma_f32_16x16x32_bf16 v[20:23], v[178:181], v[202:205], v[20:23]
	v_mfma_f32_16x16x32_bf16 v[12:15], v[156:159], v[210:213], v[12:15]
	v_mfma_f32_16x16x32_bf16 v[4:7], v[178:181], v[210:213], v[4:7]
	s_barrier
	s_add_u32 s44, s44, 0x40080
	s_addc_u32 s45, s45, 0
	s_add_i32 s73, s74, s7
	v_lshl_add_u64 v[152:153], s[44:45], 0, v[132:133]
	s_mov_b32 m0, s73
	s_nop 0
	global_load_lds_dwordx4 v[152:153], off
	v_lshl_add_u64 v[152:153], s[44:45], 0, v[128:129]
	s_add_i32 m0, s73, 0x2000
	s_nop 0
	global_load_lds_dwordx4 v[152:153], off
	s_waitcnt vmcnt(6)
	s_barrier
	v_mfma_f32_16x16x32_bf16 v[56:59], v[226:229], v[182:185], v[56:59]
	v_mfma_f32_16x16x32_bf16 v[48:51], v[236:239], v[182:185], v[48:51]
	v_mfma_f32_16x16x32_bf16 v[40:43], v[226:229], v[190:193], v[40:43]
	v_mfma_f32_16x16x32_bf16 v[32:35], v[236:239], v[190:193], v[32:35]
	v_mfma_f32_16x16x32_bf16 v[24:27], v[226:229], v[198:201], v[24:27]
	v_mfma_f32_16x16x32_bf16 v[16:19], v[236:239], v[198:201], v[16:19]
	v_mfma_f32_16x16x32_bf16 v[8:11], v[226:229], v[206:209], v[8:11]
	v_mfma_f32_16x16x32_bf16 v[0:3], v[236:239], v[206:209], v[0:3]
	v_mfma_f32_16x16x32_bf16 v[56:59], v[232:235], v[186:189], v[56:59]
	v_mfma_f32_16x16x32_bf16 v[48:51], v[240:243], v[186:189], v[48:51]
	v_mfma_f32_16x16x32_bf16 v[40:43], v[232:235], v[194:197], v[40:43]
	v_mfma_f32_16x16x32_bf16 v[32:35], v[240:243], v[194:197], v[32:35]
	v_mfma_f32_16x16x32_bf16 v[24:27], v[232:235], v[202:205], v[24:27]
	v_mfma_f32_16x16x32_bf16 v[16:19], v[240:243], v[202:205], v[16:19]
	v_mfma_f32_16x16x32_bf16 v[8:11], v[232:235], v[210:213], v[8:11]
	v_mfma_f32_16x16x32_bf16 v[0:3], v[240:243], v[210:213], v[0:3]
	s_add_i32 s72, s72, 2
	s_add_u32 s42, s42, 0x100
	s_addc_u32 s43, s43, 0
	s_add_u32 s71, s71, 0x100
	s_addc_u32 s52, s52, 0
	s_cmp_gt_u32 s72, 13
	s_barrier
	s_cbranch_scc0 .LBB0_208
	s_cmp_lt_u32 s101, 0x100
	s_cbranch_scc0 .Lxa_0
	s_barrier

; #define PG8_STAGE(bufoff, gbase, voff) do { _Pragma("unroll") for (int _i = 0; _i < 2; ++_i) \
;     __builtin_amdgcn_global_load_lds((const unsigned*)((const char*)(gbase) + (voff)[_i]), (LAS unsigned*)(lds + (bufoff) + ldsw + _i * 8192), 16, 0, 0); } while (0)
; #define PG8_LDA(dst, b, h) do { _Pragma("unroll") for (int m = 0; m < 4; ++m) _Pragma("unroll") for (int k = 0; k < 2; ++k) dst[m][k] = *(const LAS bf16x8*)(lds + PG8_SA(b, h) + aoff + m * 2048 + k * 1024); } while (0)
; #define PG8_LDB(dst, b, h) do { _Pragma("unroll") for (int n = 0; n < 2; ++n) _Pragma("unroll") for (int k = 0; k < 2; ++k) dst[n][k] = *(const LAS bf16x8*)(lds + PG8_SB(b, h) + boff + n * 2048 + k * 1024); } while (0)
; #define PG8_MMA(ai, bj, At, Bt) do { __builtin_amdgcn_s_setprio(1); _Pragma("unroll") for (int m = 0; m < 4; ++m) _Pragma("unroll") for (int n = 0; n < 2; ++n) _Pragma("unroll") for (int k = 0; k < 2; ++k) \
;     acc[ai][bj][m][n] = __builtin_amdgcn_mfma_f32_16x16x32_bf16(Bt[n][k], At[m][k], acc[ai][bj][m][n], 0, 0, 0); __builtin_amdgcn_s_setprio(0); } while (0)
; #define PG8_WAIT_L(n) asm volatile("s_waitcnt lgkmcnt(" #n ")" ::: "memory")
; #define PG8_BAR __builtin_amdgcn_s_barrier()
; #define PG8_SCHED __builtin_amdgcn_sched_barrier(0)
; template <class Epi, class Sched>
; __device__ __forceinline__ void gemm_phase(LAS unsigned char* lds, const Gemm g, const Sched& S, const Epi& E) {
;     ...
;     for (int t = 0; t < nt; t += 2) {
;       const bool last = (t == nt - 2);
;       const char* a1 = cA + (size_t)(t + 1) * kstep;
;       const char* a2 = last ? nA : cA + (size_t)(t + 2) * kstep; const char* b2 = last ? nB : cB + (size_t)(t + 2) * kstep;
;       const char* a3 = a2 + kstep; const char* b3 = b2 + kstep;
;       if (last && has_next) S.a_ready(nxt);
;       PG8_LDB(B0, 0, 0); PG8_SCHED; PG8_LDA(At, 0, 0); PG8_STAGE(PG8_SA(1, 1), a1 + hstep, voffA);
;       PG8_WAIT_L(8); PG8_BAR; PG8_WAIT_L(0); PG8_MMA(0, 0, At, B0); PG8_BAR; PG8_SCHED;
;       PG8_LDB(B1, 0, 1); PG8_STAGE(PG8_SB(0, 0), b2, voffB);
;       PG8_BAR; PG8_WAIT_L(0); PG8_MMA(0, 1, At, B1); PG8_BAR;
;       PG8_LDA(At, 0, 1); PG8_STAGE(PG8_SA(0, 0), a2, voffA);
;       PG8_BAR; PG8_WAIT_L(0); PG8_MMA(1, 0, At, B0); PG8_BAR; PG8_SCHED;
.Lxs_e1:
.LBB0_281:
	s_add_u32 s42, s34, 0x100
	s_addc_u32 s43, s35, 0
	s_add_i32 s72, 0, 0x10000
	v_add_u32_e32 v140, s72, v202
	ds_read_b128 v[128:131], v140
	ds_read_b128 v[132:135], v140 offset:1024
	ds_read_b128 v[136:139], v140 offset:2048
	ds_read_b128 v[140:143], v140 offset:3072
	s_cmp_eq_u32 s52, 40
	s_cselect_b32 vcc_hi, s23, s43
	s_cselect_b32 vcc_lo, s22, s42
	s_cselect_b32 s45, s37, s49
	s_cselect_b32 s44, s36, s48
	v_lshl_add_u64 v[208:209], s[34:35], 0, v[182:183]
	s_add_i32 m0, s51, 0xc000
	ds_read_b128 v[144:147], v203
	ds_read_b128 v[148:151], v203 offset:1024
	ds_read_b128 v[152:155], v203 offset:2048
	ds_read_b128 v[186:189], v203 offset:3072
	ds_read_b128 v[190:193], v203 offset:4096
	ds_read_b128 v[194:197], v203 offset:5120
	ds_read_b128 v[198:201], v203 offset:6144
	ds_read_b128 v[204:207], v203 offset:7168
	global_load_lds_dwordx4 v[208:209], off
	v_lshl_add_u64 v[208:209], s[34:35], 0, v[184:185]
	s_add_i32 m0, s51, 0xe000
	s_nop 0
	global_load_lds_dwordx4 v[208:209], off
	s_waitcnt lgkmcnt(8)
	s_barrier
	s_waitcnt lgkmcnt(0)
	s_waitcnt lgkmcnt(0)
	v_mfma_f32_16x16x32_bf16 v[124:127], v[128:131], v[144:147], v[124:127]
	v_mfma_f32_16x16x32_bf16 v[120:123], v[136:139], v[144:147], v[120:123]
	v_mfma_f32_16x16x32_bf16 v[108:111], v[128:131], v[152:155], v[108:111]
	v_mfma_f32_16x16x32_bf16 v[104:107], v[136:139], v[152:155], v[104:107]
	v_mfma_f32_16x16x32_bf16 v[92:95], v[128:131], v[190:193], v[92:95]
	v_mfma_f32_16x16x32_bf16 v[88:91], v[136:139], v[190:193], v[88:91]
	v_mfma_f32_16x16x32_bf16 v[76:79], v[128:131], v[198:201], v[76:79]
	v_mfma_f32_16x16x32_bf16 v[72:75], v[136:139], v[198:201], v[72:75]
	v_mfma_f32_16x16x32_bf16 v[124:127], v[132:135], v[148:151], v[124:127]
	v_mfma_f32_16x16x32_bf16 v[120:123], v[140:143], v[148:151], v[120:123]
	v_mfma_f32_16x16x32_bf16 v[108:111], v[132:135], v[186:189], v[108:111]
	v_mfma_f32_16x16x32_bf16 v[104:107], v[140:143], v[186:189], v[104:107]
	v_mfma_f32_16x16x32_bf16 v[92:95], v[132:135], v[194:197], v[92:95]
	v_mfma_f32_16x16x32_bf16 v[88:91], v[140:143], v[194:197], v[88:91]
	v_mfma_f32_16x16x32_bf16 v[76:79], v[132:135], v[204:207], v[76:79]
	v_mfma_f32_16x16x32_bf16 v[72:75], v[140:143], v[204:207], v[72:75]
	s_barrier
	s_add_i32 s73, 0, 0x14000
	s_add_i32 s34, s72, s7
	v_add_u32_e32 v160, s73, v202
	v_lshl_add_u64 v[212:213], s[44:45], 0, v[174:175]
	s_mov_b32 m0, s34
	ds_read_b128 v[208:211], v160
	ds_read_b128 v[226:229], v160 offset:1024
	ds_read_b128 v[232:235], v160 offset:2048
	ds_read_b128 v[236:239], v160 offset:3072
	global_load_lds_dwordx4 v[212:213], off
	v_lshl_add_u64 v[222:223], s[44:45], 0, v[156:157]
	s_add_i32 m0, s34, 0x2000
	s_nop 0
	global_load_lds_dwordx4 v[222:223], off
	s_barrier
	s_waitcnt lgkmcnt(0)
	s_waitcnt lgkmcnt(0)
	v_mfma_f32_16x16x32_bf16 v[116:119], v[208:211], v[144:147], v[116:119]
	v_mfma_f32_16x16x32_bf16 v[112:115], v[232:235], v[144:147], v[112:115]
	v_mfma_f32_16x16x32_bf16 v[100:103], v[208:211], v[152:155], v[100:103]
	v_mfma_f32_16x16x32_bf16 v[96:99], v[232:235], v[152:155], v[96:99]
	v_mfma_f32_16x16x32_bf16 v[84:87], v[208:211], v[190:193], v[84:87]
	v_mfma_f32_16x16x32_bf16 v[80:83], v[232:235], v[190:193], v[80:83]
	v_mfma_f32_16x16x32_bf16 v[68:71], v[208:211], v[198:201], v[68:71]
	v_mfma_f32_16x16x32_bf16 v[64:67], v[232:235], v[198:201], v[64:67]
	v_mfma_f32_16x16x32_bf16 v[116:119], v[226:229], v[148:151], v[116:119]
	v_mfma_f32_16x16x32_bf16 v[112:115], v[236:239], v[148:151], v[112:115]
	v_mfma_f32_16x16x32_bf16 v[100:103], v[226:229], v[186:189], v[100:103]
	v_mfma_f32_16x16x32_bf16 v[96:99], v[236:239], v[186:189], v[96:99]
	v_mfma_f32_16x16x32_bf16 v[84:87], v[226:229], v[194:197], v[84:87]
	v_mfma_f32_16x16x32_bf16 v[80:83], v[236:239], v[194:197], v[80:83]
	v_mfma_f32_16x16x32_bf16 v[68:71], v[226:229], v[204:207], v[68:71]
	v_mfma_f32_16x16x32_bf16 v[64:67], v[236:239], v[204:207], v[64:67]
	s_mov_b32 m0, s51
	v_lshl_add_u64 v[240:241], vcc, 0, v[176:177]
	s_barrier
	ds_read_b128 v[144:147], v203 offset:16384
	ds_read_b128 v[148:151], v203 offset:17408
	ds_read_b128 v[152:155], v203 offset:18432
	ds_read_b128 v[186:189], v203 offset:19456
	ds_read_b128 v[190:193], v203 offset:20480
	ds_read_b128 v[194:197], v203 offset:21504
	ds_read_b128 v[198:201], v203 offset:22528
	ds_read_b128 v[204:207], v203 offset:23552
	global_load_lds_dwordx4 v[240:241], off
	v_lshl_add_u64 v[242:243], vcc, 0, v[158:159]
	s_mov_b32 m0, s62
	s_nop 0
	global_load_lds_dwordx4 v[242:243], off
	s_barrier
	s_waitcnt lgkmcnt(0)
	s_waitcnt lgkmcnt(0)
	v_mfma_f32_16x16x32_bf16 v[60:63], v[128:131], v[144:147], v[60:63]
	v_mfma_f32_16x16x32_bf16 v[56:59], v[136:139], v[144:147], v[56:59]
	v_mfma_f32_16x16x32_bf16 v[44:47], v[128:131], v[152:155], v[44:47]
	v_mfma_f32_16x16x32_bf16 v[40:43], v[136:139], v[152:155], v[40:43]
	v_mfma_f32_16x16x32_bf16 v[28:31], v[128:131], v[190:193], v[28:31]
	v_mfma_f32_16x16x32_bf16 v[24:27], v[136:139], v[190:193], v[24:27]
	v_mfma_f32_16x16x32_bf16 v[12:15], v[128:131], v[198:201], v[12:15]
	v_mfma_f32_16x16x32_bf16 v[8:11], v[136:139], v[198:201], v[8:11]
	v_mfma_f32_16x16x32_bf16 v[60:63], v[132:135], v[148:151], v[60:63]
	v_mfma_f32_16x16x32_bf16 v[56:59], v[140:143], v[148:151], v[56:59]
	v_mfma_f32_16x16x32_bf16 v[44:47], v[132:135], v[186:189], v[44:47]
	v_mfma_f32_16x16x32_bf16 v[40:43], v[140:143], v[186:189], v[40:43]
	v_mfma_f32_16x16x32_bf16 v[28:31], v[132:135], v[194:197], v[28:31]
	v_mfma_f32_16x16x32_bf16 v[24:27], v[140:143], v[194:197], v[24:27]
	v_mfma_f32_16x16x32_bf16 v[12:15], v[132:135], v[204:207], v[12:15]
	v_mfma_f32_16x16x32_bf16 v[8:11], v[140:143], v[204:207], v[8:11]
	s_barrier
; #define PG8_STAGE(bufoff, gbase, voff) do { _Pragma("unroll") for (int _i = 0; _i < 2; ++_i) \
;     __builtin_amdgcn_global_load_lds((const unsigned*)((const char*)(gbase) + (voff)[_i]), (LAS unsigned*)(lds + (bufoff) + ldsw + _i * 8192), 16, 0, 0); } while (0)
; #define PG8_LDA(dst, b, h) do { _Pragma("unroll") for (int m = 0; m < 4; ++m) _Pragma("unroll") for (int k = 0; k < 2; ++k) dst[m][k] = *(const LAS bf16x8*)(lds + PG8_SA(b, h) + aoff + m * 2048 + k * 1024); } while (0)
; #define PG8_LDB(dst, b, h) do { _Pragma("unroll") for (int n = 0; n < 2; ++n) _Pragma("unroll") for (int k = 0; k < 2; ++k) dst[n][k] = *(const LAS bf16x8*)(lds + PG8_SB(b, h) + boff + n * 2048 + k * 1024); } while (0)
; #define PG8_MMA(ai, bj, At, Bt) do { __builtin_amdgcn_s_setprio(1); _Pragma("unroll") for (int m = 0; m < 4; ++m) _Pragma("unroll") for (int n = 0; n < 2; ++n) _Pragma("unroll") for (int k = 0; k < 2; ++k) \
;     acc[ai][bj][m][n] = __builtin_amdgcn_mfma_f32_16x16x32_bf16(Bt[n][k], At[m][k], acc[ai][bj][m][n], 0, 0, 0); __builtin_amdgcn_s_setprio(0); } while (0)
; #define PG8_WAIT_V(n) asm volatile("s_waitcnt vmcnt(" #n ")" ::: "memory")
; #define PG8_WAIT_L(n) asm volatile("s_waitcnt lgkmcnt(" #n ")" ::: "memory")
; #define PG8_BAR __builtin_amdgcn_s_barrier()
; #define PG8_SCHED __builtin_amdgcn_sched_barrier(0)
; template <class Epi, class Sched>
; __device__ __forceinline__ void gemm_phase(LAS unsigned char* lds, const Gemm g, const Sched& S, const Epi& E) {
;     ...
;       PG8_STAGE(PG8_SB(0, 1), b2 + hstep, voffB);
;       PG8_WAIT_V(6); PG8_BAR; PG8_MMA(1, 1, At, B1); PG8_BAR;
;       PG8_LDB(B0, 1, 0); PG8_SCHED; PG8_LDA(At, 1, 0); PG8_STAGE(PG8_SA(0, 1), a2 + hstep, voffA);
;       PG8_WAIT_L(8); PG8_BAR; PG8_WAIT_L(0); PG8_MMA(0, 0, At, B0); PG8_BAR; PG8_SCHED;
;       PG8_LDB(B1, 1, 1); PG8_STAGE(PG8_SB(1, 0), b3, voffB);
	s_add_u32 s34, s44, 0xb0000
	s_addc_u32 s35, s45, 0
	s_add_i32 s72, s73, s7
	v_lshl_add_u64 v[128:129], s[34:35], 0, v[174:175]
	s_mov_b32 m0, s72
	s_nop 0
	global_load_lds_dwordx4 v[128:129], off
	v_lshl_add_u64 v[128:129], s[34:35], 0, v[156:157]
	s_add_i32 m0, s72, 0x2000
	s_nop 0
	global_load_lds_dwordx4 v[128:129], off
	s_waitcnt vmcnt(6)
	s_barrier
	v_mfma_f32_16x16x32_bf16 v[52:55], v[208:211], v[144:147], v[52:55]
	v_mfma_f32_16x16x32_bf16 v[48:51], v[232:235], v[144:147], v[48:51]
	v_mfma_f32_16x16x32_bf16 v[36:39], v[208:211], v[152:155], v[36:39]
	v_mfma_f32_16x16x32_bf16 v[32:35], v[232:235], v[152:155], v[32:35]
	v_mfma_f32_16x16x32_bf16 v[20:23], v[208:211], v[190:193], v[20:23]
	v_mfma_f32_16x16x32_bf16 v[16:19], v[232:235], v[190:193], v[16:19]
	v_mfma_f32_16x16x32_bf16 v[4:7], v[208:211], v[198:201], v[4:7]
	v_mfma_f32_16x16x32_bf16 v[0:3], v[232:235], v[198:201], v[0:3]
	v_mfma_f32_16x16x32_bf16 v[52:55], v[226:229], v[148:151], v[52:55]
	v_mfma_f32_16x16x32_bf16 v[48:51], v[236:239], v[148:151], v[48:51]
	v_mfma_f32_16x16x32_bf16 v[36:39], v[226:229], v[186:189], v[36:39]
	v_mfma_f32_16x16x32_bf16 v[32:35], v[236:239], v[186:189], v[32:35]
	v_mfma_f32_16x16x32_bf16 v[20:23], v[226:229], v[194:197], v[20:23]
	v_mfma_f32_16x16x32_bf16 v[16:19], v[236:239], v[194:197], v[16:19]
	v_mfma_f32_16x16x32_bf16 v[4:7], v[226:229], v[204:207], v[4:7]
	v_mfma_f32_16x16x32_bf16 v[0:3], v[236:239], v[204:207], v[0:3]
	s_add_i32 s72, 0, 0x18000
	v_add_u32_e32 v140, s72, v202
	s_barrier
	ds_read_b128 v[128:131], v140
	ds_read_b128 v[132:135], v140 offset:1024
	ds_read_b128 v[136:139], v140 offset:2048
	ds_read_b128 v[140:143], v140 offset:3072
	s_add_u32 s34, vcc_lo, 0xb0000
	s_addc_u32 s35, vcc_hi, 0
	s_mov_b32 m0, s63
	v_lshl_add_u64 v[208:209], s[34:35], 0, v[176:177]
	ds_read_b128 v[144:147], v203 offset:32768
	ds_read_b128 v[148:151], v203 offset:33792
	ds_read_b128 v[152:155], v203 offset:34816
	ds_read_b128 v[186:189], v203 offset:35840
	ds_read_b128 v[190:193], v203 offset:36864
	ds_read_b128 v[194:197], v203 offset:37888
	ds_read_b128 v[198:201], v203 offset:38912
	ds_read_b128 v[204:207], v203 offset:39936
	global_load_lds_dwordx4 v[208:209], off
	v_lshl_add_u64 v[208:209], s[34:35], 0, v[158:159]
	s_mov_b32 m0, s64
	s_nop 0
	global_load_lds_dwordx4 v[208:209], off
	s_waitcnt lgkmcnt(8)
	s_barrier
	s_waitcnt lgkmcnt(0)
	s_waitcnt lgkmcnt(0)
	v_mfma_f32_16x16x32_bf16 v[124:127], v[128:131], v[144:147], v[124:127]
	v_mfma_f32_16x16x32_bf16 v[120:123], v[136:139], v[144:147], v[120:123]
	v_mfma_f32_16x16x32_bf16 v[108:111], v[128:131], v[152:155], v[108:111]
	v_mfma_f32_16x16x32_bf16 v[104:107], v[136:139], v[152:155], v[104:107]
	v_mfma_f32_16x16x32_bf16 v[92:95], v[128:131], v[190:193], v[92:95]
	v_mfma_f32_16x16x32_bf16 v[88:91], v[136:139], v[190:193], v[88:91]
	v_mfma_f32_16x16x32_bf16 v[76:79], v[128:131], v[198:201], v[76:79]
	v_mfma_f32_16x16x32_bf16 v[72:75], v[136:139], v[198:201], v[72:75]
	v_mfma_f32_16x16x32_bf16 v[124:127], v[132:135], v[148:151], v[124:127]
	v_mfma_f32_16x16x32_bf16 v[120:123], v[140:143], v[148:151], v[120:123]
	v_mfma_f32_16x16x32_bf16 v[108:111], v[132:135], v[186:189], v[108:111]
	v_mfma_f32_16x16x32_bf16 v[104:107], v[140:143], v[186:189], v[104:107]
	v_mfma_f32_16x16x32_bf16 v[92:95], v[132:135], v[194:197], v[92:95]
	v_mfma_f32_16x16x32_bf16 v[88:91], v[140:143], v[194:197], v[88:91]
	v_mfma_f32_16x16x32_bf16 v[76:79], v[132:135], v[204:207], v[76:79]
	v_mfma_f32_16x16x32_bf16 v[72:75], v[140:143], v[204:207], v[72:75]
	s_barrier
	s_add_i32 s73, 0, 0x1c000
	s_add_i32 s34, s72, s7
	v_add_u32_e32 v160, s73, v202
	v_lshl_add_u64 v[212:213], v[212:213], 0, s[80:81]
	s_mov_b32 m0, s34
	ds_read_b128 v[208:211], v160
	ds_read_b128 v[226:229], v160 offset:1024
	ds_read_b128 v[232:235], v160 offset:2048
	ds_read_b128 v[236:239], v160 offset:3072
	global_load_lds_dwordx4 v[212:213], off
	v_lshl_add_u64 v[212:213], v[222:223], 0, s[80:81]
	s_add_i32 m0, s34, 0x2000
	s_nop 0
	global_load_lds_dwordx4 v[212:213], off
	s_barrier
; #define PG8_STAGE(bufoff, gbase, voff) do { _Pragma("unroll") for (int _i = 0; _i < 2; ++_i) \
;     __builtin_amdgcn_global_load_lds((const unsigned*)((const char*)(gbase) + (voff)[_i]), (LAS unsigned*)(lds + (bufoff) + ldsw + _i * 8192), 16, 0, 0); } while (0)
; #define PG8_LDA(dst, b, h) do { _Pragma("unroll") for (int m = 0; m < 4; ++m) _Pragma("unroll") for (int k = 0; k < 2; ++k) dst[m][k] = *(const LAS bf16x8*)(lds + PG8_SA(b, h) + aoff + m * 2048 + k * 1024); } while (0)
; #define PG8_MMA(ai, bj, At, Bt) do { __builtin_amdgcn_s_setprio(1); _Pragma("unroll") for (int m = 0; m < 4; ++m) _Pragma("unroll") for (int n = 0; n < 2; ++n) _Pragma("unroll") for (int k = 0; k < 2; ++k) \
;     acc[ai][bj][m][n] = __builtin_amdgcn_mfma_f32_16x16x32_bf16(Bt[n][k], At[m][k], acc[ai][bj][m][n], 0, 0, 0); __builtin_amdgcn_s_setprio(0); } while (0)
; #define PG8_WAIT_V(n) asm volatile("s_waitcnt vmcnt(" #n ")" ::: "memory")
; #define PG8_WAIT_L(n) asm volatile("s_waitcnt lgkmcnt(" #n ")" ::: "memory")
; #define PG8_BAR __builtin_amdgcn_s_barrier()
; #define PG8_SCHED __builtin_amdgcn_sched_barrier(0)
; template <class Epi, class Sched>
; __device__ __forceinline__ void gemm_phase(LAS unsigned char* lds, const Gemm g, const Sched& S, const Epi& E) {
;     ...
;       PG8_BAR; PG8_WAIT_L(0); PG8_MMA(0, 1, At, B1); PG8_BAR;
;       PG8_LDA(At, 1, 1); PG8_STAGE(PG8_SA(1, 0), a3, voffA);
;       PG8_BAR; PG8_WAIT_L(0); PG8_MMA(1, 0, At, B0); PG8_BAR; PG8_SCHED;
;       PG8_STAGE(PG8_SB(1, 1), b3 + hstep, voffB);
;       PG8_WAIT_V(6); PG8_BAR; PG8_MMA(1, 1, At, B1); PG8_BAR;
;     }
	s_waitcnt lgkmcnt(0)
	s_waitcnt lgkmcnt(0)
	v_mfma_f32_16x16x32_bf16 v[116:119], v[208:211], v[144:147], v[116:119]
	v_mfma_f32_16x16x32_bf16 v[112:115], v[232:235], v[144:147], v[112:115]
	v_mfma_f32_16x16x32_bf16 v[100:103], v[208:211], v[152:155], v[100:103]
	v_mfma_f32_16x16x32_bf16 v[96:99], v[232:235], v[152:155], v[96:99]
	v_mfma_f32_16x16x32_bf16 v[84:87], v[208:211], v[190:193], v[84:87]
	v_mfma_f32_16x16x32_bf16 v[80:83], v[232:235], v[190:193], v[80:83]
	v_mfma_f32_16x16x32_bf16 v[68:71], v[208:211], v[198:201], v[68:71]
	v_mfma_f32_16x16x32_bf16 v[64:67], v[232:235], v[198:201], v[64:67]
	v_mfma_f32_16x16x32_bf16 v[116:119], v[226:229], v[148:151], v[116:119]
	v_mfma_f32_16x16x32_bf16 v[112:115], v[236:239], v[148:151], v[112:115]
	v_mfma_f32_16x16x32_bf16 v[100:103], v[226:229], v[186:189], v[100:103]
	v_mfma_f32_16x16x32_bf16 v[96:99], v[236:239], v[186:189], v[96:99]
	v_mfma_f32_16x16x32_bf16 v[84:87], v[226:229], v[194:197], v[84:87]
	v_mfma_f32_16x16x32_bf16 v[80:83], v[236:239], v[194:197], v[80:83]
	v_mfma_f32_16x16x32_bf16 v[68:71], v[226:229], v[204:207], v[68:71]
	v_mfma_f32_16x16x32_bf16 v[64:67], v[236:239], v[204:207], v[64:67]
	s_mov_b32 m0, s65
	v_lshl_add_u64 v[212:213], v[240:241], 0, s[80:81]
	s_barrier
	ds_read_b128 v[144:147], v203 offset:49152
	ds_read_b128 v[148:151], v203 offset:50176
	ds_read_b128 v[152:155], v203 offset:51200
	ds_read_b128 v[186:189], v203 offset:52224
	ds_read_b128 v[190:193], v203 offset:53248
	ds_read_b128 v[194:197], v203 offset:54272
	ds_read_b128 v[198:201], v203 offset:55296
	ds_read_b128 v[204:207], v203 offset:56320
	global_load_lds_dwordx4 v[212:213], off
	v_lshl_add_u64 v[212:213], v[242:243], 0, s[80:81]
	s_mov_b32 m0, s70
	s_nop 0
	global_load_lds_dwordx4 v[212:213], off
	s_barrier
	s_waitcnt lgkmcnt(0)
	s_waitcnt lgkmcnt(0)
	v_mfma_f32_16x16x32_bf16 v[60:63], v[128:131], v[144:147], v[60:63]
	v_mfma_f32_16x16x32_bf16 v[56:59], v[136:139], v[144:147], v[56:59]
	v_mfma_f32_16x16x32_bf16 v[44:47], v[128:131], v[152:155], v[44:47]
	v_mfma_f32_16x16x32_bf16 v[40:43], v[136:139], v[152:155], v[40:43]
	v_mfma_f32_16x16x32_bf16 v[28:31], v[128:131], v[190:193], v[28:31]
	v_mfma_f32_16x16x32_bf16 v[24:27], v[136:139], v[190:193], v[24:27]
	v_mfma_f32_16x16x32_bf16 v[12:15], v[128:131], v[198:201], v[12:15]
	v_mfma_f32_16x16x32_bf16 v[8:11], v[136:139], v[198:201], v[8:11]
	v_mfma_f32_16x16x32_bf16 v[60:63], v[132:135], v[148:151], v[60:63]
	v_mfma_f32_16x16x32_bf16 v[56:59], v[140:143], v[148:151], v[56:59]
	v_mfma_f32_16x16x32_bf16 v[44:47], v[132:135], v[186:189], v[44:47]
	v_mfma_f32_16x16x32_bf16 v[40:43], v[140:143], v[186:189], v[40:43]
	v_mfma_f32_16x16x32_bf16 v[28:31], v[132:135], v[194:197], v[28:31]
	v_mfma_f32_16x16x32_bf16 v[24:27], v[140:143], v[194:197], v[24:27]
	v_mfma_f32_16x16x32_bf16 v[12:15], v[132:135], v[204:207], v[12:15]
	v_mfma_f32_16x16x32_bf16 v[8:11], v[140:143], v[204:207], v[8:11]
	s_barrier
	s_add_u32 s34, s44, 0xb0080
	s_addc_u32 s35, s45, 0
	s_add_i32 s44, s73, s7
	v_lshl_add_u64 v[128:129], s[34:35], 0, v[174:175]
	s_mov_b32 m0, s44
	s_nop 0
	global_load_lds_dwordx4 v[128:129], off
	v_lshl_add_u64 v[128:129], s[34:35], 0, v[156:157]
	s_add_i32 m0, s44, 0x2000
	s_nop 0
	global_load_lds_dwordx4 v[128:129], off
	s_waitcnt vmcnt(6)
	s_barrier
	v_mfma_f32_16x16x32_bf16 v[52:55], v[208:211], v[144:147], v[52:55]
	v_mfma_f32_16x16x32_bf16 v[48:51], v[232:235], v[144:147], v[48:51]
	v_mfma_f32_16x16x32_bf16 v[36:39], v[208:211], v[152:155], v[36:39]
	v_mfma_f32_16x16x32_bf16 v[32:35], v[232:235], v[152:155], v[32:35]
	v_mfma_f32_16x16x32_bf16 v[20:23], v[208:211], v[190:193], v[20:23]
	v_mfma_f32_16x16x32_bf16 v[16:19], v[232:235], v[190:193], v[16:19]
	v_mfma_f32_16x16x32_bf16 v[4:7], v[208:211], v[198:201], v[4:7]
	v_mfma_f32_16x16x32_bf16 v[0:3], v[232:235], v[198:201], v[0:3]
	v_mfma_f32_16x16x32_bf16 v[52:55], v[226:229], v[148:151], v[52:55]
	v_mfma_f32_16x16x32_bf16 v[48:51], v[236:239], v[148:151], v[48:51]
	v_mfma_f32_16x16x32_bf16 v[36:39], v[226:229], v[186:189], v[36:39]
	v_mfma_f32_16x16x32_bf16 v[32:35], v[236:239], v[186:189], v[32:35]
	v_mfma_f32_16x16x32_bf16 v[20:23], v[226:229], v[194:197], v[20:23]
	v_mfma_f32_16x16x32_bf16 v[16:19], v[236:239], v[194:197], v[16:19]
	v_mfma_f32_16x16x32_bf16 v[4:7], v[226:229], v[204:207], v[4:7]
	v_mfma_f32_16x16x32_bf16 v[0:3], v[236:239], v[204:207], v[0:3]
	s_add_i32 s52, s52, 2
	s_add_u32 s48, s48, 0x100
	s_addc_u32 s49, s49, 0
	s_cmp_gt_u32 s52, 41
	s_mov_b64 s[34:35], s[42:43]
	s_barrier
	s_cbranch_scc0 .LBB0_281
	s_cmp_lt_u32 s101, 0x100
	s_cbranch_scc0 .Lxa_1
	s_barrier

; #define PG8_STAGE(bufoff, gbase, voff) do { _Pragma("unroll") for (int _i = 0; _i < 2; ++_i) \
;     __builtin_amdgcn_global_load_lds((const unsigned*)((const char*)(gbase) + (voff)[_i]), (LAS unsigned*)(lds + (bufoff) + ldsw + _i * 8192), 16, 0, 0); } while (0)
; #define PG8_LDA(dst, b, h) do { _Pragma("unroll") for (int m = 0; m < 4; ++m) _Pragma("unroll") for (int k = 0; k < 2; ++k) dst[m][k] = *(const LAS bf16x8*)(lds + PG8_SA(b, h) + aoff + m * 2048 + k * 1024); } while (0)
; #define PG8_LDB(dst, b, h) do { _Pragma("unroll") for (int n = 0; n < 2; ++n) _Pragma("unroll") for (int k = 0; k < 2; ++k) dst[n][k] = *(const LAS bf16x8*)(lds + PG8_SB(b, h) + boff + n * 2048 + k * 1024); } while (0)
; #define PG8_MMA(ai, bj, At, Bt) do { __builtin_amdgcn_s_setprio(1); _Pragma("unroll") for (int m = 0; m < 4; ++m) _Pragma("unroll") for (int n = 0; n < 2; ++n) _Pragma("unroll") for (int k = 0; k < 2; ++k) \
;     acc[ai][bj][m][n] = __builtin_amdgcn_mfma_f32_16x16x32_bf16(Bt[n][k], At[m][k], acc[ai][bj][m][n], 0, 0, 0); __builtin_amdgcn_s_setprio(0); } while (0)
; #define PG8_WAIT_L(n) asm volatile("s_waitcnt lgkmcnt(" #n ")" ::: "memory")
; #define PG8_BAR __builtin_amdgcn_s_barrier()
; #define PG8_SCHED __builtin_amdgcn_sched_barrier(0)
; template <class Epi, class Sched>
; __device__ __forceinline__ void gemm_phase(LAS unsigned char* lds, const Gemm g, const Sched& S, const Epi& E) {
;     ...
;     for (int t = 0; t < nt; t += 2) {
;       const bool last = (t == nt - 2);
;       const char* a1 = cA + (size_t)(t + 1) * kstep;
;       const char* a2 = last ? nA : cA + (size_t)(t + 2) * kstep; const char* b2 = last ? nB : cB + (size_t)(t + 2) * kstep;
;       const char* a3 = a2 + kstep; const char* b3 = b2 + kstep;
;       if (last && has_next) S.a_ready(nxt);
;       PG8_LDB(B0, 0, 0); PG8_SCHED; PG8_LDA(At, 0, 0); PG8_STAGE(PG8_SA(1, 1), a1 + hstep, voffA);
;       PG8_WAIT_L(8); PG8_BAR; PG8_WAIT_L(0); PG8_MMA(0, 0, At, B0); PG8_BAR; PG8_SCHED;
;       PG8_LDB(B1, 0, 1); PG8_STAGE(PG8_SB(0, 0), b2, voffB);
;       PG8_BAR; PG8_WAIT_L(0); PG8_MMA(0, 1, At, B1); PG8_BAR;
;       PG8_LDA(At, 0, 1); PG8_STAGE(PG8_SA(0, 0), a2, voffA);
;       PG8_BAR; PG8_WAIT_L(0); PG8_MMA(1, 0, At, B0); PG8_BAR; PG8_SCHED;
.Lxs_e2:
.LBB0_367:
	s_add_u32 s44, s34, 0xfffc0080
	s_addc_u32 s45, s35, -1
	s_add_i32 s73, 0, 0x10000
	v_add_u32_e32 v140, s73, v183
	ds_read_b128 v[128:131], v140
	ds_read_b128 v[132:135], v140 offset:1024
	ds_read_b128 v[136:139], v140 offset:2048
	ds_read_b128 v[140:143], v140 offset:3072
	s_cmp_eq_u32 s72, 12
	s_cselect_b32 vcc_hi, s37, s45
	s_cselect_b32 vcc_lo, s70, s44
	s_cselect_b32 s45, s23, s52
	s_cselect_b32 s44, s71, s6
	v_lshl_add_u64 v[210:211], s[34:35], 0, v[154:155]
	s_add_i32 m0, s12, 0xc000
	ds_read_b128 v[174:177], v185
	ds_read_b128 v[178:181], v185 offset:1024
	ds_read_b128 v[186:189], v185 offset:2048
	ds_read_b128 v[190:193], v185 offset:3072
	ds_read_b128 v[194:197], v185 offset:4096
	ds_read_b128 v[198:201], v185 offset:5120
	ds_read_b128 v[202:205], v185 offset:6144
	ds_read_b128 v[206:209], v185 offset:7168
	global_load_lds_dwordx4 v[210:211], off
	v_lshl_add_u64 v[210:211], s[34:35], 0, v[156:157]
	s_add_i32 m0, s12, 0xe000
	s_nop 0
	global_load_lds_dwordx4 v[210:211], off
	s_waitcnt lgkmcnt(8)
	s_barrier
	s_waitcnt lgkmcnt(0)
	s_waitcnt lgkmcnt(0)
	v_mfma_f32_16x16x32_bf16 v[124:127], v[128:131], v[174:177], v[124:127]
	v_mfma_f32_16x16x32_bf16 v[120:123], v[136:139], v[174:177], v[120:123]
	v_mfma_f32_16x16x32_bf16 v[116:119], v[128:131], v[186:189], v[116:119]
	v_mfma_f32_16x16x32_bf16 v[108:111], v[136:139], v[186:189], v[108:111]
	v_mfma_f32_16x16x32_bf16 v[96:99], v[128:131], v[194:197], v[96:99]
	v_mfma_f32_16x16x32_bf16 v[88:91], v[136:139], v[194:197], v[88:91]
	v_mfma_f32_16x16x32_bf16 v[84:87], v[128:131], v[202:205], v[84:87]
	v_mfma_f32_16x16x32_bf16 v[76:79], v[136:139], v[202:205], v[76:79]
	v_mfma_f32_16x16x32_bf16 v[124:127], v[132:135], v[178:181], v[124:127]
	v_mfma_f32_16x16x32_bf16 v[120:123], v[140:143], v[178:181], v[120:123]
	v_mfma_f32_16x16x32_bf16 v[116:119], v[132:135], v[190:193], v[116:119]
	v_mfma_f32_16x16x32_bf16 v[108:111], v[140:143], v[190:193], v[108:111]
	v_mfma_f32_16x16x32_bf16 v[96:99], v[132:135], v[198:201], v[96:99]
	v_mfma_f32_16x16x32_bf16 v[88:91], v[140:143], v[198:201], v[88:91]
	v_mfma_f32_16x16x32_bf16 v[84:87], v[132:135], v[206:209], v[84:87]
	v_mfma_f32_16x16x32_bf16 v[76:79], v[140:143], v[206:209], v[76:79]
	s_barrier
	s_add_i32 s76, 0, 0x14000
	s_add_i32 s73, s73, s7
	v_add_u32_e32 v159, s76, v183
	v_lshl_add_u64 v[222:223], s[44:45], 0, v[148:149]
	s_mov_b32 m0, s73
	ds_read_b128 v[210:213], v159
	ds_read_b128 v[226:229], v159 offset:1024
	ds_read_b128 v[232:235], v159 offset:2048
	ds_read_b128 v[236:239], v159 offset:3072
	global_load_lds_dwordx4 v[222:223], off
	v_lshl_add_u64 v[240:241], s[44:45], 0, v[144:145]
	s_add_i32 m0, s73, 0x2000
	s_nop 0
	global_load_lds_dwordx4 v[240:241], off
	s_barrier
	s_waitcnt lgkmcnt(0)
	s_waitcnt lgkmcnt(0)
	v_mfma_f32_16x16x32_bf16 v[112:115], v[210:213], v[174:177], v[112:115]
	v_mfma_f32_16x16x32_bf16 v[104:107], v[232:235], v[174:177], v[104:107]
	v_mfma_f32_16x16x32_bf16 v[100:103], v[210:213], v[186:189], v[100:103]
	v_mfma_f32_16x16x32_bf16 v[92:95], v[232:235], v[186:189], v[92:95]
	v_mfma_f32_16x16x32_bf16 v[80:83], v[210:213], v[194:197], v[80:83]
	v_mfma_f32_16x16x32_bf16 v[72:75], v[232:235], v[194:197], v[72:75]
	v_mfma_f32_16x16x32_bf16 v[68:71], v[210:213], v[202:205], v[68:71]
	v_mfma_f32_16x16x32_bf16 v[64:67], v[232:235], v[202:205], v[64:67]
	v_mfma_f32_16x16x32_bf16 v[112:115], v[226:229], v[178:181], v[112:115]
	v_mfma_f32_16x16x32_bf16 v[104:107], v[236:239], v[178:181], v[104:107]
	v_mfma_f32_16x16x32_bf16 v[100:103], v[226:229], v[190:193], v[100:103]
	v_mfma_f32_16x16x32_bf16 v[92:95], v[236:239], v[190:193], v[92:95]
	v_mfma_f32_16x16x32_bf16 v[80:83], v[226:229], v[198:201], v[80:83]
	v_mfma_f32_16x16x32_bf16 v[72:75], v[236:239], v[198:201], v[72:75]
	v_mfma_f32_16x16x32_bf16 v[68:71], v[226:229], v[206:209], v[68:71]
	v_mfma_f32_16x16x32_bf16 v[64:67], v[236:239], v[206:209], v[64:67]
	s_mov_b32 m0, s12
	v_lshl_add_u64 v[242:243], vcc, 0, v[150:151]
	s_barrier
	ds_read_b128 v[174:177], v185 offset:16384
	ds_read_b128 v[178:181], v185 offset:17408
	ds_read_b128 v[186:189], v185 offset:18432
	ds_read_b128 v[190:193], v185 offset:19456
	ds_read_b128 v[194:197], v185 offset:20480
	ds_read_b128 v[198:201], v185 offset:21504
	ds_read_b128 v[202:205], v185 offset:22528
	ds_read_b128 v[206:209], v185 offset:23552
	global_load_lds_dwordx4 v[242:243], off
	v_lshl_add_u64 v[244:245], vcc, 0, v[146:147]
	s_mov_b32 m0, s13
	s_nop 0
	global_load_lds_dwordx4 v[244:245], off
	s_barrier
	s_waitcnt lgkmcnt(0)
	s_waitcnt lgkmcnt(0)
	v_mfma_f32_16x16x32_bf16 v[60:63], v[128:131], v[174:177], v[60:63]
	v_mfma_f32_16x16x32_bf16 v[56:59], v[136:139], v[174:177], v[56:59]
	v_mfma_f32_16x16x32_bf16 v[52:55], v[128:131], v[186:189], v[52:55]
	v_mfma_f32_16x16x32_bf16 v[44:47], v[136:139], v[186:189], v[44:47]
	v_mfma_f32_16x16x32_bf16 v[32:35], v[128:131], v[194:197], v[32:35]
	v_mfma_f32_16x16x32_bf16 v[24:27], v[136:139], v[194:197], v[24:27]
	v_mfma_f32_16x16x32_bf16 v[20:23], v[128:131], v[202:205], v[20:23]
	v_mfma_f32_16x16x32_bf16 v[12:15], v[136:139], v[202:205], v[12:15]
	v_mfma_f32_16x16x32_bf16 v[60:63], v[132:135], v[178:181], v[60:63]
	v_mfma_f32_16x16x32_bf16 v[56:59], v[140:143], v[178:181], v[56:59]
	v_mfma_f32_16x16x32_bf16 v[52:55], v[132:135], v[190:193], v[52:55]
	v_mfma_f32_16x16x32_bf16 v[44:47], v[140:143], v[190:193], v[44:47]
	v_mfma_f32_16x16x32_bf16 v[32:35], v[132:135], v[198:201], v[32:35]
	v_mfma_f32_16x16x32_bf16 v[24:27], v[140:143], v[198:201], v[24:27]
	v_mfma_f32_16x16x32_bf16 v[20:23], v[132:135], v[206:209], v[20:23]
	v_mfma_f32_16x16x32_bf16 v[12:15], v[140:143], v[206:209], v[12:15]
	s_barrier
; #define PG8_STAGE(bufoff, gbase, voff) do { _Pragma("unroll") for (int _i = 0; _i < 2; ++_i) \
;     __builtin_amdgcn_global_load_lds((const unsigned*)((const char*)(gbase) + (voff)[_i]), (LAS unsigned*)(lds + (bufoff) + ldsw + _i * 8192), 16, 0, 0); } while (0)
; #define PG8_LDA(dst, b, h) do { _Pragma("unroll") for (int m = 0; m < 4; ++m) _Pragma("unroll") for (int k = 0; k < 2; ++k) dst[m][k] = *(const LAS bf16x8*)(lds + PG8_SA(b, h) + aoff + m * 2048 + k * 1024); } while (0)
; #define PG8_LDB(dst, b, h) do { _Pragma("unroll") for (int n = 0; n < 2; ++n) _Pragma("unroll") for (int k = 0; k < 2; ++k) dst[n][k] = *(const LAS bf16x8*)(lds + PG8_SB(b, h) + boff + n * 2048 + k * 1024); } while (0)
; #define PG8_MMA(ai, bj, At, Bt) do { __builtin_amdgcn_s_setprio(1); _Pragma("unroll") for (int m = 0; m < 4; ++m) _Pragma("unroll") for (int n = 0; n < 2; ++n) _Pragma("unroll") for (int k = 0; k < 2; ++k) \
;     acc[ai][bj][m][n] = __builtin_amdgcn_mfma_f32_16x16x32_bf16(Bt[n][k], At[m][k], acc[ai][bj][m][n], 0, 0, 0); __builtin_amdgcn_s_setprio(0); } while (0)
; #define PG8_WAIT_V(n) asm volatile("s_waitcnt vmcnt(" #n ")" ::: "memory")
; #define PG8_WAIT_L(n) asm volatile("s_waitcnt lgkmcnt(" #n ")" ::: "memory")
; #define PG8_BAR __builtin_amdgcn_s_barrier()
; #define PG8_SCHED __builtin_amdgcn_sched_barrier(0)
; template <class Epi, class Sched>
; __device__ __forceinline__ void gemm_phase(LAS unsigned char* lds, const Gemm g, const Sched& S, const Epi& E) {
;     ...
;       PG8_STAGE(PG8_SB(0, 1), b2 + hstep, voffB);
;       PG8_WAIT_V(6); PG8_BAR; PG8_MMA(1, 1, At, B1); PG8_BAR;
;       PG8_LDB(B0, 1, 0); PG8_SCHED; PG8_LDA(At, 1, 0); PG8_STAGE(PG8_SA(0, 1), a2 + hstep, voffA);
;       PG8_WAIT_L(8); PG8_BAR; PG8_WAIT_L(0); PG8_MMA(0, 0, At, B0); PG8_BAR; PG8_SCHED;
;       PG8_LDB(B1, 1, 1); PG8_STAGE(PG8_SB(1, 0), b3, voffB);
	s_add_u32 s74, s44, 0x40000
	s_addc_u32 s75, s45, 0
	s_add_i32 s73, s76, s7
	v_lshl_add_u64 v[128:129], s[74:75], 0, v[148:149]
	s_mov_b32 m0, s73
	s_nop 0
	global_load_lds_dwordx4 v[128:129], off
	v_lshl_add_u64 v[128:129], s[74:75], 0, v[144:145]
	s_add_i32 m0, s73, 0x2000
	s_nop 0
	global_load_lds_dwordx4 v[128:129], off
	s_waitcnt vmcnt(6)
	s_barrier
	v_mfma_f32_16x16x32_bf16 v[48:51], v[210:213], v[174:177], v[48:51]
	v_mfma_f32_16x16x32_bf16 v[40:43], v[232:235], v[174:177], v[40:43]
	v_mfma_f32_16x16x32_bf16 v[36:39], v[210:213], v[186:189], v[36:39]
	v_mfma_f32_16x16x32_bf16 v[28:31], v[232:235], v[186:189], v[28:31]
	v_mfma_f32_16x16x32_bf16 v[16:19], v[210:213], v[194:197], v[16:19]
	v_mfma_f32_16x16x32_bf16 v[8:11], v[232:235], v[194:197], v[8:11]
	v_mfma_f32_16x16x32_bf16 v[4:7], v[210:213], v[202:205], v[4:7]
	v_mfma_f32_16x16x32_bf16 v[0:3], v[232:235], v[202:205], v[0:3]
	v_mfma_f32_16x16x32_bf16 v[48:51], v[226:229], v[178:181], v[48:51]
	v_mfma_f32_16x16x32_bf16 v[40:43], v[236:239], v[178:181], v[40:43]
	v_mfma_f32_16x16x32_bf16 v[36:39], v[226:229], v[190:193], v[36:39]
	v_mfma_f32_16x16x32_bf16 v[28:31], v[236:239], v[190:193], v[28:31]
	v_mfma_f32_16x16x32_bf16 v[16:19], v[226:229], v[198:201], v[16:19]
	v_mfma_f32_16x16x32_bf16 v[8:11], v[236:239], v[198:201], v[8:11]
	v_mfma_f32_16x16x32_bf16 v[4:7], v[226:229], v[206:209], v[4:7]
	v_mfma_f32_16x16x32_bf16 v[0:3], v[236:239], v[206:209], v[0:3]
	s_add_i32 s73, 0, 0x18000
	v_add_u32_e32 v140, s73, v183
	s_barrier
	ds_read_b128 v[128:131], v140
	ds_read_b128 v[132:135], v140 offset:1024
	ds_read_b128 v[136:139], v140 offset:2048
	ds_read_b128 v[140:143], v140 offset:3072
	s_add_u32 s74, vcc_lo, 0x40000
	s_addc_u32 s75, vcc_hi, 0
	s_mov_b32 m0, s20
	v_lshl_add_u64 v[210:211], s[74:75], 0, v[150:151]
	ds_read_b128 v[174:177], v185 offset:32768
	ds_read_b128 v[178:181], v185 offset:33792
	ds_read_b128 v[186:189], v185 offset:34816
	ds_read_b128 v[190:193], v185 offset:35840
	ds_read_b128 v[194:197], v185 offset:36864
	ds_read_b128 v[198:201], v185 offset:37888
	ds_read_b128 v[202:205], v185 offset:38912
	ds_read_b128 v[206:209], v185 offset:39936
	global_load_lds_dwordx4 v[210:211], off
	v_lshl_add_u64 v[210:211], s[74:75], 0, v[146:147]
	s_mov_b32 m0, s48
	s_nop 0
	global_load_lds_dwordx4 v[210:211], off
	s_waitcnt lgkmcnt(8)
	s_barrier
	s_waitcnt lgkmcnt(0)
	s_waitcnt lgkmcnt(0)
	v_mfma_f32_16x16x32_bf16 v[124:127], v[128:131], v[174:177], v[124:127]
	v_mfma_f32_16x16x32_bf16 v[120:123], v[136:139], v[174:177], v[120:123]
	v_mfma_f32_16x16x32_bf16 v[116:119], v[128:131], v[186:189], v[116:119]
	v_mfma_f32_16x16x32_bf16 v[108:111], v[136:139], v[186:189], v[108:111]
	v_mfma_f32_16x16x32_bf16 v[96:99], v[128:131], v[194:197], v[96:99]
	v_mfma_f32_16x16x32_bf16 v[88:91], v[136:139], v[194:197], v[88:91]
	v_mfma_f32_16x16x32_bf16 v[84:87], v[128:131], v[202:205], v[84:87]
	v_mfma_f32_16x16x32_bf16 v[76:79], v[136:139], v[202:205], v[76:79]
	v_mfma_f32_16x16x32_bf16 v[124:127], v[132:135], v[178:181], v[124:127]
	v_mfma_f32_16x16x32_bf16 v[120:123], v[140:143], v[178:181], v[120:123]
	v_mfma_f32_16x16x32_bf16 v[116:119], v[132:135], v[190:193], v[116:119]
	v_mfma_f32_16x16x32_bf16 v[108:111], v[140:143], v[190:193], v[108:111]
	v_mfma_f32_16x16x32_bf16 v[96:99], v[132:135], v[198:201], v[96:99]
	v_mfma_f32_16x16x32_bf16 v[88:91], v[140:143], v[198:201], v[88:91]
	v_mfma_f32_16x16x32_bf16 v[84:87], v[132:135], v[206:209], v[84:87]
	v_mfma_f32_16x16x32_bf16 v[76:79], v[140:143], v[206:209], v[76:79]
	s_barrier
	s_add_i32 s74, 0, 0x1c000
	s_add_i32 s73, s73, s7
	v_add_u32_e32 v159, s74, v183
	v_lshl_add_u64 v[222:223], v[222:223], 0, s[80:81]
	s_mov_b32 m0, s73
	ds_read_b128 v[210:213], v159
	ds_read_b128 v[226:229], v159 offset:1024
	ds_read_b128 v[232:235], v159 offset:2048
	ds_read_b128 v[236:239], v159 offset:3072
	global_load_lds_dwordx4 v[222:223], off
	v_lshl_add_u64 v[222:223], v[240:241], 0, s[80:81]
	s_add_i32 m0, s73, 0x2000
	s_nop 0
	global_load_lds_dwordx4 v[222:223], off
	s_barrier
; #define PG8_STAGE(bufoff, gbase, voff) do { _Pragma("unroll") for (int _i = 0; _i < 2; ++_i) \
;     __builtin_amdgcn_global_load_lds((const unsigned*)((const char*)(gbase) + (voff)[_i]), (LAS unsigned*)(lds + (bufoff) + ldsw + _i * 8192), 16, 0, 0); } while (0)
; #define PG8_LDA(dst, b, h) do { _Pragma("unroll") for (int m = 0; m < 4; ++m) _Pragma("unroll") for (int k = 0; k < 2; ++k) dst[m][k] = *(const LAS bf16x8*)(lds + PG8_SA(b, h) + aoff + m * 2048 + k * 1024); } while (0)
; #define PG8_MMA(ai, bj, At, Bt) do { __builtin_amdgcn_s_setprio(1); _Pragma("unroll") for (int m = 0; m < 4; ++m) _Pragma("unroll") for (int n = 0; n < 2; ++n) _Pragma("unroll") for (int k = 0; k < 2; ++k) \
;     acc[ai][bj][m][n] = __builtin_amdgcn_mfma_f32_16x16x32_bf16(Bt[n][k], At[m][k], acc[ai][bj][m][n], 0, 0, 0); __builtin_amdgcn_s_setprio(0); } while (0)
; #define PG8_WAIT_V(n) asm volatile("s_waitcnt vmcnt(" #n ")" ::: "memory")
; #define PG8_WAIT_L(n) asm volatile("s_waitcnt lgkmcnt(" #n ")" ::: "memory")
; #define PG8_BAR __builtin_amdgcn_s_barrier()
; #define PG8_SCHED __builtin_amdgcn_sched_barrier(0)
; template <class Epi, class Sched>
; __device__ __forceinline__ void gemm_phase(LAS unsigned char* lds, const Gemm g, const Sched& S, const Epi& E) {
;     ...
;       PG8_BAR; PG8_WAIT_L(0); PG8_MMA(0, 1, At, B1); PG8_BAR;
;       PG8_LDA(At, 1, 1); PG8_STAGE(PG8_SA(1, 0), a3, voffA);
;       PG8_BAR; PG8_WAIT_L(0); PG8_MMA(1, 0, At, B0); PG8_BAR; PG8_SCHED;
;       PG8_STAGE(PG8_SB(1, 1), b3 + hstep, voffB);
;       PG8_WAIT_V(6); PG8_BAR; PG8_MMA(1, 1, At, B1); PG8_BAR;
;     }
	s_waitcnt lgkmcnt(0)
	s_waitcnt lgkmcnt(0)
	v_mfma_f32_16x16x32_bf16 v[112:115], v[210:213], v[174:177], v[112:115]
	v_mfma_f32_16x16x32_bf16 v[104:107], v[232:235], v[174:177], v[104:107]
	v_mfma_f32_16x16x32_bf16 v[100:103], v[210:213], v[186:189], v[100:103]
	v_mfma_f32_16x16x32_bf16 v[92:95], v[232:235], v[186:189], v[92:95]
	v_mfma_f32_16x16x32_bf16 v[80:83], v[210:213], v[194:197], v[80:83]
	v_mfma_f32_16x16x32_bf16 v[72:75], v[232:235], v[194:197], v[72:75]
	v_mfma_f32_16x16x32_bf16 v[68:71], v[210:213], v[202:205], v[68:71]
	v_mfma_f32_16x16x32_bf16 v[64:67], v[232:235], v[202:205], v[64:67]
	v_mfma_f32_16x16x32_bf16 v[112:115], v[226:229], v[178:181], v[112:115]
	v_mfma_f32_16x16x32_bf16 v[104:107], v[236:239], v[178:181], v[104:107]
	v_mfma_f32_16x16x32_bf16 v[100:103], v[226:229], v[190:193], v[100:103]
	v_mfma_f32_16x16x32_bf16 v[92:95], v[236:239], v[190:193], v[92:95]
	v_mfma_f32_16x16x32_bf16 v[80:83], v[226:229], v[198:201], v[80:83]
	v_mfma_f32_16x16x32_bf16 v[72:75], v[236:239], v[198:201], v[72:75]
	v_mfma_f32_16x16x32_bf16 v[68:71], v[226:229], v[206:209], v[68:71]
	v_mfma_f32_16x16x32_bf16 v[64:67], v[236:239], v[206:209], v[64:67]
	s_mov_b32 m0, s49
	v_lshl_add_u64 v[222:223], v[242:243], 0, s[80:81]
	s_barrier
	ds_read_b128 v[174:177], v185 offset:49152
	ds_read_b128 v[178:181], v185 offset:50176
	ds_read_b128 v[186:189], v185 offset:51200
	ds_read_b128 v[190:193], v185 offset:52224
	ds_read_b128 v[194:197], v185 offset:53248
	ds_read_b128 v[198:201], v185 offset:54272
	ds_read_b128 v[202:205], v185 offset:55296
	ds_read_b128 v[206:209], v185 offset:56320
	global_load_lds_dwordx4 v[222:223], off
	v_lshl_add_u64 v[222:223], v[244:245], 0, s[80:81]
	s_mov_b32 m0, s51
	s_nop 0
	global_load_lds_dwordx4 v[222:223], off
	s_barrier
	s_waitcnt lgkmcnt(0)
	s_waitcnt lgkmcnt(0)
	v_mfma_f32_16x16x32_bf16 v[60:63], v[128:131], v[174:177], v[60:63]
	v_mfma_f32_16x16x32_bf16 v[56:59], v[136:139], v[174:177], v[56:59]
	v_mfma_f32_16x16x32_bf16 v[52:55], v[128:131], v[186:189], v[52:55]
	v_mfma_f32_16x16x32_bf16 v[44:47], v[136:139], v[186:189], v[44:47]
	v_mfma_f32_16x16x32_bf16 v[32:35], v[128:131], v[194:197], v[32:35]
	v_mfma_f32_16x16x32_bf16 v[24:27], v[136:139], v[194:197], v[24:27]
	v_mfma_f32_16x16x32_bf16 v[20:23], v[128:131], v[202:205], v[20:23]
	v_mfma_f32_16x16x32_bf16 v[12:15], v[136:139], v[202:205], v[12:15]
	v_mfma_f32_16x16x32_bf16 v[60:63], v[132:135], v[178:181], v[60:63]
	v_mfma_f32_16x16x32_bf16 v[56:59], v[140:143], v[178:181], v[56:59]
	v_mfma_f32_16x16x32_bf16 v[52:55], v[132:135], v[190:193], v[52:55]
	v_mfma_f32_16x16x32_bf16 v[44:47], v[140:143], v[190:193], v[44:47]
	v_mfma_f32_16x16x32_bf16 v[32:35], v[132:135], v[198:201], v[32:35]
	v_mfma_f32_16x16x32_bf16 v[24:27], v[140:143], v[198:201], v[24:27]
	v_mfma_f32_16x16x32_bf16 v[20:23], v[132:135], v[206:209], v[20:23]
	v_mfma_f32_16x16x32_bf16 v[12:15], v[140:143], v[206:209], v[12:15]
	s_barrier
	s_add_u32 s44, s44, 0x40080
	s_addc_u32 s45, s45, 0
	s_add_i32 s73, s74, s7
	v_lshl_add_u64 v[128:129], s[44:45], 0, v[148:149]
	s_mov_b32 m0, s73
	s_nop 0
	global_load_lds_dwordx4 v[128:129], off
	v_lshl_add_u64 v[128:129], s[44:45], 0, v[144:145]
	s_add_i32 m0, s73, 0x2000
	s_nop 0
	global_load_lds_dwordx4 v[128:129], off
	s_waitcnt vmcnt(6)
	s_barrier
	v_mfma_f32_16x16x32_bf16 v[48:51], v[210:213], v[174:177], v[48:51]
	v_mfma_f32_16x16x32_bf16 v[40:43], v[232:235], v[174:177], v[40:43]
	v_mfma_f32_16x16x32_bf16 v[36:39], v[210:213], v[186:189], v[36:39]
	v_mfma_f32_16x16x32_bf16 v[28:31], v[232:235], v[186:189], v[28:31]
	v_mfma_f32_16x16x32_bf16 v[16:19], v[210:213], v[194:197], v[16:19]
	v_mfma_f32_16x16x32_bf16 v[8:11], v[232:235], v[194:197], v[8:11]
	v_mfma_f32_16x16x32_bf16 v[4:7], v[210:213], v[202:205], v[4:7]
	v_mfma_f32_16x16x32_bf16 v[0:3], v[232:235], v[202:205], v[0:3]
	v_mfma_f32_16x16x32_bf16 v[48:51], v[226:229], v[178:181], v[48:51]
	v_mfma_f32_16x16x32_bf16 v[40:43], v[236:239], v[178:181], v[40:43]
	v_mfma_f32_16x16x32_bf16 v[36:39], v[226:229], v[190:193], v[36:39]
	v_mfma_f32_16x16x32_bf16 v[28:31], v[236:239], v[190:193], v[28:31]
	v_mfma_f32_16x16x32_bf16 v[16:19], v[226:229], v[198:201], v[16:19]
	v_mfma_f32_16x16x32_bf16 v[8:11], v[236:239], v[198:201], v[8:11]
	v_mfma_f32_16x16x32_bf16 v[4:7], v[226:229], v[206:209], v[4:7]
	v_mfma_f32_16x16x32_bf16 v[0:3], v[236:239], v[206:209], v[0:3]
	s_add_i32 s72, s72, 2
	s_add_u32 s34, s34, 0x100
	s_addc_u32 s35, s35, 0
	s_add_u32 s6, s6, 0x100
	s_addc_u32 s52, s52, 0
	s_cmp_gt_u32 s72, 13
	s_barrier
	s_cbranch_scc0 .LBB0_367
	s_cmp_lt_u32 s101, 0x100
	s_cbranch_scc0 .Lxa_2
	s_barrier

; #define PG8_STAGE(bufoff, gbase, voff) do { _Pragma("unroll") for (int _i = 0; _i < 2; ++_i) \
;     __builtin_amdgcn_global_load_lds((const unsigned*)((const char*)(gbase) + (voff)[_i]), (LAS unsigned*)(lds + (bufoff) + ldsw + _i * 8192), 16, 0, 0); } while (0)
; #define PG8_LDA(dst, b, h) do { _Pragma("unroll") for (int m = 0; m < 4; ++m) _Pragma("unroll") for (int k = 0; k < 2; ++k) dst[m][k] = *(const LAS bf16x8*)(lds + PG8_SA(b, h) + aoff + m * 2048 + k * 1024); } while (0)
; #define PG8_LDB(dst, b, h) do { _Pragma("unroll") for (int n = 0; n < 2; ++n) _Pragma("unroll") for (int k = 0; k < 2; ++k) dst[n][k] = *(const LAS bf16x8*)(lds + PG8_SB(b, h) + boff + n * 2048 + k * 1024); } while (0)
; #define PG8_MMA(ai, bj, At, Bt) do { __builtin_amdgcn_s_setprio(1); _Pragma("unroll") for (int m = 0; m < 4; ++m) _Pragma("unroll") for (int n = 0; n < 2; ++n) _Pragma("unroll") for (int k = 0; k < 2; ++k) \
;     acc[ai][bj][m][n] = __builtin_amdgcn_mfma_f32_16x16x32_bf16(Bt[n][k], At[m][k], acc[ai][bj][m][n], 0, 0, 0); __builtin_amdgcn_s_setprio(0); } while (0)
; #define PG8_WAIT_L(n) asm volatile("s_waitcnt lgkmcnt(" #n ")" ::: "memory")
; #define PG8_BAR __builtin_amdgcn_s_barrier()
; #define PG8_SCHED __builtin_amdgcn_sched_barrier(0)
; template <class Epi, class Sched>
; __device__ __forceinline__ void gemm_phase(LAS unsigned char* lds, const Gemm g, const Sched& S, const Epi& E) {
;     ...
;     for (int t = 0; t < nt; t += 2) {
;       const bool last = (t == nt - 2);
;       const char* a1 = cA + (size_t)(t + 1) * kstep;
;       const char* a2 = last ? nA : cA + (size_t)(t + 2) * kstep; const char* b2 = last ? nB : cB + (size_t)(t + 2) * kstep;
;       const char* a3 = a2 + kstep; const char* b3 = b2 + kstep;
;       if (last && has_next) S.a_ready(nxt);
;       PG8_LDB(B0, 0, 0); PG8_SCHED; PG8_LDA(At, 0, 0); PG8_STAGE(PG8_SA(1, 1), a1 + hstep, voffA);
;       PG8_WAIT_L(8); PG8_BAR; PG8_WAIT_L(0); PG8_MMA(0, 0, At, B0); PG8_BAR; PG8_SCHED;
;       PG8_LDB(B1, 0, 1); PG8_STAGE(PG8_SB(0, 0), b2, voffB);
;       PG8_BAR; PG8_WAIT_L(0); PG8_MMA(0, 1, At, B1); PG8_BAR;
;       PG8_LDA(At, 0, 1); PG8_STAGE(PG8_SA(0, 0), a2, voffA);
;       PG8_BAR; PG8_WAIT_L(0); PG8_MMA(1, 0, At, B0); PG8_BAR; PG8_SCHED;
.Lxs_e3:
.LBB0_707:
	s_add_u32 s48, s34, 0xfffc0080
	s_addc_u32 s49, s35, -1
	s_add_i32 s73, 0, 0x10000
	v_add_u32_e32 v140, s73, v201
	ds_read_b128 v[120:123], v140
	ds_read_b128 v[124:127], v140 offset:1024
	ds_read_b128 v[136:139], v140 offset:2048
	ds_read_b128 v[140:143], v140 offset:3072
	s_cmp_eq_u32 s72, 12
	s_cselect_b32 s49, s20, s49
	s_cselect_b32 s48, s45, s48
	s_cselect_b32 vcc_hi, s43, s52
	s_cselect_b32 vcc_lo, s68, s69
	v_lshl_add_u64 v[198:199], s[34:35], 0, v[182:183]
	s_add_i32 m0, s65, 0xc000
	ds_read_b128 v[144:147], v203
	ds_read_b128 v[148:151], v203 offset:1024
	ds_read_b128 v[152:155], v203 offset:2048
	ds_read_b128 v[186:189], v203 offset:3072
	ds_read_b128 v[190:193], v203 offset:4096
	ds_read_b128 v[194:197], v203 offset:5120
	ds_read_b128 v[204:207], v203 offset:6144
	ds_read_b128 v[208:211], v203 offset:7168
	global_load_lds_dwordx4 v[198:199], off
	v_lshl_add_u64 v[198:199], s[34:35], 0, v[184:185]
	s_add_i32 m0, s65, 0xe000
	s_nop 0
	global_load_lds_dwordx4 v[198:199], off
	s_waitcnt lgkmcnt(8)
	s_barrier
	s_waitcnt lgkmcnt(0)
	s_waitcnt lgkmcnt(0)
	v_mfma_f32_16x16x32_bf16 v[132:135], v[120:123], v[144:147], v[132:135]
	v_mfma_f32_16x16x32_bf16 v[128:131], v[136:139], v[144:147], v[128:131]
	v_mfma_f32_16x16x32_bf16 v[108:111], v[120:123], v[152:155], v[108:111]
	v_mfma_f32_16x16x32_bf16 v[104:107], v[136:139], v[152:155], v[104:107]
	v_mfma_f32_16x16x32_bf16 v[92:95], v[120:123], v[190:193], v[92:95]
	v_mfma_f32_16x16x32_bf16 v[88:91], v[136:139], v[190:193], v[88:91]
	v_mfma_f32_16x16x32_bf16 v[76:79], v[120:123], v[204:207], v[76:79]
	v_mfma_f32_16x16x32_bf16 v[72:75], v[136:139], v[204:207], v[72:75]
	v_mfma_f32_16x16x32_bf16 v[132:135], v[124:127], v[148:151], v[132:135]
	v_mfma_f32_16x16x32_bf16 v[128:131], v[140:143], v[148:151], v[128:131]
	v_mfma_f32_16x16x32_bf16 v[108:111], v[124:127], v[186:189], v[108:111]
	v_mfma_f32_16x16x32_bf16 v[104:107], v[140:143], v[186:189], v[104:107]
	v_mfma_f32_16x16x32_bf16 v[92:95], v[124:127], v[194:197], v[92:95]
	v_mfma_f32_16x16x32_bf16 v[88:91], v[140:143], v[194:197], v[88:91]
	v_mfma_f32_16x16x32_bf16 v[76:79], v[124:127], v[208:211], v[76:79]
	v_mfma_f32_16x16x32_bf16 v[72:75], v[140:143], v[208:211], v[72:75]
	s_barrier
	s_add_i32 s76, 0, 0x14000
	s_add_i32 s73, s73, s64
	v_add_u32_e32 v160, s76, v201
	v_lshl_add_u64 v[198:199], vcc, 0, v[174:175]
	s_mov_b32 m0, s73
	ds_read_b128 v[226:229], v160
	ds_read_b128 v[232:235], v160 offset:1024
	ds_read_b128 v[236:239], v160 offset:2048
	ds_read_b128 v[240:243], v160 offset:3072
	global_load_lds_dwordx4 v[198:199], off
	v_lshl_add_u64 v[212:213], vcc, 0, v[156:157]
	s_add_i32 m0, s73, 0x2000
	s_nop 0
	global_load_lds_dwordx4 v[212:213], off
	s_barrier
	s_waitcnt lgkmcnt(0)
	s_waitcnt lgkmcnt(0)
	v_mfma_f32_16x16x32_bf16 v[116:119], v[226:229], v[144:147], v[116:119]
	v_mfma_f32_16x16x32_bf16 v[112:115], v[236:239], v[144:147], v[112:115]
	v_mfma_f32_16x16x32_bf16 v[100:103], v[226:229], v[152:155], v[100:103]
	v_mfma_f32_16x16x32_bf16 v[96:99], v[236:239], v[152:155], v[96:99]
	v_mfma_f32_16x16x32_bf16 v[84:87], v[226:229], v[190:193], v[84:87]
	v_mfma_f32_16x16x32_bf16 v[80:83], v[236:239], v[190:193], v[80:83]
	v_mfma_f32_16x16x32_bf16 v[68:71], v[226:229], v[204:207], v[68:71]
	v_mfma_f32_16x16x32_bf16 v[64:67], v[236:239], v[204:207], v[64:67]
	v_mfma_f32_16x16x32_bf16 v[116:119], v[232:235], v[148:151], v[116:119]
	v_mfma_f32_16x16x32_bf16 v[112:115], v[240:243], v[148:151], v[112:115]
	v_mfma_f32_16x16x32_bf16 v[100:103], v[232:235], v[186:189], v[100:103]
	v_mfma_f32_16x16x32_bf16 v[96:99], v[240:243], v[186:189], v[96:99]
	v_mfma_f32_16x16x32_bf16 v[84:87], v[232:235], v[194:197], v[84:87]
	v_mfma_f32_16x16x32_bf16 v[80:83], v[240:243], v[194:197], v[80:83]
	v_mfma_f32_16x16x32_bf16 v[68:71], v[232:235], v[208:211], v[68:71]
	v_mfma_f32_16x16x32_bf16 v[64:67], v[240:243], v[208:211], v[64:67]
	s_mov_b32 m0, s65
	v_lshl_add_u64 v[222:223], s[48:49], 0, v[176:177]
	s_barrier
	ds_read_b128 v[144:147], v203 offset:16384
	ds_read_b128 v[148:151], v203 offset:17408
	ds_read_b128 v[152:155], v203 offset:18432
	ds_read_b128 v[186:189], v203 offset:19456
	ds_read_b128 v[190:193], v203 offset:20480
	ds_read_b128 v[194:197], v203 offset:21504
	ds_read_b128 v[204:207], v203 offset:22528
	ds_read_b128 v[208:211], v203 offset:23552
	global_load_lds_dwordx4 v[222:223], off
	v_lshl_add_u64 v[244:245], s[48:49], 0, v[158:159]
	s_mov_b32 m0, s51
	s_nop 0
	global_load_lds_dwordx4 v[244:245], off
	s_barrier
	s_waitcnt lgkmcnt(0)
	s_waitcnt lgkmcnt(0)
	v_mfma_f32_16x16x32_bf16 v[60:63], v[120:123], v[144:147], v[60:63]
	v_mfma_f32_16x16x32_bf16 v[56:59], v[136:139], v[144:147], v[56:59]
	v_mfma_f32_16x16x32_bf16 v[44:47], v[120:123], v[152:155], v[44:47]
	v_mfma_f32_16x16x32_bf16 v[40:43], v[136:139], v[152:155], v[40:43]
	v_mfma_f32_16x16x32_bf16 v[28:31], v[120:123], v[190:193], v[28:31]
	v_mfma_f32_16x16x32_bf16 v[24:27], v[136:139], v[190:193], v[24:27]
	v_mfma_f32_16x16x32_bf16 v[12:15], v[120:123], v[204:207], v[12:15]
	v_mfma_f32_16x16x32_bf16 v[8:11], v[136:139], v[204:207], v[8:11]
	v_mfma_f32_16x16x32_bf16 v[60:63], v[124:127], v[148:151], v[60:63]
	v_mfma_f32_16x16x32_bf16 v[56:59], v[140:143], v[148:151], v[56:59]
	v_mfma_f32_16x16x32_bf16 v[44:47], v[124:127], v[186:189], v[44:47]
	v_mfma_f32_16x16x32_bf16 v[40:43], v[140:143], v[186:189], v[40:43]
	v_mfma_f32_16x16x32_bf16 v[28:31], v[124:127], v[194:197], v[28:31]
	v_mfma_f32_16x16x32_bf16 v[24:27], v[140:143], v[194:197], v[24:27]
	v_mfma_f32_16x16x32_bf16 v[12:15], v[124:127], v[208:211], v[12:15]
	v_mfma_f32_16x16x32_bf16 v[8:11], v[140:143], v[208:211], v[8:11]
	s_barrier
; #define PG8_STAGE(bufoff, gbase, voff) do { _Pragma("unroll") for (int _i = 0; _i < 2; ++_i) \
;     __builtin_amdgcn_global_load_lds((const unsigned*)((const char*)(gbase) + (voff)[_i]), (LAS unsigned*)(lds + (bufoff) + ldsw + _i * 8192), 16, 0, 0); } while (0)
; #define PG8_LDA(dst, b, h) do { _Pragma("unroll") for (int m = 0; m < 4; ++m) _Pragma("unroll") for (int k = 0; k < 2; ++k) dst[m][k] = *(const LAS bf16x8*)(lds + PG8_SA(b, h) + aoff + m * 2048 + k * 1024); } while (0)
; #define PG8_LDB(dst, b, h) do { _Pragma("unroll") for (int n = 0; n < 2; ++n) _Pragma("unroll") for (int k = 0; k < 2; ++k) dst[n][k] = *(const LAS bf16x8*)(lds + PG8_SB(b, h) + boff + n * 2048 + k * 1024); } while (0)
; #define PG8_MMA(ai, bj, At, Bt) do { __builtin_amdgcn_s_setprio(1); _Pragma("unroll") for (int m = 0; m < 4; ++m) _Pragma("unroll") for (int n = 0; n < 2; ++n) _Pragma("unroll") for (int k = 0; k < 2; ++k) \
;     acc[ai][bj][m][n] = __builtin_amdgcn_mfma_f32_16x16x32_bf16(Bt[n][k], At[m][k], acc[ai][bj][m][n], 0, 0, 0); __builtin_amdgcn_s_setprio(0); } while (0)
; #define PG8_WAIT_V(n) asm volatile("s_waitcnt vmcnt(" #n ")" ::: "memory")
; #define PG8_WAIT_L(n) asm volatile("s_waitcnt lgkmcnt(" #n ")" ::: "memory")
; #define PG8_BAR __builtin_amdgcn_s_barrier()
; #define PG8_SCHED __builtin_amdgcn_sched_barrier(0)
; template <class Epi, class Sched>
; __device__ __forceinline__ void gemm_phase(LAS unsigned char* lds, const Gemm g, const Sched& S, const Epi& E) {
;     ...
;       PG8_STAGE(PG8_SB(0, 1), b2 + hstep, voffB);
;       PG8_WAIT_V(6); PG8_BAR; PG8_MMA(1, 1, At, B1); PG8_BAR;
;       PG8_LDB(B0, 1, 0); PG8_SCHED; PG8_LDA(At, 1, 0); PG8_STAGE(PG8_SA(0, 1), a2 + hstep, voffA);
;       PG8_WAIT_L(8); PG8_BAR; PG8_WAIT_L(0); PG8_MMA(0, 0, At, B0); PG8_BAR; PG8_SCHED;
;       PG8_LDB(B1, 1, 1); PG8_STAGE(PG8_SB(1, 0), b3, voffB);
	s_add_u32 s74, vcc_lo, 0x40000
	s_addc_u32 s75, vcc_hi, 0
	s_add_i32 s73, s76, s64
	v_lshl_add_u64 v[120:121], s[74:75], 0, v[174:175]
	s_mov_b32 m0, s73
	s_nop 0
	global_load_lds_dwordx4 v[120:121], off
	v_lshl_add_u64 v[120:121], s[74:75], 0, v[156:157]
	s_add_i32 m0, s73, 0x2000
	s_nop 0
	global_load_lds_dwordx4 v[120:121], off
	s_waitcnt vmcnt(6)
	s_barrier
	v_mfma_f32_16x16x32_bf16 v[52:55], v[226:229], v[144:147], v[52:55]
	v_mfma_f32_16x16x32_bf16 v[48:51], v[236:239], v[144:147], v[48:51]
	v_mfma_f32_16x16x32_bf16 v[36:39], v[226:229], v[152:155], v[36:39]
	v_mfma_f32_16x16x32_bf16 v[32:35], v[236:239], v[152:155], v[32:35]
	v_mfma_f32_16x16x32_bf16 v[20:23], v[226:229], v[190:193], v[20:23]
	v_mfma_f32_16x16x32_bf16 v[16:19], v[236:239], v[190:193], v[16:19]
	v_mfma_f32_16x16x32_bf16 v[4:7], v[226:229], v[204:207], v[4:7]
	v_mfma_f32_16x16x32_bf16 v[0:3], v[236:239], v[204:207], v[0:3]
	v_mfma_f32_16x16x32_bf16 v[52:55], v[232:235], v[148:151], v[52:55]
	v_mfma_f32_16x16x32_bf16 v[48:51], v[240:243], v[148:151], v[48:51]
	v_mfma_f32_16x16x32_bf16 v[36:39], v[232:235], v[186:189], v[36:39]
	v_mfma_f32_16x16x32_bf16 v[32:35], v[240:243], v[186:189], v[32:35]
	v_mfma_f32_16x16x32_bf16 v[20:23], v[232:235], v[194:197], v[20:23]
	v_mfma_f32_16x16x32_bf16 v[16:19], v[240:243], v[194:197], v[16:19]
	v_mfma_f32_16x16x32_bf16 v[4:7], v[232:235], v[208:211], v[4:7]
	v_mfma_f32_16x16x32_bf16 v[0:3], v[240:243], v[208:211], v[0:3]
	s_add_i32 s73, 0, 0x18000
	v_add_u32_e32 v140, s73, v201
	s_barrier
	ds_read_b128 v[120:123], v140
	ds_read_b128 v[124:127], v140 offset:1024
	ds_read_b128 v[136:139], v140 offset:2048
	ds_read_b128 v[140:143], v140 offset:3072
	s_add_u32 s48, s48, 0x40000
	s_addc_u32 s49, s49, 0
	s_mov_b32 m0, s62
	v_lshl_add_u64 v[226:227], s[48:49], 0, v[176:177]
	ds_read_b128 v[144:147], v203 offset:32768
	ds_read_b128 v[148:151], v203 offset:33792
	ds_read_b128 v[152:155], v203 offset:34816
	ds_read_b128 v[186:189], v203 offset:35840
	ds_read_b128 v[190:193], v203 offset:36864
	ds_read_b128 v[194:197], v203 offset:37888
	ds_read_b128 v[204:207], v203 offset:38912
	ds_read_b128 v[208:211], v203 offset:39936
	global_load_lds_dwordx4 v[226:227], off
	v_lshl_add_u64 v[226:227], s[48:49], 0, v[158:159]
	s_mov_b32 m0, s63
	s_nop 0
	global_load_lds_dwordx4 v[226:227], off
	s_waitcnt lgkmcnt(8)
	s_barrier
	s_waitcnt lgkmcnt(0)
	s_waitcnt lgkmcnt(0)
	v_mfma_f32_16x16x32_bf16 v[132:135], v[120:123], v[144:147], v[132:135]
	v_mfma_f32_16x16x32_bf16 v[128:131], v[136:139], v[144:147], v[128:131]
	v_mfma_f32_16x16x32_bf16 v[108:111], v[120:123], v[152:155], v[108:111]
	v_mfma_f32_16x16x32_bf16 v[104:107], v[136:139], v[152:155], v[104:107]
	v_mfma_f32_16x16x32_bf16 v[92:95], v[120:123], v[190:193], v[92:95]
	v_mfma_f32_16x16x32_bf16 v[88:91], v[136:139], v[190:193], v[88:91]
	v_mfma_f32_16x16x32_bf16 v[76:79], v[120:123], v[204:207], v[76:79]
	v_mfma_f32_16x16x32_bf16 v[72:75], v[136:139], v[204:207], v[72:75]
	v_mfma_f32_16x16x32_bf16 v[132:135], v[124:127], v[148:151], v[132:135]
	v_mfma_f32_16x16x32_bf16 v[128:131], v[140:143], v[148:151], v[128:131]
	v_mfma_f32_16x16x32_bf16 v[108:111], v[124:127], v[186:189], v[108:111]
	v_mfma_f32_16x16x32_bf16 v[104:107], v[140:143], v[186:189], v[104:107]
	v_mfma_f32_16x16x32_bf16 v[92:95], v[124:127], v[194:197], v[92:95]
	v_mfma_f32_16x16x32_bf16 v[88:91], v[140:143], v[194:197], v[88:91]
	v_mfma_f32_16x16x32_bf16 v[76:79], v[124:127], v[208:211], v[76:79]
	v_mfma_f32_16x16x32_bf16 v[72:75], v[140:143], v[208:211], v[72:75]
	s_barrier
	s_add_i32 s74, 0, 0x1c000
	s_add_i32 s48, s73, s64
	v_add_u32_e32 v160, s74, v201
	v_lshl_add_u64 v[198:199], v[198:199], 0, s[80:81]
	s_mov_b32 m0, s48
	ds_read_b128 v[226:229], v160
	ds_read_b128 v[232:235], v160 offset:1024
	ds_read_b128 v[236:239], v160 offset:2048
	ds_read_b128 v[240:243], v160 offset:3072
	global_load_lds_dwordx4 v[198:199], off
	v_lshl_add_u64 v[198:199], v[212:213], 0, s[80:81]
	s_add_i32 m0, s48, 0x2000
	s_nop 0
	global_load_lds_dwordx4 v[198:199], off
	s_barrier
; #define PG8_STAGE(bufoff, gbase, voff) do { _Pragma("unroll") for (int _i = 0; _i < 2; ++_i) \
;     __builtin_amdgcn_global_load_lds((const unsigned*)((const char*)(gbase) + (voff)[_i]), (LAS unsigned*)(lds + (bufoff) + ldsw + _i * 8192), 16, 0, 0); } while (0)
; #define PG8_LDA(dst, b, h) do { _Pragma("unroll") for (int m = 0; m < 4; ++m) _Pragma("unroll") for (int k = 0; k < 2; ++k) dst[m][k] = *(const LAS bf16x8*)(lds + PG8_SA(b, h) + aoff + m * 2048 + k * 1024); } while (0)
; #define PG8_MMA(ai, bj, At, Bt) do { __builtin_amdgcn_s_setprio(1); _Pragma("unroll") for (int m = 0; m < 4; ++m) _Pragma("unroll") for (int n = 0; n < 2; ++n) _Pragma("unroll") for (int k = 0; k < 2; ++k) \
;     acc[ai][bj][m][n] = __builtin_amdgcn_mfma_f32_16x16x32_bf16(Bt[n][k], At[m][k], acc[ai][bj][m][n], 0, 0, 0); __builtin_amdgcn_s_setprio(0); } while (0)
; #define PG8_WAIT_V(n) asm volatile("s_waitcnt vmcnt(" #n ")" ::: "memory")
; #define PG8_WAIT_L(n) asm volatile("s_waitcnt lgkmcnt(" #n ")" ::: "memory")
; #define PG8_BAR __builtin_amdgcn_s_barrier()
; #define PG8_SCHED __builtin_amdgcn_sched_barrier(0)
; template <class Epi, class Sched>
; __device__ __forceinline__ void gemm_phase(LAS unsigned char* lds, const Gemm g, const Sched& S, const Epi& E) {
;     ...
;       PG8_BAR; PG8_WAIT_L(0); PG8_MMA(0, 1, At, B1); PG8_BAR;
;       PG8_LDA(At, 1, 1); PG8_STAGE(PG8_SA(1, 0), a3, voffA);
;       PG8_BAR; PG8_WAIT_L(0); PG8_MMA(1, 0, At, B0); PG8_BAR; PG8_SCHED;
;       PG8_STAGE(PG8_SB(1, 1), b3 + hstep, voffB);
;       PG8_WAIT_V(6); PG8_BAR; PG8_MMA(1, 1, At, B1); PG8_BAR;
;     }
	s_waitcnt lgkmcnt(0)
	s_waitcnt lgkmcnt(0)
	v_mfma_f32_16x16x32_bf16 v[116:119], v[226:229], v[144:147], v[116:119]
	v_mfma_f32_16x16x32_bf16 v[112:115], v[236:239], v[144:147], v[112:115]
	v_mfma_f32_16x16x32_bf16 v[100:103], v[226:229], v[152:155], v[100:103]
	v_mfma_f32_16x16x32_bf16 v[96:99], v[236:239], v[152:155], v[96:99]
	v_mfma_f32_16x16x32_bf16 v[84:87], v[226:229], v[190:193], v[84:87]
	v_mfma_f32_16x16x32_bf16 v[80:83], v[236:239], v[190:193], v[80:83]
	v_mfma_f32_16x16x32_bf16 v[68:71], v[226:229], v[204:207], v[68:71]
	v_mfma_f32_16x16x32_bf16 v[64:67], v[236:239], v[204:207], v[64:67]
	v_mfma_f32_16x16x32_bf16 v[116:119], v[232:235], v[148:151], v[116:119]
	v_mfma_f32_16x16x32_bf16 v[112:115], v[240:243], v[148:151], v[112:115]
	v_mfma_f32_16x16x32_bf16 v[100:103], v[232:235], v[186:189], v[100:103]
	v_mfma_f32_16x16x32_bf16 v[96:99], v[240:243], v[186:189], v[96:99]
	v_mfma_f32_16x16x32_bf16 v[84:87], v[232:235], v[194:197], v[84:87]
	v_mfma_f32_16x16x32_bf16 v[80:83], v[240:243], v[194:197], v[80:83]
	v_mfma_f32_16x16x32_bf16 v[68:71], v[232:235], v[208:211], v[68:71]
	v_mfma_f32_16x16x32_bf16 v[64:67], v[240:243], v[208:211], v[64:67]
	s_mov_b32 m0, s70
	v_lshl_add_u64 v[198:199], v[222:223], 0, s[80:81]
	s_barrier
	ds_read_b128 v[144:147], v203 offset:49152
	ds_read_b128 v[148:151], v203 offset:50176
	ds_read_b128 v[152:155], v203 offset:51200
	ds_read_b128 v[186:189], v203 offset:52224
	ds_read_b128 v[190:193], v203 offset:53248
	ds_read_b128 v[194:197], v203 offset:54272
	ds_read_b128 v[204:207], v203 offset:55296
	ds_read_b128 v[208:211], v203 offset:56320
	global_load_lds_dwordx4 v[198:199], off
	v_lshl_add_u64 v[198:199], v[244:245], 0, s[80:81]
	s_mov_b32 m0, s71
	s_nop 0
	global_load_lds_dwordx4 v[198:199], off
	s_barrier
	s_waitcnt lgkmcnt(0)
	s_waitcnt lgkmcnt(0)
	v_mfma_f32_16x16x32_bf16 v[60:63], v[120:123], v[144:147], v[60:63]
	v_mfma_f32_16x16x32_bf16 v[56:59], v[136:139], v[144:147], v[56:59]
	v_mfma_f32_16x16x32_bf16 v[44:47], v[120:123], v[152:155], v[44:47]
	v_mfma_f32_16x16x32_bf16 v[40:43], v[136:139], v[152:155], v[40:43]
	v_mfma_f32_16x16x32_bf16 v[28:31], v[120:123], v[190:193], v[28:31]
	v_mfma_f32_16x16x32_bf16 v[24:27], v[136:139], v[190:193], v[24:27]
	v_mfma_f32_16x16x32_bf16 v[12:15], v[120:123], v[204:207], v[12:15]
	v_mfma_f32_16x16x32_bf16 v[8:11], v[136:139], v[204:207], v[8:11]
	v_mfma_f32_16x16x32_bf16 v[60:63], v[124:127], v[148:151], v[60:63]
	v_mfma_f32_16x16x32_bf16 v[56:59], v[140:143], v[148:151], v[56:59]
	v_mfma_f32_16x16x32_bf16 v[44:47], v[124:127], v[186:189], v[44:47]
	v_mfma_f32_16x16x32_bf16 v[40:43], v[140:143], v[186:189], v[40:43]
	v_mfma_f32_16x16x32_bf16 v[28:31], v[124:127], v[194:197], v[28:31]
	v_mfma_f32_16x16x32_bf16 v[24:27], v[140:143], v[194:197], v[24:27]
	v_mfma_f32_16x16x32_bf16 v[12:15], v[124:127], v[208:211], v[12:15]
	v_mfma_f32_16x16x32_bf16 v[8:11], v[140:143], v[208:211], v[8:11]
	s_barrier
	s_add_u32 s48, vcc_lo, 0x40080
	s_addc_u32 s49, vcc_hi, 0
	s_add_i32 s73, s74, s64
	v_lshl_add_u64 v[120:121], s[48:49], 0, v[174:175]
	s_mov_b32 m0, s73
	s_nop 0
	global_load_lds_dwordx4 v[120:121], off
	v_lshl_add_u64 v[120:121], s[48:49], 0, v[156:157]
	s_add_i32 m0, s73, 0x2000
	s_nop 0
	global_load_lds_dwordx4 v[120:121], off
	s_waitcnt vmcnt(6)
	s_barrier
	v_mfma_f32_16x16x32_bf16 v[52:55], v[226:229], v[144:147], v[52:55]
	v_mfma_f32_16x16x32_bf16 v[48:51], v[236:239], v[144:147], v[48:51]
	v_mfma_f32_16x16x32_bf16 v[36:39], v[226:229], v[152:155], v[36:39]
	v_mfma_f32_16x16x32_bf16 v[32:35], v[236:239], v[152:155], v[32:35]
	v_mfma_f32_16x16x32_bf16 v[20:23], v[226:229], v[190:193], v[20:23]
	v_mfma_f32_16x16x32_bf16 v[16:19], v[236:239], v[190:193], v[16:19]
	v_mfma_f32_16x16x32_bf16 v[4:7], v[226:229], v[204:207], v[4:7]
	v_mfma_f32_16x16x32_bf16 v[0:3], v[236:239], v[204:207], v[0:3]
	v_mfma_f32_16x16x32_bf16 v[52:55], v[232:235], v[148:151], v[52:55]
	v_mfma_f32_16x16x32_bf16 v[48:51], v[240:243], v[148:151], v[48:51]
	v_mfma_f32_16x16x32_bf16 v[36:39], v[232:235], v[186:189], v[36:39]
	v_mfma_f32_16x16x32_bf16 v[32:35], v[240:243], v[186:189], v[32:35]
	v_mfma_f32_16x16x32_bf16 v[20:23], v[232:235], v[194:197], v[20:23]
	v_mfma_f32_16x16x32_bf16 v[16:19], v[240:243], v[194:197], v[16:19]
	v_mfma_f32_16x16x32_bf16 v[4:7], v[232:235], v[208:211], v[4:7]
	v_mfma_f32_16x16x32_bf16 v[0:3], v[240:243], v[208:211], v[0:3]
	s_add_i32 s72, s72, 2
	s_add_u32 s34, s34, 0x100
	s_addc_u32 s35, s35, 0
	s_add_u32 s69, s69, 0x100
	s_addc_u32 s52, s52, 0
	s_cmp_gt_u32 s72, 13
	s_barrier
	s_cbranch_scc0 .LBB0_707
	s_cmp_lt_u32 s101, 0x100
	s_cbranch_scc0 .Lxa_3
	s_barrier

; #define PG8_STAGE(bufoff, gbase, voff) do { _Pragma("unroll") for (int _i = 0; _i < 2; ++_i) \
;     __builtin_amdgcn_global_load_lds((const unsigned*)((const char*)(gbase) + (voff)[_i]), (LAS unsigned*)(lds + (bufoff) + ldsw + _i * 8192), 16, 0, 0); } while (0)
; #define PG8_LDA(dst, b, h) do { _Pragma("unroll") for (int m = 0; m < 4; ++m) _Pragma("unroll") for (int k = 0; k < 2; ++k) dst[m][k] = *(const LAS bf16x8*)(lds + PG8_SA(b, h) + aoff + m * 2048 + k * 1024); } while (0)
; #define PG8_LDB(dst, b, h) do { _Pragma("unroll") for (int n = 0; n < 2; ++n) _Pragma("unroll") for (int k = 0; k < 2; ++k) dst[n][k] = *(const LAS bf16x8*)(lds + PG8_SB(b, h) + boff + n * 2048 + k * 1024); } while (0)
; #define PG8_MMA(ai, bj, At, Bt) do { __builtin_amdgcn_s_setprio(1); _Pragma("unroll") for (int m = 0; m < 4; ++m) _Pragma("unroll") for (int n = 0; n < 2; ++n) _Pragma("unroll") for (int k = 0; k < 2; ++k) \
;     acc[ai][bj][m][n] = __builtin_amdgcn_mfma_f32_16x16x32_bf16(Bt[n][k], At[m][k], acc[ai][bj][m][n], 0, 0, 0); __builtin_amdgcn_s_setprio(0); } while (0)
; #define PG8_WAIT_L(n) asm volatile("s_waitcnt lgkmcnt(" #n ")" ::: "memory")
; #define PG8_BAR __builtin_amdgcn_s_barrier()
; #define PG8_SCHED __builtin_amdgcn_sched_barrier(0)
; template <class Epi, class Sched>
; __device__ __forceinline__ void gemm_phase(LAS unsigned char* lds, const Gemm g, const Sched& S, const Epi& E) {
;     ...
;     for (int t = 0; t < nt; t += 2) {
;       const bool last = (t == nt - 2);
;       const char* a1 = cA + (size_t)(t + 1) * kstep;
;       const char* a2 = last ? nA : cA + (size_t)(t + 2) * kstep; const char* b2 = last ? nB : cB + (size_t)(t + 2) * kstep;
;       const char* a3 = a2 + kstep; const char* b3 = b2 + kstep;
;       if (last && has_next) S.a_ready(nxt);
;       PG8_LDB(B0, 0, 0); PG8_SCHED; PG8_LDA(At, 0, 0); PG8_STAGE(PG8_SA(1, 1), a1 + hstep, voffA);
;       PG8_WAIT_L(8); PG8_BAR; PG8_WAIT_L(0); PG8_MMA(0, 0, At, B0); PG8_BAR; PG8_SCHED;
;       PG8_LDB(B1, 0, 1); PG8_STAGE(PG8_SB(0, 0), b2, voffB);
;       PG8_BAR; PG8_WAIT_L(0); PG8_MMA(0, 1, At, B1); PG8_BAR;
;       PG8_LDA(At, 0, 1); PG8_STAGE(PG8_SA(0, 0), a2, voffA);
;       PG8_BAR; PG8_WAIT_L(0); PG8_MMA(1, 0, At, B0); PG8_BAR; PG8_SCHED;
.Lxs_e4:
.LBB0_778:
	s_add_u32 s44, s34, 0xfffe0080
	s_addc_u32 s45, s35, -1
	s_add_i32 s73, 0, 0x10000
	v_add_u32_e32 v150, s73, v177
	ds_read_b128 v[138:141], v150
	ds_read_b128 v[142:145], v150 offset:1024
	ds_read_b128 v[146:149], v150 offset:2048
	ds_read_b128 v[150:153], v150 offset:3072
	s_cmp_eq_u32 s72, 4
	s_cselect_b32 s49, s37, s45
	s_cselect_b32 s48, s69, s44
	s_cselect_b32 s45, s23, s52
	s_cselect_b32 s44, s70, s71
	v_lshl_add_u64 v[158:159], s[34:35], 0, v[134:135]
	s_add_i32 m0, s12, 0xc000
	ds_read_b128 v[154:157], v179
	ds_read_b128 v[180:183], v179 offset:1024
	ds_read_b128 v[184:187], v179 offset:2048
	ds_read_b128 v[188:191], v179 offset:3072
	ds_read_b128 v[192:195], v179 offset:4096
	ds_read_b128 v[196:199], v179 offset:5120
	ds_read_b128 v[200:203], v179 offset:6144
	ds_read_b128 v[204:207], v179 offset:7168
	global_load_lds_dwordx4 v[158:159], off
	v_lshl_add_u64 v[158:159], s[34:35], 0, v[136:137]
	s_add_i32 m0, s12, 0xe000
	s_nop 0
	global_load_lds_dwordx4 v[158:159], off
	s_waitcnt lgkmcnt(8)
	s_barrier
	s_waitcnt lgkmcnt(0)
	s_waitcnt lgkmcnt(0)
	v_mfma_f32_16x16x32_bf16 v[124:127], v[138:141], v[154:157], v[124:127]
	v_mfma_f32_16x16x32_bf16 v[120:123], v[146:149], v[154:157], v[120:123]
	v_mfma_f32_16x16x32_bf16 v[108:111], v[138:141], v[184:187], v[108:111]
	v_mfma_f32_16x16x32_bf16 v[104:107], v[146:149], v[184:187], v[104:107]
	v_mfma_f32_16x16x32_bf16 v[92:95], v[138:141], v[192:195], v[92:95]
	v_mfma_f32_16x16x32_bf16 v[88:91], v[146:149], v[192:195], v[88:91]
	v_mfma_f32_16x16x32_bf16 v[76:79], v[138:141], v[200:203], v[76:79]
	v_mfma_f32_16x16x32_bf16 v[72:75], v[146:149], v[200:203], v[72:75]
	v_mfma_f32_16x16x32_bf16 v[124:127], v[142:145], v[180:183], v[124:127]
	v_mfma_f32_16x16x32_bf16 v[120:123], v[150:153], v[180:183], v[120:123]
	v_mfma_f32_16x16x32_bf16 v[108:111], v[142:145], v[188:191], v[108:111]
	v_mfma_f32_16x16x32_bf16 v[104:107], v[150:153], v[188:191], v[104:107]
	v_mfma_f32_16x16x32_bf16 v[92:95], v[142:145], v[196:199], v[92:95]
	v_mfma_f32_16x16x32_bf16 v[88:91], v[150:153], v[196:199], v[88:91]
	v_mfma_f32_16x16x32_bf16 v[76:79], v[142:145], v[204:207], v[76:79]
	v_mfma_f32_16x16x32_bf16 v[72:75], v[150:153], v[204:207], v[72:75]
	s_barrier
	s_add_i32 s76, 0, 0x14000
	v_add_u32_e32 v158, s76, v177
	s_add_i32 s73, s73, s7
	ds_read_b128 v[208:211], v158
	ds_read_b128 v[226:229], v158 offset:1024
	ds_read_b128 v[232:235], v158 offset:2048
	ds_read_b128 v[236:239], v158 offset:3072
	v_lshl_add_u64 v[158:159], s[44:45], 0, v[160:161]
	s_mov_b32 m0, s73
	v_lshl_add_u64 v[174:175], s[44:45], 0, v[128:129]
	global_load_lds_dwordx4 v[158:159], off
	s_add_i32 m0, s73, 0x2000
	s_nop 0
	global_load_lds_dwordx4 v[174:175], off
	s_barrier
	s_waitcnt lgkmcnt(0)
	s_waitcnt lgkmcnt(0)
	v_mfma_f32_16x16x32_bf16 v[116:119], v[208:211], v[154:157], v[116:119]
	v_mfma_f32_16x16x32_bf16 v[112:115], v[232:235], v[154:157], v[112:115]
	v_mfma_f32_16x16x32_bf16 v[100:103], v[208:211], v[184:187], v[100:103]
	v_mfma_f32_16x16x32_bf16 v[96:99], v[232:235], v[184:187], v[96:99]
	v_mfma_f32_16x16x32_bf16 v[84:87], v[208:211], v[192:195], v[84:87]
	v_mfma_f32_16x16x32_bf16 v[80:83], v[232:235], v[192:195], v[80:83]
	v_mfma_f32_16x16x32_bf16 v[68:71], v[208:211], v[200:203], v[68:71]
	v_mfma_f32_16x16x32_bf16 v[64:67], v[232:235], v[200:203], v[64:67]
	v_mfma_f32_16x16x32_bf16 v[116:119], v[226:229], v[180:183], v[116:119]
	v_mfma_f32_16x16x32_bf16 v[112:115], v[236:239], v[180:183], v[112:115]
	v_mfma_f32_16x16x32_bf16 v[100:103], v[226:229], v[188:191], v[100:103]
	v_mfma_f32_16x16x32_bf16 v[96:99], v[236:239], v[188:191], v[96:99]
	v_mfma_f32_16x16x32_bf16 v[84:87], v[226:229], v[196:199], v[84:87]
	v_mfma_f32_16x16x32_bf16 v[80:83], v[236:239], v[196:199], v[80:83]
	v_mfma_f32_16x16x32_bf16 v[68:71], v[226:229], v[204:207], v[68:71]
	v_mfma_f32_16x16x32_bf16 v[64:67], v[236:239], v[204:207], v[64:67]
	s_mov_b32 m0, s12
	v_lshl_add_u64 v[212:213], s[48:49], 0, v[132:133]
	s_barrier
	ds_read_b128 v[154:157], v179 offset:16384
	ds_read_b128 v[180:183], v179 offset:17408
	ds_read_b128 v[184:187], v179 offset:18432
	ds_read_b128 v[188:191], v179 offset:19456
	ds_read_b128 v[192:195], v179 offset:20480
	ds_read_b128 v[196:199], v179 offset:21504
	ds_read_b128 v[200:203], v179 offset:22528
	ds_read_b128 v[204:207], v179 offset:23552
	global_load_lds_dwordx4 v[212:213], off
	v_lshl_add_u64 v[222:223], s[48:49], 0, v[130:131]
	s_mov_b32 m0, s13
	s_nop 0
	global_load_lds_dwordx4 v[222:223], off
	s_barrier
	s_waitcnt lgkmcnt(0)
	s_waitcnt lgkmcnt(0)
	v_mfma_f32_16x16x32_bf16 v[60:63], v[138:141], v[154:157], v[60:63]
	v_mfma_f32_16x16x32_bf16 v[56:59], v[146:149], v[154:157], v[56:59]
	v_mfma_f32_16x16x32_bf16 v[44:47], v[138:141], v[184:187], v[44:47]
	v_mfma_f32_16x16x32_bf16 v[40:43], v[146:149], v[184:187], v[40:43]
	v_mfma_f32_16x16x32_bf16 v[28:31], v[138:141], v[192:195], v[28:31]
	v_mfma_f32_16x16x32_bf16 v[24:27], v[146:149], v[192:195], v[24:27]
	v_mfma_f32_16x16x32_bf16 v[12:15], v[138:141], v[200:203], v[12:15]
	v_mfma_f32_16x16x32_bf16 v[8:11], v[146:149], v[200:203], v[8:11]
	v_mfma_f32_16x16x32_bf16 v[60:63], v[142:145], v[180:183], v[60:63]
	v_mfma_f32_16x16x32_bf16 v[56:59], v[150:153], v[180:183], v[56:59]
	v_mfma_f32_16x16x32_bf16 v[44:47], v[142:145], v[188:191], v[44:47]
	v_mfma_f32_16x16x32_bf16 v[40:43], v[150:153], v[188:191], v[40:43]
	v_mfma_f32_16x16x32_bf16 v[28:31], v[142:145], v[196:199], v[28:31]
	v_mfma_f32_16x16x32_bf16 v[24:27], v[150:153], v[196:199], v[24:27]
	v_mfma_f32_16x16x32_bf16 v[12:15], v[142:145], v[204:207], v[12:15]
	v_mfma_f32_16x16x32_bf16 v[8:11], v[150:153], v[204:207], v[8:11]
	s_barrier
; #define PG8_STAGE(bufoff, gbase, voff) do { _Pragma("unroll") for (int _i = 0; _i < 2; ++_i) \
;     __builtin_amdgcn_global_load_lds((const unsigned*)((const char*)(gbase) + (voff)[_i]), (LAS unsigned*)(lds + (bufoff) + ldsw + _i * 8192), 16, 0, 0); } while (0)
; #define PG8_LDA(dst, b, h) do { _Pragma("unroll") for (int m = 0; m < 4; ++m) _Pragma("unroll") for (int k = 0; k < 2; ++k) dst[m][k] = *(const LAS bf16x8*)(lds + PG8_SA(b, h) + aoff + m * 2048 + k * 1024); } while (0)
; #define PG8_LDB(dst, b, h) do { _Pragma("unroll") for (int n = 0; n < 2; ++n) _Pragma("unroll") for (int k = 0; k < 2; ++k) dst[n][k] = *(const LAS bf16x8*)(lds + PG8_SB(b, h) + boff + n * 2048 + k * 1024); } while (0)
; #define PG8_MMA(ai, bj, At, Bt) do { __builtin_amdgcn_s_setprio(1); _Pragma("unroll") for (int m = 0; m < 4; ++m) _Pragma("unroll") for (int n = 0; n < 2; ++n) _Pragma("unroll") for (int k = 0; k < 2; ++k) \
;     acc[ai][bj][m][n] = __builtin_amdgcn_mfma_f32_16x16x32_bf16(Bt[n][k], At[m][k], acc[ai][bj][m][n], 0, 0, 0); __builtin_amdgcn_s_setprio(0); } while (0)
; #define PG8_WAIT_V(n) asm volatile("s_waitcnt vmcnt(" #n ")" ::: "memory")
; #define PG8_WAIT_L(n) asm volatile("s_waitcnt lgkmcnt(" #n ")" ::: "memory")
; #define PG8_BAR __builtin_amdgcn_s_barrier()
; #define PG8_SCHED __builtin_amdgcn_sched_barrier(0)
; template <class Epi, class Sched>
; __device__ __forceinline__ void gemm_phase(LAS unsigned char* lds, const Gemm g, const Sched& S, const Epi& E) {
;     ...
;       PG8_STAGE(PG8_SB(0, 1), b2 + hstep, voffB);
;       PG8_WAIT_V(6); PG8_BAR; PG8_MMA(1, 1, At, B1); PG8_BAR;
;       PG8_LDB(B0, 1, 0); PG8_SCHED; PG8_LDA(At, 1, 0); PG8_STAGE(PG8_SA(0, 1), a2 + hstep, voffA);
;       PG8_WAIT_L(8); PG8_BAR; PG8_WAIT_L(0); PG8_MMA(0, 0, At, B0); PG8_BAR; PG8_SCHED;
;       PG8_LDB(B1, 1, 1); PG8_STAGE(PG8_SB(1, 0), b3, voffB);
	s_add_u32 s74, s44, 0x20000
	s_addc_u32 s75, s45, 0
	s_add_i32 s73, s76, s7
	v_lshl_add_u64 v[138:139], s[74:75], 0, v[160:161]
	s_mov_b32 m0, s73
	s_nop 0
	global_load_lds_dwordx4 v[138:139], off
	v_lshl_add_u64 v[138:139], s[74:75], 0, v[128:129]
	s_add_i32 m0, s73, 0x2000
	s_nop 0
	global_load_lds_dwordx4 v[138:139], off
	s_waitcnt vmcnt(6)
	s_barrier
	v_mfma_f32_16x16x32_bf16 v[52:55], v[208:211], v[154:157], v[52:55]
	v_mfma_f32_16x16x32_bf16 v[48:51], v[232:235], v[154:157], v[48:51]
	v_mfma_f32_16x16x32_bf16 v[36:39], v[208:211], v[184:187], v[36:39]
	v_mfma_f32_16x16x32_bf16 v[32:35], v[232:235], v[184:187], v[32:35]
	v_mfma_f32_16x16x32_bf16 v[20:23], v[208:211], v[192:195], v[20:23]
	v_mfma_f32_16x16x32_bf16 v[16:19], v[232:235], v[192:195], v[16:19]
	v_mfma_f32_16x16x32_bf16 v[4:7], v[208:211], v[200:203], v[4:7]
	v_mfma_f32_16x16x32_bf16 v[0:3], v[232:235], v[200:203], v[0:3]
	v_mfma_f32_16x16x32_bf16 v[52:55], v[226:229], v[180:183], v[52:55]
	v_mfma_f32_16x16x32_bf16 v[48:51], v[236:239], v[180:183], v[48:51]
	v_mfma_f32_16x16x32_bf16 v[36:39], v[226:229], v[188:191], v[36:39]
	v_mfma_f32_16x16x32_bf16 v[32:35], v[236:239], v[188:191], v[32:35]
	v_mfma_f32_16x16x32_bf16 v[20:23], v[226:229], v[196:199], v[20:23]
	v_mfma_f32_16x16x32_bf16 v[16:19], v[236:239], v[196:199], v[16:19]
	v_mfma_f32_16x16x32_bf16 v[4:7], v[226:229], v[204:207], v[4:7]
	v_mfma_f32_16x16x32_bf16 v[0:3], v[236:239], v[204:207], v[0:3]
	s_add_i32 s73, 0, 0x18000
	v_add_u32_e32 v150, s73, v177
	s_barrier
	ds_read_b128 v[138:141], v150
	ds_read_b128 v[142:145], v150 offset:1024
	ds_read_b128 v[146:149], v150 offset:2048
	ds_read_b128 v[150:153], v150 offset:3072
	s_add_u32 s48, s48, 0x20000
	s_addc_u32 s49, s49, 0
	s_mov_b32 m0, s20
	v_lshl_add_u64 v[208:209], s[48:49], 0, v[132:133]
	ds_read_b128 v[154:157], v179 offset:32768
	ds_read_b128 v[180:183], v179 offset:33792
	ds_read_b128 v[184:187], v179 offset:34816
	ds_read_b128 v[188:191], v179 offset:35840
	ds_read_b128 v[192:195], v179 offset:36864
	ds_read_b128 v[196:199], v179 offset:37888
	ds_read_b128 v[200:203], v179 offset:38912
	ds_read_b128 v[204:207], v179 offset:39936
	global_load_lds_dwordx4 v[208:209], off
	v_lshl_add_u64 v[208:209], s[48:49], 0, v[130:131]
	s_mov_b32 m0, s51
	s_nop 0
	global_load_lds_dwordx4 v[208:209], off
	s_waitcnt lgkmcnt(8)
	s_barrier
	s_waitcnt lgkmcnt(0)
	s_waitcnt lgkmcnt(0)
	v_mfma_f32_16x16x32_bf16 v[124:127], v[138:141], v[154:157], v[124:127]
	v_mfma_f32_16x16x32_bf16 v[120:123], v[146:149], v[154:157], v[120:123]
	v_mfma_f32_16x16x32_bf16 v[108:111], v[138:141], v[184:187], v[108:111]
	v_mfma_f32_16x16x32_bf16 v[104:107], v[146:149], v[184:187], v[104:107]
	v_mfma_f32_16x16x32_bf16 v[92:95], v[138:141], v[192:195], v[92:95]
	v_mfma_f32_16x16x32_bf16 v[88:91], v[146:149], v[192:195], v[88:91]
	v_mfma_f32_16x16x32_bf16 v[76:79], v[138:141], v[200:203], v[76:79]
	v_mfma_f32_16x16x32_bf16 v[72:75], v[146:149], v[200:203], v[72:75]
	v_mfma_f32_16x16x32_bf16 v[124:127], v[142:145], v[180:183], v[124:127]
	v_mfma_f32_16x16x32_bf16 v[120:123], v[150:153], v[180:183], v[120:123]
	v_mfma_f32_16x16x32_bf16 v[108:111], v[142:145], v[188:191], v[108:111]
	v_mfma_f32_16x16x32_bf16 v[104:107], v[150:153], v[188:191], v[104:107]
	v_mfma_f32_16x16x32_bf16 v[92:95], v[142:145], v[196:199], v[92:95]
	v_mfma_f32_16x16x32_bf16 v[88:91], v[150:153], v[196:199], v[88:91]
	v_mfma_f32_16x16x32_bf16 v[76:79], v[142:145], v[204:207], v[76:79]
	v_mfma_f32_16x16x32_bf16 v[72:75], v[150:153], v[204:207], v[72:75]
	s_barrier
	s_add_i32 s48, 0, 0x1c000
	s_add_i32 s49, s73, s7
	v_add_u32_e32 v225, s48, v177
	v_lshl_add_u64 v[158:159], v[158:159], 0, s[80:81]
	s_mov_b32 m0, s49
	ds_read_b128 v[208:211], v225
	ds_read_b128 v[226:229], v225 offset:1024
	ds_read_b128 v[232:235], v225 offset:2048
	ds_read_b128 v[236:239], v225 offset:3072
	global_load_lds_dwordx4 v[158:159], off
	v_lshl_add_u64 v[158:159], v[174:175], 0, s[80:81]
	s_add_i32 m0, s49, 0x2000
	s_nop 0
	global_load_lds_dwordx4 v[158:159], off
	s_barrier
; #define PG8_STAGE(bufoff, gbase, voff) do { _Pragma("unroll") for (int _i = 0; _i < 2; ++_i) \
;     __builtin_amdgcn_global_load_lds((const unsigned*)((const char*)(gbase) + (voff)[_i]), (LAS unsigned*)(lds + (bufoff) + ldsw + _i * 8192), 16, 0, 0); } while (0)
; #define PG8_LDA(dst, b, h) do { _Pragma("unroll") for (int m = 0; m < 4; ++m) _Pragma("unroll") for (int k = 0; k < 2; ++k) dst[m][k] = *(const LAS bf16x8*)(lds + PG8_SA(b, h) + aoff + m * 2048 + k * 1024); } while (0)
; #define PG8_MMA(ai, bj, At, Bt) do { __builtin_amdgcn_s_setprio(1); _Pragma("unroll") for (int m = 0; m < 4; ++m) _Pragma("unroll") for (int n = 0; n < 2; ++n) _Pragma("unroll") for (int k = 0; k < 2; ++k) \
;     acc[ai][bj][m][n] = __builtin_amdgcn_mfma_f32_16x16x32_bf16(Bt[n][k], At[m][k], acc[ai][bj][m][n], 0, 0, 0); __builtin_amdgcn_s_setprio(0); } while (0)
; #define PG8_WAIT_V(n) asm volatile("s_waitcnt vmcnt(" #n ")" ::: "memory")
; #define PG8_WAIT_L(n) asm volatile("s_waitcnt lgkmcnt(" #n ")" ::: "memory")
; #define PG8_BAR __builtin_amdgcn_s_barrier()
; #define PG8_SCHED __builtin_amdgcn_sched_barrier(0)
; template <class Epi, class Sched>
; __device__ __forceinline__ void gemm_phase(LAS unsigned char* lds, const Gemm g, const Sched& S, const Epi& E) {
;     ...
;       PG8_BAR; PG8_WAIT_L(0); PG8_MMA(0, 1, At, B1); PG8_BAR;
;       PG8_LDA(At, 1, 1); PG8_STAGE(PG8_SA(1, 0), a3, voffA);
;       PG8_BAR; PG8_WAIT_L(0); PG8_MMA(1, 0, At, B0); PG8_BAR; PG8_SCHED;
;       PG8_STAGE(PG8_SB(1, 1), b3 + hstep, voffB);
;       PG8_WAIT_V(6); PG8_BAR; PG8_MMA(1, 1, At, B1); PG8_BAR;
;     }
	s_waitcnt lgkmcnt(0)
	s_waitcnt lgkmcnt(0)
	v_mfma_f32_16x16x32_bf16 v[116:119], v[208:211], v[154:157], v[116:119]
	v_mfma_f32_16x16x32_bf16 v[112:115], v[232:235], v[154:157], v[112:115]
	v_mfma_f32_16x16x32_bf16 v[100:103], v[208:211], v[184:187], v[100:103]
	v_mfma_f32_16x16x32_bf16 v[96:99], v[232:235], v[184:187], v[96:99]
	v_mfma_f32_16x16x32_bf16 v[84:87], v[208:211], v[192:195], v[84:87]
	v_mfma_f32_16x16x32_bf16 v[80:83], v[232:235], v[192:195], v[80:83]
	v_mfma_f32_16x16x32_bf16 v[68:71], v[208:211], v[200:203], v[68:71]
	v_mfma_f32_16x16x32_bf16 v[64:67], v[232:235], v[200:203], v[64:67]
	v_mfma_f32_16x16x32_bf16 v[116:119], v[226:229], v[180:183], v[116:119]
	v_mfma_f32_16x16x32_bf16 v[112:115], v[236:239], v[180:183], v[112:115]
	v_mfma_f32_16x16x32_bf16 v[100:103], v[226:229], v[188:191], v[100:103]
	v_mfma_f32_16x16x32_bf16 v[96:99], v[236:239], v[188:191], v[96:99]
	v_mfma_f32_16x16x32_bf16 v[84:87], v[226:229], v[196:199], v[84:87]
	v_mfma_f32_16x16x32_bf16 v[80:83], v[236:239], v[196:199], v[80:83]
	v_mfma_f32_16x16x32_bf16 v[68:71], v[226:229], v[204:207], v[68:71]
	v_mfma_f32_16x16x32_bf16 v[64:67], v[236:239], v[204:207], v[64:67]
	s_mov_b32 m0, s62
	v_lshl_add_u64 v[158:159], v[212:213], 0, s[80:81]
	s_barrier
	ds_read_b128 v[154:157], v179 offset:49152
	ds_read_b128 v[180:183], v179 offset:50176
	ds_read_b128 v[184:187], v179 offset:51200
	ds_read_b128 v[188:191], v179 offset:52224
	ds_read_b128 v[192:195], v179 offset:53248
	ds_read_b128 v[196:199], v179 offset:54272
	ds_read_b128 v[200:203], v179 offset:55296
	ds_read_b128 v[204:207], v179 offset:56320
	global_load_lds_dwordx4 v[158:159], off
	v_lshl_add_u64 v[158:159], v[222:223], 0, s[80:81]
	s_mov_b32 m0, s63
	s_nop 0
	global_load_lds_dwordx4 v[158:159], off
	s_barrier
	s_waitcnt lgkmcnt(0)
	s_waitcnt lgkmcnt(0)
	v_mfma_f32_16x16x32_bf16 v[60:63], v[138:141], v[154:157], v[60:63]
	v_mfma_f32_16x16x32_bf16 v[56:59], v[146:149], v[154:157], v[56:59]
	v_mfma_f32_16x16x32_bf16 v[44:47], v[138:141], v[184:187], v[44:47]
	v_mfma_f32_16x16x32_bf16 v[40:43], v[146:149], v[184:187], v[40:43]
	v_mfma_f32_16x16x32_bf16 v[28:31], v[138:141], v[192:195], v[28:31]
	v_mfma_f32_16x16x32_bf16 v[24:27], v[146:149], v[192:195], v[24:27]
	v_mfma_f32_16x16x32_bf16 v[12:15], v[138:141], v[200:203], v[12:15]
	v_mfma_f32_16x16x32_bf16 v[8:11], v[146:149], v[200:203], v[8:11]
	v_mfma_f32_16x16x32_bf16 v[60:63], v[142:145], v[180:183], v[60:63]
	v_mfma_f32_16x16x32_bf16 v[56:59], v[150:153], v[180:183], v[56:59]
	v_mfma_f32_16x16x32_bf16 v[44:47], v[142:145], v[188:191], v[44:47]
	v_mfma_f32_16x16x32_bf16 v[40:43], v[150:153], v[188:191], v[40:43]
	v_mfma_f32_16x16x32_bf16 v[28:31], v[142:145], v[196:199], v[28:31]
	v_mfma_f32_16x16x32_bf16 v[24:27], v[150:153], v[196:199], v[24:27]
	v_mfma_f32_16x16x32_bf16 v[12:15], v[142:145], v[204:207], v[12:15]
	v_mfma_f32_16x16x32_bf16 v[8:11], v[150:153], v[204:207], v[8:11]
	s_barrier
	s_add_u32 s44, s44, 0x20080
	s_addc_u32 s45, s45, 0
	s_add_i32 s48, s48, s7
	v_lshl_add_u64 v[138:139], s[44:45], 0, v[160:161]
	s_mov_b32 m0, s48
	s_nop 0
	global_load_lds_dwordx4 v[138:139], off
	v_lshl_add_u64 v[138:139], s[44:45], 0, v[128:129]
	s_add_i32 m0, s48, 0x2000
	s_nop 0
	global_load_lds_dwordx4 v[138:139], off
	s_waitcnt vmcnt(6)
	s_barrier
	v_mfma_f32_16x16x32_bf16 v[52:55], v[208:211], v[154:157], v[52:55]
	v_mfma_f32_16x16x32_bf16 v[48:51], v[232:235], v[154:157], v[48:51]
	v_mfma_f32_16x16x32_bf16 v[36:39], v[208:211], v[184:187], v[36:39]
	v_mfma_f32_16x16x32_bf16 v[32:35], v[232:235], v[184:187], v[32:35]
	v_mfma_f32_16x16x32_bf16 v[20:23], v[208:211], v[192:195], v[20:23]
	v_mfma_f32_16x16x32_bf16 v[16:19], v[232:235], v[192:195], v[16:19]
	v_mfma_f32_16x16x32_bf16 v[4:7], v[208:211], v[200:203], v[4:7]
	v_mfma_f32_16x16x32_bf16 v[0:3], v[232:235], v[200:203], v[0:3]
	v_mfma_f32_16x16x32_bf16 v[52:55], v[226:229], v[180:183], v[52:55]
	v_mfma_f32_16x16x32_bf16 v[48:51], v[236:239], v[180:183], v[48:51]
	v_mfma_f32_16x16x32_bf16 v[36:39], v[226:229], v[188:191], v[36:39]
	v_mfma_f32_16x16x32_bf16 v[32:35], v[236:239], v[188:191], v[32:35]
	v_mfma_f32_16x16x32_bf16 v[20:23], v[226:229], v[196:199], v[20:23]
	v_mfma_f32_16x16x32_bf16 v[16:19], v[236:239], v[196:199], v[16:19]
	v_mfma_f32_16x16x32_bf16 v[4:7], v[226:229], v[204:207], v[4:7]
	v_mfma_f32_16x16x32_bf16 v[0:3], v[236:239], v[204:207], v[0:3]
	s_add_i32 s72, s72, 2
	s_add_u32 s34, s34, 0x100
	s_addc_u32 s35, s35, 0
	s_add_u32 s71, s71, 0x100
	s_addc_u32 s52, s52, 0
	s_cmp_gt_u32 s72, 5
	s_barrier
	s_cbranch_scc0 .LBB0_778
	s_cmp_lt_u32 s101, 0x100
	s_cbranch_scc0 .Lxa_4
	s_barrier

; #define PG8_STAGE(bufoff, gbase, voff) do { _Pragma("unroll") for (int _i = 0; _i < 2; ++_i) \
;     __builtin_amdgcn_global_load_lds((const unsigned*)((const char*)(gbase) + (voff)[_i]), (LAS unsigned*)(lds + (bufoff) + ldsw + _i * 8192), 16, 0, 0); } while (0)
; #define PG8_LDA(dst, b, h) do { _Pragma("unroll") for (int m = 0; m < 4; ++m) _Pragma("unroll") for (int k = 0; k < 2; ++k) dst[m][k] = *(const LAS bf16x8*)(lds + PG8_SA(b, h) + aoff + m * 2048 + k * 1024); } while (0)
; #define PG8_LDB(dst, b, h) do { _Pragma("unroll") for (int n = 0; n < 2; ++n) _Pragma("unroll") for (int k = 0; k < 2; ++k) dst[n][k] = *(const LAS bf16x8*)(lds + PG8_SB(b, h) + boff + n * 2048 + k * 1024); } while (0)
; #define PG8_MMA(ai, bj, At, Bt) do { __builtin_amdgcn_s_setprio(1); _Pragma("unroll") for (int m = 0; m < 4; ++m) _Pragma("unroll") for (int n = 0; n < 2; ++n) _Pragma("unroll") for (int k = 0; k < 2; ++k) \
;     acc[ai][bj][m][n] = __builtin_amdgcn_mfma_f32_16x16x32_bf16(Bt[n][k], At[m][k], acc[ai][bj][m][n], 0, 0, 0); __builtin_amdgcn_s_setprio(0); } while (0)
; #define PG8_WAIT_L(n) asm volatile("s_waitcnt lgkmcnt(" #n ")" ::: "memory")
; #define PG8_BAR __builtin_amdgcn_s_barrier()
; #define PG8_SCHED __builtin_amdgcn_sched_barrier(0)
; template <class Epi, class Sched>
; __device__ __forceinline__ void gemm_phase(LAS unsigned char* lds, const Gemm g, const Sched& S, const Epi& E) {
;     ...
;     for (int t = 0; t < nt; t += 2) {
;       const bool last = (t == nt - 2);
;       const char* a1 = cA + (size_t)(t + 1) * kstep;
;       const char* a2 = last ? nA : cA + (size_t)(t + 2) * kstep; const char* b2 = last ? nB : cB + (size_t)(t + 2) * kstep;
;       const char* a3 = a2 + kstep; const char* b3 = b2 + kstep;
;       if (last && has_next) S.a_ready(nxt);
;       PG8_LDB(B0, 0, 0); PG8_SCHED; PG8_LDA(At, 0, 0); PG8_STAGE(PG8_SA(1, 1), a1 + hstep, voffA);
;       PG8_WAIT_L(8); PG8_BAR; PG8_WAIT_L(0); PG8_MMA(0, 0, At, B0); PG8_BAR; PG8_SCHED;
;       PG8_LDB(B1, 0, 1); PG8_STAGE(PG8_SB(0, 0), b2, voffB);
;       PG8_BAR; PG8_WAIT_L(0); PG8_MMA(0, 1, At, B1); PG8_BAR;
;       PG8_LDA(At, 0, 1); PG8_STAGE(PG8_SA(0, 0), a2, voffA);
;       PG8_BAR; PG8_WAIT_L(0); PG8_MMA(1, 0, At, B0); PG8_BAR; PG8_SCHED;
.Lxs_e5:
.LBB0_794:
	s_add_u32 s44, s34, 0xfffc0080
	s_addc_u32 s45, s35, -1
	s_add_i32 s73, 0, 0x10000
	v_add_u32_e32 v140, s73, v226
	ds_read_b128 v[128:131], v140
	ds_read_b128 v[132:135], v140 offset:1024
	ds_read_b128 v[136:139], v140 offset:2048
	ds_read_b128 v[140:143], v140 offset:3072
	s_cmp_eq_u32 s72, 12
	s_cselect_b32 s49, s37, s45
	s_cselect_b32 s48, s69, s44
	s_cselect_b32 s45, s23, s52
	s_cselect_b32 s44, s70, s71
	v_lshl_add_u64 v[200:201], s[34:35], 0, v[180:181]
	s_add_i32 m0, s12, 0xc000
	ds_read_b128 v[144:147], v228
	ds_read_b128 v[148:151], v228 offset:1024
	ds_read_b128 v[152:155], v228 offset:2048
	ds_read_b128 v[156:159], v228 offset:3072
	ds_read_b128 v[184:187], v228 offset:4096
	ds_read_b128 v[188:191], v228 offset:5120
	ds_read_b128 v[192:195], v228 offset:6144
	ds_read_b128 v[196:199], v228 offset:7168
	global_load_lds_dwordx4 v[200:201], off
	v_lshl_add_u64 v[200:201], s[34:35], 0, v[182:183]
	s_add_i32 m0, s12, 0xe000
	s_nop 0
	global_load_lds_dwordx4 v[200:201], off
	s_waitcnt lgkmcnt(8)
	s_barrier
	s_waitcnt lgkmcnt(0)
	s_waitcnt lgkmcnt(0)
	v_mfma_f32_16x16x32_bf16 v[124:127], v[128:131], v[144:147], v[124:127]
	v_mfma_f32_16x16x32_bf16 v[120:123], v[136:139], v[144:147], v[120:123]
	v_mfma_f32_16x16x32_bf16 v[108:111], v[128:131], v[152:155], v[108:111]
	v_mfma_f32_16x16x32_bf16 v[104:107], v[136:139], v[152:155], v[104:107]
	v_mfma_f32_16x16x32_bf16 v[92:95], v[128:131], v[184:187], v[92:95]
	v_mfma_f32_16x16x32_bf16 v[88:91], v[136:139], v[184:187], v[88:91]
	v_mfma_f32_16x16x32_bf16 v[76:79], v[128:131], v[192:195], v[76:79]
	v_mfma_f32_16x16x32_bf16 v[72:75], v[136:139], v[192:195], v[72:75]
	v_mfma_f32_16x16x32_bf16 v[124:127], v[132:135], v[148:151], v[124:127]
	v_mfma_f32_16x16x32_bf16 v[120:123], v[140:143], v[148:151], v[120:123]
	v_mfma_f32_16x16x32_bf16 v[108:111], v[132:135], v[156:159], v[108:111]
	v_mfma_f32_16x16x32_bf16 v[104:107], v[140:143], v[156:159], v[104:107]
	v_mfma_f32_16x16x32_bf16 v[92:95], v[132:135], v[188:191], v[92:95]
	v_mfma_f32_16x16x32_bf16 v[88:91], v[140:143], v[188:191], v[88:91]
	v_mfma_f32_16x16x32_bf16 v[76:79], v[132:135], v[196:199], v[76:79]
	v_mfma_f32_16x16x32_bf16 v[72:75], v[140:143], v[196:199], v[72:75]
	s_barrier
	s_add_i32 s76, 0, 0x14000
	v_add_u32_e32 v212, s76, v226
	s_add_i32 s73, s73, s7
	ds_read_b128 v[200:203], v212
	ds_read_b128 v[204:207], v212 offset:1024
	ds_read_b128 v[208:211], v212 offset:2048
	ds_read_b128 v[232:235], v212 offset:3072
	v_lshl_add_u64 v[212:213], s[44:45], 0, v[160:161]
	s_mov_b32 m0, s73
	v_lshl_add_u64 v[222:223], s[44:45], 0, v[174:175]
	global_load_lds_dwordx4 v[212:213], off
	s_add_i32 m0, s73, 0x2000
	s_nop 0
	global_load_lds_dwordx4 v[222:223], off
	s_barrier
	s_waitcnt lgkmcnt(0)
	s_waitcnt lgkmcnt(0)
	v_mfma_f32_16x16x32_bf16 v[116:119], v[200:203], v[144:147], v[116:119]
	v_mfma_f32_16x16x32_bf16 v[112:115], v[208:211], v[144:147], v[112:115]
	v_mfma_f32_16x16x32_bf16 v[100:103], v[200:203], v[152:155], v[100:103]
	v_mfma_f32_16x16x32_bf16 v[96:99], v[208:211], v[152:155], v[96:99]
	v_mfma_f32_16x16x32_bf16 v[84:87], v[200:203], v[184:187], v[84:87]
	v_mfma_f32_16x16x32_bf16 v[80:83], v[208:211], v[184:187], v[80:83]
	v_mfma_f32_16x16x32_bf16 v[68:71], v[200:203], v[192:195], v[68:71]
	v_mfma_f32_16x16x32_bf16 v[64:67], v[208:211], v[192:195], v[64:67]
	v_mfma_f32_16x16x32_bf16 v[116:119], v[204:207], v[148:151], v[116:119]
	v_mfma_f32_16x16x32_bf16 v[112:115], v[232:235], v[148:151], v[112:115]
	v_mfma_f32_16x16x32_bf16 v[100:103], v[204:207], v[156:159], v[100:103]
	v_mfma_f32_16x16x32_bf16 v[96:99], v[232:235], v[156:159], v[96:99]
	v_mfma_f32_16x16x32_bf16 v[84:87], v[204:207], v[188:191], v[84:87]
	v_mfma_f32_16x16x32_bf16 v[80:83], v[232:235], v[188:191], v[80:83]
	v_mfma_f32_16x16x32_bf16 v[68:71], v[204:207], v[196:199], v[68:71]
	v_mfma_f32_16x16x32_bf16 v[64:67], v[232:235], v[196:199], v[64:67]
	s_mov_b32 m0, s12
	v_lshl_add_u64 v[236:237], s[48:49], 0, v[178:179]
	s_barrier
	ds_read_b128 v[144:147], v228 offset:16384
	ds_read_b128 v[148:151], v228 offset:17408
	ds_read_b128 v[152:155], v228 offset:18432
	ds_read_b128 v[156:159], v228 offset:19456
	ds_read_b128 v[184:187], v228 offset:20480
	ds_read_b128 v[188:191], v228 offset:21504
	ds_read_b128 v[192:195], v228 offset:22528
	ds_read_b128 v[196:199], v228 offset:23552
	global_load_lds_dwordx4 v[236:237], off
	v_lshl_add_u64 v[238:239], s[48:49], 0, v[176:177]
	s_mov_b32 m0, s13
	s_nop 0
	global_load_lds_dwordx4 v[238:239], off
	s_barrier
	s_waitcnt lgkmcnt(0)
	s_waitcnt lgkmcnt(0)
	v_mfma_f32_16x16x32_bf16 v[60:63], v[128:131], v[144:147], v[60:63]
	v_mfma_f32_16x16x32_bf16 v[56:59], v[136:139], v[144:147], v[56:59]
	v_mfma_f32_16x16x32_bf16 v[44:47], v[128:131], v[152:155], v[44:47]
	v_mfma_f32_16x16x32_bf16 v[40:43], v[136:139], v[152:155], v[40:43]
	v_mfma_f32_16x16x32_bf16 v[28:31], v[128:131], v[184:187], v[28:31]
	v_mfma_f32_16x16x32_bf16 v[24:27], v[136:139], v[184:187], v[24:27]
	v_mfma_f32_16x16x32_bf16 v[12:15], v[128:131], v[192:195], v[12:15]
	v_mfma_f32_16x16x32_bf16 v[8:11], v[136:139], v[192:195], v[8:11]
	v_mfma_f32_16x16x32_bf16 v[60:63], v[132:135], v[148:151], v[60:63]
	v_mfma_f32_16x16x32_bf16 v[56:59], v[140:143], v[148:151], v[56:59]
	v_mfma_f32_16x16x32_bf16 v[44:47], v[132:135], v[156:159], v[44:47]
	v_mfma_f32_16x16x32_bf16 v[40:43], v[140:143], v[156:159], v[40:43]
	v_mfma_f32_16x16x32_bf16 v[28:31], v[132:135], v[188:191], v[28:31]
	v_mfma_f32_16x16x32_bf16 v[24:27], v[140:143], v[188:191], v[24:27]
	v_mfma_f32_16x16x32_bf16 v[12:15], v[132:135], v[196:199], v[12:15]
	v_mfma_f32_16x16x32_bf16 v[8:11], v[140:143], v[196:199], v[8:11]
	s_barrier
; #define PG8_STAGE(bufoff, gbase, voff) do { _Pragma("unroll") for (int _i = 0; _i < 2; ++_i) \
;     __builtin_amdgcn_global_load_lds((const unsigned*)((const char*)(gbase) + (voff)[_i]), (LAS unsigned*)(lds + (bufoff) + ldsw + _i * 8192), 16, 0, 0); } while (0)
; #define PG8_LDA(dst, b, h) do { _Pragma("unroll") for (int m = 0; m < 4; ++m) _Pragma("unroll") for (int k = 0; k < 2; ++k) dst[m][k] = *(const LAS bf16x8*)(lds + PG8_SA(b, h) + aoff + m * 2048 + k * 1024); } while (0)
; #define PG8_LDB(dst, b, h) do { _Pragma("unroll") for (int n = 0; n < 2; ++n) _Pragma("unroll") for (int k = 0; k < 2; ++k) dst[n][k] = *(const LAS bf16x8*)(lds + PG8_SB(b, h) + boff + n * 2048 + k * 1024); } while (0)
; #define PG8_MMA(ai, bj, At, Bt) do { __builtin_amdgcn_s_setprio(1); _Pragma("unroll") for (int m = 0; m < 4; ++m) _Pragma("unroll") for (int n = 0; n < 2; ++n) _Pragma("unroll") for (int k = 0; k < 2; ++k) \
;     acc[ai][bj][m][n] = __builtin_amdgcn_mfma_f32_16x16x32_bf16(Bt[n][k], At[m][k], acc[ai][bj][m][n], 0, 0, 0); __builtin_amdgcn_s_setprio(0); } while (0)
; #define PG8_WAIT_V(n) asm volatile("s_waitcnt vmcnt(" #n ")" ::: "memory")
; #define PG8_WAIT_L(n) asm volatile("s_waitcnt lgkmcnt(" #n ")" ::: "memory")
; #define PG8_BAR __builtin_amdgcn_s_barrier()
; #define PG8_SCHED __builtin_amdgcn_sched_barrier(0)
; template <class Epi, class Sched>
; __device__ __forceinline__ void gemm_phase(LAS unsigned char* lds, const Gemm g, const Sched& S, const Epi& E) {
;     ...
;       PG8_STAGE(PG8_SB(0, 1), b2 + hstep, voffB);
;       PG8_WAIT_V(6); PG8_BAR; PG8_MMA(1, 1, At, B1); PG8_BAR;
;       PG8_LDB(B0, 1, 0); PG8_SCHED; PG8_LDA(At, 1, 0); PG8_STAGE(PG8_SA(0, 1), a2 + hstep, voffA);
;       PG8_WAIT_L(8); PG8_BAR; PG8_WAIT_L(0); PG8_MMA(0, 0, At, B0); PG8_BAR; PG8_SCHED;
;       PG8_LDB(B1, 1, 1); PG8_STAGE(PG8_SB(1, 0), b3, voffB);
	s_add_u32 s74, s44, 0x40000
	s_addc_u32 s75, s45, 0
	s_add_i32 s73, s76, s7
	v_lshl_add_u64 v[128:129], s[74:75], 0, v[160:161]
	s_mov_b32 m0, s73
	s_nop 0
	global_load_lds_dwordx4 v[128:129], off
	v_lshl_add_u64 v[128:129], s[74:75], 0, v[174:175]
	s_add_i32 m0, s73, 0x2000
	s_nop 0
	global_load_lds_dwordx4 v[128:129], off
	s_waitcnt vmcnt(6)
	s_barrier
	v_mfma_f32_16x16x32_bf16 v[52:55], v[200:203], v[144:147], v[52:55]
	v_mfma_f32_16x16x32_bf16 v[48:51], v[208:211], v[144:147], v[48:51]
	v_mfma_f32_16x16x32_bf16 v[36:39], v[200:203], v[152:155], v[36:39]
	v_mfma_f32_16x16x32_bf16 v[32:35], v[208:211], v[152:155], v[32:35]
	v_mfma_f32_16x16x32_bf16 v[20:23], v[200:203], v[184:187], v[20:23]
	v_mfma_f32_16x16x32_bf16 v[16:19], v[208:211], v[184:187], v[16:19]
	v_mfma_f32_16x16x32_bf16 v[4:7], v[200:203], v[192:195], v[4:7]
	v_mfma_f32_16x16x32_bf16 v[0:3], v[208:211], v[192:195], v[0:3]
	v_mfma_f32_16x16x32_bf16 v[52:55], v[204:207], v[148:151], v[52:55]
	v_mfma_f32_16x16x32_bf16 v[48:51], v[232:235], v[148:151], v[48:51]
	v_mfma_f32_16x16x32_bf16 v[36:39], v[204:207], v[156:159], v[36:39]
	v_mfma_f32_16x16x32_bf16 v[32:35], v[232:235], v[156:159], v[32:35]
	v_mfma_f32_16x16x32_bf16 v[20:23], v[204:207], v[188:191], v[20:23]
	v_mfma_f32_16x16x32_bf16 v[16:19], v[232:235], v[188:191], v[16:19]
	v_mfma_f32_16x16x32_bf16 v[4:7], v[204:207], v[196:199], v[4:7]
	v_mfma_f32_16x16x32_bf16 v[0:3], v[232:235], v[196:199], v[0:3]
	s_add_i32 s73, 0, 0x18000
	v_add_u32_e32 v140, s73, v226
	s_barrier
	ds_read_b128 v[128:131], v140
	ds_read_b128 v[132:135], v140 offset:1024
	ds_read_b128 v[136:139], v140 offset:2048
	ds_read_b128 v[140:143], v140 offset:3072
	s_add_u32 s48, s48, 0x40000
	s_addc_u32 s49, s49, 0
	s_mov_b32 m0, s20
	v_lshl_add_u64 v[200:201], s[48:49], 0, v[178:179]
	ds_read_b128 v[144:147], v228 offset:32768
	ds_read_b128 v[148:151], v228 offset:33792
	ds_read_b128 v[152:155], v228 offset:34816
	ds_read_b128 v[156:159], v228 offset:35840
	ds_read_b128 v[184:187], v228 offset:36864
	ds_read_b128 v[188:191], v228 offset:37888
	ds_read_b128 v[192:195], v228 offset:38912
	ds_read_b128 v[196:199], v228 offset:39936
	global_load_lds_dwordx4 v[200:201], off
	v_lshl_add_u64 v[200:201], s[48:49], 0, v[176:177]
	s_mov_b32 m0, s51
	s_nop 0
	global_load_lds_dwordx4 v[200:201], off
	s_waitcnt lgkmcnt(8)
	s_barrier
	s_waitcnt lgkmcnt(0)
	s_waitcnt lgkmcnt(0)
	v_mfma_f32_16x16x32_bf16 v[124:127], v[128:131], v[144:147], v[124:127]
	v_mfma_f32_16x16x32_bf16 v[120:123], v[136:139], v[144:147], v[120:123]
	v_mfma_f32_16x16x32_bf16 v[108:111], v[128:131], v[152:155], v[108:111]
	v_mfma_f32_16x16x32_bf16 v[104:107], v[136:139], v[152:155], v[104:107]
	v_mfma_f32_16x16x32_bf16 v[92:95], v[128:131], v[184:187], v[92:95]
	v_mfma_f32_16x16x32_bf16 v[88:91], v[136:139], v[184:187], v[88:91]
	v_mfma_f32_16x16x32_bf16 v[76:79], v[128:131], v[192:195], v[76:79]
	v_mfma_f32_16x16x32_bf16 v[72:75], v[136:139], v[192:195], v[72:75]
	v_mfma_f32_16x16x32_bf16 v[124:127], v[132:135], v[148:151], v[124:127]
	v_mfma_f32_16x16x32_bf16 v[120:123], v[140:143], v[148:151], v[120:123]
	v_mfma_f32_16x16x32_bf16 v[108:111], v[132:135], v[156:159], v[108:111]
	v_mfma_f32_16x16x32_bf16 v[104:107], v[140:143], v[156:159], v[104:107]
	v_mfma_f32_16x16x32_bf16 v[92:95], v[132:135], v[188:191], v[92:95]
	v_mfma_f32_16x16x32_bf16 v[88:91], v[140:143], v[188:191], v[88:91]
	v_mfma_f32_16x16x32_bf16 v[76:79], v[132:135], v[196:199], v[76:79]
	v_mfma_f32_16x16x32_bf16 v[72:75], v[140:143], v[196:199], v[72:75]
	s_barrier
	s_add_i32 s48, 0, 0x1c000
	s_add_i32 s49, s73, s7
	v_add_u32_e32 v229, s48, v226
	v_lshl_add_u64 v[212:213], v[212:213], 0, s[80:81]
	s_mov_b32 m0, s49
	ds_read_b128 v[200:203], v229
	ds_read_b128 v[204:207], v229 offset:1024
	ds_read_b128 v[208:211], v229 offset:2048
	ds_read_b128 v[232:235], v229 offset:3072
	global_load_lds_dwordx4 v[212:213], off
	v_lshl_add_u64 v[212:213], v[222:223], 0, s[80:81]
	s_add_i32 m0, s49, 0x2000
	s_nop 0
	global_load_lds_dwordx4 v[212:213], off
	s_barrier
; #define PG8_STAGE(bufoff, gbase, voff) do { _Pragma("unroll") for (int _i = 0; _i < 2; ++_i) \
;     __builtin_amdgcn_global_load_lds((const unsigned*)((const char*)(gbase) + (voff)[_i]), (LAS unsigned*)(lds + (bufoff) + ldsw + _i * 8192), 16, 0, 0); } while (0)
; #define PG8_LDA(dst, b, h) do { _Pragma("unroll") for (int m = 0; m < 4; ++m) _Pragma("unroll") for (int k = 0; k < 2; ++k) dst[m][k] = *(const LAS bf16x8*)(lds + PG8_SA(b, h) + aoff + m * 2048 + k * 1024); } while (0)
; #define PG8_MMA(ai, bj, At, Bt) do { __builtin_amdgcn_s_setprio(1); _Pragma("unroll") for (int m = 0; m < 4; ++m) _Pragma("unroll") for (int n = 0; n < 2; ++n) _Pragma("unroll") for (int k = 0; k < 2; ++k) \
;     acc[ai][bj][m][n] = __builtin_amdgcn_mfma_f32_16x16x32_bf16(Bt[n][k], At[m][k], acc[ai][bj][m][n], 0, 0, 0); __builtin_amdgcn_s_setprio(0); } while (0)
; #define PG8_WAIT_V(n) asm volatile("s_waitcnt vmcnt(" #n ")" ::: "memory")
; #define PG8_WAIT_L(n) asm volatile("s_waitcnt lgkmcnt(" #n ")" ::: "memory")
; #define PG8_BAR __builtin_amdgcn_s_barrier()
; #define PG8_SCHED __builtin_amdgcn_sched_barrier(0)
; template <class Epi, class Sched>
; __device__ __forceinline__ void gemm_phase(LAS unsigned char* lds, const Gemm g, const Sched& S, const Epi& E) {
;     ...
;       PG8_BAR; PG8_WAIT_L(0); PG8_MMA(0, 1, At, B1); PG8_BAR;
;       PG8_LDA(At, 1, 1); PG8_STAGE(PG8_SA(1, 0), a3, voffA);
;       PG8_BAR; PG8_WAIT_L(0); PG8_MMA(1, 0, At, B0); PG8_BAR; PG8_SCHED;
;       PG8_STAGE(PG8_SB(1, 1), b3 + hstep, voffB);
;       PG8_WAIT_V(6); PG8_BAR; PG8_MMA(1, 1, At, B1); PG8_BAR;
;     }
	s_waitcnt lgkmcnt(0)
	s_waitcnt lgkmcnt(0)
	v_mfma_f32_16x16x32_bf16 v[116:119], v[200:203], v[144:147], v[116:119]
	v_mfma_f32_16x16x32_bf16 v[112:115], v[208:211], v[144:147], v[112:115]
	v_mfma_f32_16x16x32_bf16 v[100:103], v[200:203], v[152:155], v[100:103]
	v_mfma_f32_16x16x32_bf16 v[96:99], v[208:211], v[152:155], v[96:99]
	v_mfma_f32_16x16x32_bf16 v[84:87], v[200:203], v[184:187], v[84:87]
	v_mfma_f32_16x16x32_bf16 v[80:83], v[208:211], v[184:187], v[80:83]
	v_mfma_f32_16x16x32_bf16 v[68:71], v[200:203], v[192:195], v[68:71]
	v_mfma_f32_16x16x32_bf16 v[64:67], v[208:211], v[192:195], v[64:67]
	v_mfma_f32_16x16x32_bf16 v[116:119], v[204:207], v[148:151], v[116:119]
	v_mfma_f32_16x16x32_bf16 v[112:115], v[232:235], v[148:151], v[112:115]
	v_mfma_f32_16x16x32_bf16 v[100:103], v[204:207], v[156:159], v[100:103]
	v_mfma_f32_16x16x32_bf16 v[96:99], v[232:235], v[156:159], v[96:99]
	v_mfma_f32_16x16x32_bf16 v[84:87], v[204:207], v[188:191], v[84:87]
	v_mfma_f32_16x16x32_bf16 v[80:83], v[232:235], v[188:191], v[80:83]
	v_mfma_f32_16x16x32_bf16 v[68:71], v[204:207], v[196:199], v[68:71]
	v_mfma_f32_16x16x32_bf16 v[64:67], v[232:235], v[196:199], v[64:67]
	s_mov_b32 m0, s62
	v_lshl_add_u64 v[212:213], v[236:237], 0, s[80:81]
	s_barrier
	ds_read_b128 v[144:147], v228 offset:49152
	ds_read_b128 v[148:151], v228 offset:50176
	ds_read_b128 v[152:155], v228 offset:51200
	ds_read_b128 v[156:159], v228 offset:52224
	ds_read_b128 v[184:187], v228 offset:53248
	ds_read_b128 v[188:191], v228 offset:54272
	ds_read_b128 v[192:195], v228 offset:55296
	ds_read_b128 v[196:199], v228 offset:56320
	global_load_lds_dwordx4 v[212:213], off
	v_lshl_add_u64 v[212:213], v[238:239], 0, s[80:81]
	s_mov_b32 m0, s63
	s_nop 0
	global_load_lds_dwordx4 v[212:213], off
	s_barrier
	s_waitcnt lgkmcnt(0)
	s_waitcnt lgkmcnt(0)
	v_mfma_f32_16x16x32_bf16 v[60:63], v[128:131], v[144:147], v[60:63]
	v_mfma_f32_16x16x32_bf16 v[56:59], v[136:139], v[144:147], v[56:59]
	v_mfma_f32_16x16x32_bf16 v[44:47], v[128:131], v[152:155], v[44:47]
	v_mfma_f32_16x16x32_bf16 v[40:43], v[136:139], v[152:155], v[40:43]
	v_mfma_f32_16x16x32_bf16 v[28:31], v[128:131], v[184:187], v[28:31]
	v_mfma_f32_16x16x32_bf16 v[24:27], v[136:139], v[184:187], v[24:27]
	v_mfma_f32_16x16x32_bf16 v[12:15], v[128:131], v[192:195], v[12:15]
	v_mfma_f32_16x16x32_bf16 v[8:11], v[136:139], v[192:195], v[8:11]
	v_mfma_f32_16x16x32_bf16 v[60:63], v[132:135], v[148:151], v[60:63]
	v_mfma_f32_16x16x32_bf16 v[56:59], v[140:143], v[148:151], v[56:59]
	v_mfma_f32_16x16x32_bf16 v[44:47], v[132:135], v[156:159], v[44:47]
	v_mfma_f32_16x16x32_bf16 v[40:43], v[140:143], v[156:159], v[40:43]
	v_mfma_f32_16x16x32_bf16 v[28:31], v[132:135], v[188:191], v[28:31]
	v_mfma_f32_16x16x32_bf16 v[24:27], v[140:143], v[188:191], v[24:27]
	v_mfma_f32_16x16x32_bf16 v[12:15], v[132:135], v[196:199], v[12:15]
	v_mfma_f32_16x16x32_bf16 v[8:11], v[140:143], v[196:199], v[8:11]
	s_barrier
	s_add_u32 s44, s44, 0x40080
	s_addc_u32 s45, s45, 0
	s_add_i32 s48, s48, s7
	v_lshl_add_u64 v[128:129], s[44:45], 0, v[160:161]
	s_mov_b32 m0, s48
	s_nop 0
	global_load_lds_dwordx4 v[128:129], off
	v_lshl_add_u64 v[128:129], s[44:45], 0, v[174:175]
	s_add_i32 m0, s48, 0x2000
	s_nop 0
	global_load_lds_dwordx4 v[128:129], off
	s_waitcnt vmcnt(6)
	s_barrier
	v_mfma_f32_16x16x32_bf16 v[52:55], v[200:203], v[144:147], v[52:55]
	v_mfma_f32_16x16x32_bf16 v[48:51], v[208:211], v[144:147], v[48:51]
	v_mfma_f32_16x16x32_bf16 v[36:39], v[200:203], v[152:155], v[36:39]
	v_mfma_f32_16x16x32_bf16 v[32:35], v[208:211], v[152:155], v[32:35]
	v_mfma_f32_16x16x32_bf16 v[20:23], v[200:203], v[184:187], v[20:23]
	v_mfma_f32_16x16x32_bf16 v[16:19], v[208:211], v[184:187], v[16:19]
	v_mfma_f32_16x16x32_bf16 v[4:7], v[200:203], v[192:195], v[4:7]
	v_mfma_f32_16x16x32_bf16 v[0:3], v[208:211], v[192:195], v[0:3]
	v_mfma_f32_16x16x32_bf16 v[52:55], v[204:207], v[148:151], v[52:55]
	v_mfma_f32_16x16x32_bf16 v[48:51], v[232:235], v[148:151], v[48:51]
	v_mfma_f32_16x16x32_bf16 v[36:39], v[204:207], v[156:159], v[36:39]
	v_mfma_f32_16x16x32_bf16 v[32:35], v[232:235], v[156:159], v[32:35]
	v_mfma_f32_16x16x32_bf16 v[20:23], v[204:207], v[188:191], v[20:23]
	v_mfma_f32_16x16x32_bf16 v[16:19], v[232:235], v[188:191], v[16:19]
	v_mfma_f32_16x16x32_bf16 v[4:7], v[204:207], v[196:199], v[4:7]
	v_mfma_f32_16x16x32_bf16 v[0:3], v[232:235], v[196:199], v[0:3]
	s_add_i32 s72, s72, 2
	s_add_u32 s34, s34, 0x100
	s_addc_u32 s35, s35, 0
	s_add_u32 s71, s71, 0x100
	s_addc_u32 s52, s52, 0
	s_cmp_gt_u32 s72, 13
	s_barrier
	s_cbranch_scc0 .LBB0_794
	s_cmp_lt_u32 s101, 0x100
	s_cbranch_scc0 .Lxa_5
	s_barrier

; #define PG8_STAGE(bufoff, gbase, voff) do { _Pragma("unroll") for (int _i = 0; _i < 2; ++_i) \
;     __builtin_amdgcn_global_load_lds((const unsigned*)((const char*)(gbase) + (voff)[_i]), (LAS unsigned*)(lds + (bufoff) + ldsw + _i * 8192), 16, 0, 0); } while (0)
; #define PG8_LDA(dst, b, h) do { _Pragma("unroll") for (int m = 0; m < 4; ++m) _Pragma("unroll") for (int k = 0; k < 2; ++k) dst[m][k] = *(const LAS bf16x8*)(lds + PG8_SA(b, h) + aoff + m * 2048 + k * 1024); } while (0)
; #define PG8_LDB(dst, b, h) do { _Pragma("unroll") for (int n = 0; n < 2; ++n) _Pragma("unroll") for (int k = 0; k < 2; ++k) dst[n][k] = *(const LAS bf16x8*)(lds + PG8_SB(b, h) + boff + n * 2048 + k * 1024); } while (0)
; #define PG8_MMA(ai, bj, At, Bt) do { __builtin_amdgcn_s_setprio(1); _Pragma("unroll") for (int m = 0; m < 4; ++m) _Pragma("unroll") for (int n = 0; n < 2; ++n) _Pragma("unroll") for (int k = 0; k < 2; ++k) \
;     acc[ai][bj][m][n] = __builtin_amdgcn_mfma_f32_16x16x32_bf16(Bt[n][k], At[m][k], acc[ai][bj][m][n], 0, 0, 0); __builtin_amdgcn_s_setprio(0); } while (0)
; #define PG8_WAIT_L(n) asm volatile("s_waitcnt lgkmcnt(" #n ")" ::: "memory")
; #define PG8_BAR __builtin_amdgcn_s_barrier()
; #define PG8_SCHED __builtin_amdgcn_sched_barrier(0)
; template <class Epi, class Sched>
; __device__ __forceinline__ void gemm_phase(LAS unsigned char* lds, const Gemm g, const Sched& S, const Epi& E) {
;     ...
;     for (int t = 0; t < nt; t += 2) {
;       const bool last = (t == nt - 2);
;       const char* a1 = cA + (size_t)(t + 1) * kstep;
;       const char* a2 = last ? nA : cA + (size_t)(t + 2) * kstep; const char* b2 = last ? nB : cB + (size_t)(t + 2) * kstep;
;       const char* a3 = a2 + kstep; const char* b3 = b2 + kstep;
;       if (last && has_next) S.a_ready(nxt);
;       PG8_LDB(B0, 0, 0); PG8_SCHED; PG8_LDA(At, 0, 0); PG8_STAGE(PG8_SA(1, 1), a1 + hstep, voffA);
;       PG8_WAIT_L(8); PG8_BAR; PG8_WAIT_L(0); PG8_MMA(0, 0, At, B0); PG8_BAR; PG8_SCHED;
;       PG8_LDB(B1, 0, 1); PG8_STAGE(PG8_SB(0, 0), b2, voffB);
;       PG8_BAR; PG8_WAIT_L(0); PG8_MMA(0, 1, At, B1); PG8_BAR;
;       PG8_LDA(At, 0, 1); PG8_STAGE(PG8_SA(0, 0), a2, voffA);
;       PG8_BAR; PG8_WAIT_L(0); PG8_MMA(1, 0, At, B0); PG8_BAR; PG8_SCHED;
.Lxs_e6:
.LBB0_863:
	s_add_u32 s48, s34, 0xfffc0080
	s_addc_u32 s49, s35, -1
	s_add_i32 s74, 0, 0x10000
	v_add_u32_e32 v140, s74, v202
	ds_read_b128 v[128:131], v140
	ds_read_b128 v[132:135], v140 offset:1024
	ds_read_b128 v[136:139], v140 offset:2048
	ds_read_b128 v[140:143], v140 offset:3072
	s_cmp_eq_u32 s73, 12
	s_cselect_b32 s49, s37, s49
	s_cselect_b32 s48, s68, s48
	s_cselect_b32 vcc_hi, s23, s72
	s_cselect_b32 vcc_lo, s69, s52
	v_lshl_add_u64 v[208:209], s[34:35], 0, v[182:183]
	s_add_i32 m0, s51, 0xc000
	ds_read_b128 v[144:147], v203
	ds_read_b128 v[148:151], v203 offset:1024
	ds_read_b128 v[152:155], v203 offset:2048
	ds_read_b128 v[186:189], v203 offset:3072
	ds_read_b128 v[190:193], v203 offset:4096
	ds_read_b128 v[194:197], v203 offset:5120
	ds_read_b128 v[198:201], v203 offset:6144
	ds_read_b128 v[204:207], v203 offset:7168
	global_load_lds_dwordx4 v[208:209], off
	v_lshl_add_u64 v[208:209], s[34:35], 0, v[184:185]
	s_add_i32 m0, s51, 0xe000
	s_nop 0
	global_load_lds_dwordx4 v[208:209], off
	s_waitcnt lgkmcnt(8)
	s_barrier
	s_waitcnt lgkmcnt(0)
	s_waitcnt lgkmcnt(0)
	v_mfma_f32_16x16x32_bf16 v[124:127], v[128:131], v[144:147], v[124:127]
	v_mfma_f32_16x16x32_bf16 v[120:123], v[136:139], v[144:147], v[120:123]
	v_mfma_f32_16x16x32_bf16 v[108:111], v[128:131], v[152:155], v[108:111]
	v_mfma_f32_16x16x32_bf16 v[104:107], v[136:139], v[152:155], v[104:107]
	v_mfma_f32_16x16x32_bf16 v[92:95], v[128:131], v[190:193], v[92:95]
	v_mfma_f32_16x16x32_bf16 v[88:91], v[136:139], v[190:193], v[88:91]
	v_mfma_f32_16x16x32_bf16 v[76:79], v[128:131], v[198:201], v[76:79]
	v_mfma_f32_16x16x32_bf16 v[72:75], v[136:139], v[198:201], v[72:75]
	v_mfma_f32_16x16x32_bf16 v[124:127], v[132:135], v[148:151], v[124:127]
	v_mfma_f32_16x16x32_bf16 v[120:123], v[140:143], v[148:151], v[120:123]
	v_mfma_f32_16x16x32_bf16 v[108:111], v[132:135], v[186:189], v[108:111]
	v_mfma_f32_16x16x32_bf16 v[104:107], v[140:143], v[186:189], v[104:107]
	v_mfma_f32_16x16x32_bf16 v[92:95], v[132:135], v[194:197], v[92:95]
	v_mfma_f32_16x16x32_bf16 v[88:91], v[140:143], v[194:197], v[88:91]
	v_mfma_f32_16x16x32_bf16 v[76:79], v[132:135], v[204:207], v[76:79]
	v_mfma_f32_16x16x32_bf16 v[72:75], v[140:143], v[204:207], v[72:75]
	s_barrier
	s_add_i32 s76, 0, 0x14000
	s_add_i32 s74, s74, s7
	v_add_u32_e32 v160, s76, v202
	v_lshl_add_u64 v[212:213], vcc, 0, v[174:175]
	s_mov_b32 m0, s74
	ds_read_b128 v[208:211], v160
	ds_read_b128 v[226:229], v160 offset:1024
	ds_read_b128 v[232:235], v160 offset:2048
	ds_read_b128 v[236:239], v160 offset:3072
	global_load_lds_dwordx4 v[212:213], off
	v_lshl_add_u64 v[222:223], vcc, 0, v[156:157]
	s_add_i32 m0, s74, 0x2000
	s_nop 0
	global_load_lds_dwordx4 v[222:223], off
	s_barrier
	s_waitcnt lgkmcnt(0)
	s_waitcnt lgkmcnt(0)
	v_mfma_f32_16x16x32_bf16 v[116:119], v[208:211], v[144:147], v[116:119]
	v_mfma_f32_16x16x32_bf16 v[112:115], v[232:235], v[144:147], v[112:115]
	v_mfma_f32_16x16x32_bf16 v[100:103], v[208:211], v[152:155], v[100:103]
	v_mfma_f32_16x16x32_bf16 v[96:99], v[232:235], v[152:155], v[96:99]
	v_mfma_f32_16x16x32_bf16 v[84:87], v[208:211], v[190:193], v[84:87]
	v_mfma_f32_16x16x32_bf16 v[80:83], v[232:235], v[190:193], v[80:83]
	v_mfma_f32_16x16x32_bf16 v[68:71], v[208:211], v[198:201], v[68:71]
	v_mfma_f32_16x16x32_bf16 v[64:67], v[232:235], v[198:201], v[64:67]
	v_mfma_f32_16x16x32_bf16 v[116:119], v[226:229], v[148:151], v[116:119]
	v_mfma_f32_16x16x32_bf16 v[112:115], v[236:239], v[148:151], v[112:115]
	v_mfma_f32_16x16x32_bf16 v[100:103], v[226:229], v[186:189], v[100:103]
	v_mfma_f32_16x16x32_bf16 v[96:99], v[236:239], v[186:189], v[96:99]
	v_mfma_f32_16x16x32_bf16 v[84:87], v[226:229], v[194:197], v[84:87]
	v_mfma_f32_16x16x32_bf16 v[80:83], v[236:239], v[194:197], v[80:83]
	v_mfma_f32_16x16x32_bf16 v[68:71], v[226:229], v[204:207], v[68:71]
	v_mfma_f32_16x16x32_bf16 v[64:67], v[236:239], v[204:207], v[64:67]
	s_mov_b32 m0, s51
	v_lshl_add_u64 v[240:241], s[48:49], 0, v[176:177]
	s_barrier
	ds_read_b128 v[144:147], v203 offset:16384
	ds_read_b128 v[148:151], v203 offset:17408
	ds_read_b128 v[152:155], v203 offset:18432
	ds_read_b128 v[186:189], v203 offset:19456
	ds_read_b128 v[190:193], v203 offset:20480
	ds_read_b128 v[194:197], v203 offset:21504
	ds_read_b128 v[198:201], v203 offset:22528
	ds_read_b128 v[204:207], v203 offset:23552
	global_load_lds_dwordx4 v[240:241], off
	v_lshl_add_u64 v[242:243], s[48:49], 0, v[158:159]
	s_mov_b32 m0, s62
	s_nop 0
	global_load_lds_dwordx4 v[242:243], off
	s_barrier
	s_waitcnt lgkmcnt(0)
	s_waitcnt lgkmcnt(0)
	v_mfma_f32_16x16x32_bf16 v[60:63], v[128:131], v[144:147], v[60:63]
	v_mfma_f32_16x16x32_bf16 v[56:59], v[136:139], v[144:147], v[56:59]
	v_mfma_f32_16x16x32_bf16 v[44:47], v[128:131], v[152:155], v[44:47]
	v_mfma_f32_16x16x32_bf16 v[40:43], v[136:139], v[152:155], v[40:43]
	v_mfma_f32_16x16x32_bf16 v[28:31], v[128:131], v[190:193], v[28:31]
	v_mfma_f32_16x16x32_bf16 v[24:27], v[136:139], v[190:193], v[24:27]
	v_mfma_f32_16x16x32_bf16 v[12:15], v[128:131], v[198:201], v[12:15]
	v_mfma_f32_16x16x32_bf16 v[8:11], v[136:139], v[198:201], v[8:11]
	v_mfma_f32_16x16x32_bf16 v[60:63], v[132:135], v[148:151], v[60:63]
	v_mfma_f32_16x16x32_bf16 v[56:59], v[140:143], v[148:151], v[56:59]
	v_mfma_f32_16x16x32_bf16 v[44:47], v[132:135], v[186:189], v[44:47]
	v_mfma_f32_16x16x32_bf16 v[40:43], v[140:143], v[186:189], v[40:43]
	v_mfma_f32_16x16x32_bf16 v[28:31], v[132:135], v[194:197], v[28:31]
	v_mfma_f32_16x16x32_bf16 v[24:27], v[140:143], v[194:197], v[24:27]
	v_mfma_f32_16x16x32_bf16 v[12:15], v[132:135], v[204:207], v[12:15]
	v_mfma_f32_16x16x32_bf16 v[8:11], v[140:143], v[204:207], v[8:11]
	s_barrier
; #define PG8_STAGE(bufoff, gbase, voff) do { _Pragma("unroll") for (int _i = 0; _i < 2; ++_i) \
;     __builtin_amdgcn_global_load_lds((const unsigned*)((const char*)(gbase) + (voff)[_i]), (LAS unsigned*)(lds + (bufoff) + ldsw + _i * 8192), 16, 0, 0); } while (0)
; #define PG8_LDA(dst, b, h) do { _Pragma("unroll") for (int m = 0; m < 4; ++m) _Pragma("unroll") for (int k = 0; k < 2; ++k) dst[m][k] = *(const LAS bf16x8*)(lds + PG8_SA(b, h) + aoff + m * 2048 + k * 1024); } while (0)
; #define PG8_LDB(dst, b, h) do { _Pragma("unroll") for (int n = 0; n < 2; ++n) _Pragma("unroll") for (int k = 0; k < 2; ++k) dst[n][k] = *(const LAS bf16x8*)(lds + PG8_SB(b, h) + boff + n * 2048 + k * 1024); } while (0)
; #define PG8_MMA(ai, bj, At, Bt) do { __builtin_amdgcn_s_setprio(1); _Pragma("unroll") for (int m = 0; m < 4; ++m) _Pragma("unroll") for (int n = 0; n < 2; ++n) _Pragma("unroll") for (int k = 0; k < 2; ++k) \
;     acc[ai][bj][m][n] = __builtin_amdgcn_mfma_f32_16x16x32_bf16(Bt[n][k], At[m][k], acc[ai][bj][m][n], 0, 0, 0); __builtin_amdgcn_s_setprio(0); } while (0)
; #define PG8_WAIT_V(n) asm volatile("s_waitcnt vmcnt(" #n ")" ::: "memory")
; #define PG8_WAIT_L(n) asm volatile("s_waitcnt lgkmcnt(" #n ")" ::: "memory")
; #define PG8_BAR __builtin_amdgcn_s_barrier()
; #define PG8_SCHED __builtin_amdgcn_sched_barrier(0)
; template <class Epi, class Sched>
; __device__ __forceinline__ void gemm_phase(LAS unsigned char* lds, const Gemm g, const Sched& S, const Epi& E) {
;     ...
;       PG8_STAGE(PG8_SB(0, 1), b2 + hstep, voffB);
;       PG8_WAIT_V(6); PG8_BAR; PG8_MMA(1, 1, At, B1); PG8_BAR;
;       PG8_LDB(B0, 1, 0); PG8_SCHED; PG8_LDA(At, 1, 0); PG8_STAGE(PG8_SA(0, 1), a2 + hstep, voffA);
;       PG8_WAIT_L(8); PG8_BAR; PG8_WAIT_L(0); PG8_MMA(0, 0, At, B0); PG8_BAR; PG8_SCHED;
;       PG8_LDB(B1, 1, 1); PG8_STAGE(PG8_SB(1, 0), b3, voffB);
	s_add_u32 s74, vcc_lo, 0x40000
	s_addc_u32 s75, vcc_hi, 0
	s_add_i32 s76, s76, s7
	v_lshl_add_u64 v[128:129], s[74:75], 0, v[174:175]
	s_mov_b32 m0, s76
	s_nop 0
	global_load_lds_dwordx4 v[128:129], off
	v_lshl_add_u64 v[128:129], s[74:75], 0, v[156:157]
	s_add_i32 m0, s76, 0x2000
	s_nop 0
	global_load_lds_dwordx4 v[128:129], off
	s_waitcnt vmcnt(6)
	s_barrier
	v_mfma_f32_16x16x32_bf16 v[52:55], v[208:211], v[144:147], v[52:55]
	v_mfma_f32_16x16x32_bf16 v[48:51], v[232:235], v[144:147], v[48:51]
	v_mfma_f32_16x16x32_bf16 v[36:39], v[208:211], v[152:155], v[36:39]
	v_mfma_f32_16x16x32_bf16 v[32:35], v[232:235], v[152:155], v[32:35]
	v_mfma_f32_16x16x32_bf16 v[20:23], v[208:211], v[190:193], v[20:23]
	v_mfma_f32_16x16x32_bf16 v[16:19], v[232:235], v[190:193], v[16:19]
	v_mfma_f32_16x16x32_bf16 v[4:7], v[208:211], v[198:201], v[4:7]
	v_mfma_f32_16x16x32_bf16 v[0:3], v[232:235], v[198:201], v[0:3]
	v_mfma_f32_16x16x32_bf16 v[52:55], v[226:229], v[148:151], v[52:55]
	v_mfma_f32_16x16x32_bf16 v[48:51], v[236:239], v[148:151], v[48:51]
	v_mfma_f32_16x16x32_bf16 v[36:39], v[226:229], v[186:189], v[36:39]
	v_mfma_f32_16x16x32_bf16 v[32:35], v[236:239], v[186:189], v[32:35]
	v_mfma_f32_16x16x32_bf16 v[20:23], v[226:229], v[194:197], v[20:23]
	v_mfma_f32_16x16x32_bf16 v[16:19], v[236:239], v[194:197], v[16:19]
	v_mfma_f32_16x16x32_bf16 v[4:7], v[226:229], v[204:207], v[4:7]
	v_mfma_f32_16x16x32_bf16 v[0:3], v[236:239], v[204:207], v[0:3]
	s_add_i32 s74, 0, 0x18000
	v_add_u32_e32 v140, s74, v202
	s_barrier
	ds_read_b128 v[128:131], v140
	ds_read_b128 v[132:135], v140 offset:1024
	ds_read_b128 v[136:139], v140 offset:2048
	ds_read_b128 v[140:143], v140 offset:3072
	s_add_u32 s48, s48, 0x40000
	s_addc_u32 s49, s49, 0
	s_mov_b32 m0, s63
	v_lshl_add_u64 v[208:209], s[48:49], 0, v[176:177]
	ds_read_b128 v[144:147], v203 offset:32768
	ds_read_b128 v[148:151], v203 offset:33792
	ds_read_b128 v[152:155], v203 offset:34816
	ds_read_b128 v[186:189], v203 offset:35840
	ds_read_b128 v[190:193], v203 offset:36864
	ds_read_b128 v[194:197], v203 offset:37888
	ds_read_b128 v[198:201], v203 offset:38912
	ds_read_b128 v[204:207], v203 offset:39936
	global_load_lds_dwordx4 v[208:209], off
	v_lshl_add_u64 v[208:209], s[48:49], 0, v[158:159]
	s_mov_b32 m0, s64
	s_nop 0
	global_load_lds_dwordx4 v[208:209], off
	s_waitcnt lgkmcnt(8)
	s_barrier
	s_waitcnt lgkmcnt(0)
	s_waitcnt lgkmcnt(0)
	v_mfma_f32_16x16x32_bf16 v[124:127], v[128:131], v[144:147], v[124:127]
	v_mfma_f32_16x16x32_bf16 v[120:123], v[136:139], v[144:147], v[120:123]
	v_mfma_f32_16x16x32_bf16 v[108:111], v[128:131], v[152:155], v[108:111]
	v_mfma_f32_16x16x32_bf16 v[104:107], v[136:139], v[152:155], v[104:107]
	v_mfma_f32_16x16x32_bf16 v[92:95], v[128:131], v[190:193], v[92:95]
	v_mfma_f32_16x16x32_bf16 v[88:91], v[136:139], v[190:193], v[88:91]
	v_mfma_f32_16x16x32_bf16 v[76:79], v[128:131], v[198:201], v[76:79]
	v_mfma_f32_16x16x32_bf16 v[72:75], v[136:139], v[198:201], v[72:75]
	v_mfma_f32_16x16x32_bf16 v[124:127], v[132:135], v[148:151], v[124:127]
	v_mfma_f32_16x16x32_bf16 v[120:123], v[140:143], v[148:151], v[120:123]
	v_mfma_f32_16x16x32_bf16 v[108:111], v[132:135], v[186:189], v[108:111]
	v_mfma_f32_16x16x32_bf16 v[104:107], v[140:143], v[186:189], v[104:107]
	v_mfma_f32_16x16x32_bf16 v[92:95], v[132:135], v[194:197], v[92:95]
	v_mfma_f32_16x16x32_bf16 v[88:91], v[140:143], v[194:197], v[88:91]
	v_mfma_f32_16x16x32_bf16 v[76:79], v[132:135], v[204:207], v[76:79]
	v_mfma_f32_16x16x32_bf16 v[72:75], v[140:143], v[204:207], v[72:75]
	s_barrier
	s_add_i32 s75, 0, 0x1c000
	s_add_i32 s48, s74, s7
	v_add_u32_e32 v160, s75, v202
	v_lshl_add_u64 v[212:213], v[212:213], 0, s[80:81]
	s_mov_b32 m0, s48
	ds_read_b128 v[208:211], v160
	ds_read_b128 v[226:229], v160 offset:1024
	ds_read_b128 v[232:235], v160 offset:2048
	ds_read_b128 v[236:239], v160 offset:3072
	global_load_lds_dwordx4 v[212:213], off
	v_lshl_add_u64 v[212:213], v[222:223], 0, s[80:81]
	s_add_i32 m0, s48, 0x2000
	s_nop 0
	global_load_lds_dwordx4 v[212:213], off
	s_barrier
; #define PG8_STAGE(bufoff, gbase, voff) do { _Pragma("unroll") for (int _i = 0; _i < 2; ++_i) \
;     __builtin_amdgcn_global_load_lds((const unsigned*)((const char*)(gbase) + (voff)[_i]), (LAS unsigned*)(lds + (bufoff) + ldsw + _i * 8192), 16, 0, 0); } while (0)
; #define PG8_LDA(dst, b, h) do { _Pragma("unroll") for (int m = 0; m < 4; ++m) _Pragma("unroll") for (int k = 0; k < 2; ++k) dst[m][k] = *(const LAS bf16x8*)(lds + PG8_SA(b, h) + aoff + m * 2048 + k * 1024); } while (0)
; #define PG8_MMA(ai, bj, At, Bt) do { __builtin_amdgcn_s_setprio(1); _Pragma("unroll") for (int m = 0; m < 4; ++m) _Pragma("unroll") for (int n = 0; n < 2; ++n) _Pragma("unroll") for (int k = 0; k < 2; ++k) \
;     acc[ai][bj][m][n] = __builtin_amdgcn_mfma_f32_16x16x32_bf16(Bt[n][k], At[m][k], acc[ai][bj][m][n], 0, 0, 0); __builtin_amdgcn_s_setprio(0); } while (0)
; #define PG8_WAIT_V(n) asm volatile("s_waitcnt vmcnt(" #n ")" ::: "memory")
; #define PG8_WAIT_L(n) asm volatile("s_waitcnt lgkmcnt(" #n ")" ::: "memory")
; #define PG8_BAR __builtin_amdgcn_s_barrier()
; #define PG8_SCHED __builtin_amdgcn_sched_barrier(0)
; template <class Epi, class Sched>
; __device__ __forceinline__ void gemm_phase(LAS unsigned char* lds, const Gemm g, const Sched& S, const Epi& E) {
;     ...
;       PG8_BAR; PG8_WAIT_L(0); PG8_MMA(0, 1, At, B1); PG8_BAR;
;       PG8_LDA(At, 1, 1); PG8_STAGE(PG8_SA(1, 0), a3, voffA);
;       PG8_BAR; PG8_WAIT_L(0); PG8_MMA(1, 0, At, B0); PG8_BAR; PG8_SCHED;
;       PG8_STAGE(PG8_SB(1, 1), b3 + hstep, voffB);
;       PG8_WAIT_V(6); PG8_BAR; PG8_MMA(1, 1, At, B1); PG8_BAR;
;     }
	s_waitcnt lgkmcnt(0)
	s_waitcnt lgkmcnt(0)
	v_mfma_f32_16x16x32_bf16 v[116:119], v[208:211], v[144:147], v[116:119]
	v_mfma_f32_16x16x32_bf16 v[112:115], v[232:235], v[144:147], v[112:115]
	v_mfma_f32_16x16x32_bf16 v[100:103], v[208:211], v[152:155], v[100:103]
	v_mfma_f32_16x16x32_bf16 v[96:99], v[232:235], v[152:155], v[96:99]
	v_mfma_f32_16x16x32_bf16 v[84:87], v[208:211], v[190:193], v[84:87]
	v_mfma_f32_16x16x32_bf16 v[80:83], v[232:235], v[190:193], v[80:83]
	v_mfma_f32_16x16x32_bf16 v[68:71], v[208:211], v[198:201], v[68:71]
	v_mfma_f32_16x16x32_bf16 v[64:67], v[232:235], v[198:201], v[64:67]
	v_mfma_f32_16x16x32_bf16 v[116:119], v[226:229], v[148:151], v[116:119]
	v_mfma_f32_16x16x32_bf16 v[112:115], v[236:239], v[148:151], v[112:115]
	v_mfma_f32_16x16x32_bf16 v[100:103], v[226:229], v[186:189], v[100:103]
	v_mfma_f32_16x16x32_bf16 v[96:99], v[236:239], v[186:189], v[96:99]
	v_mfma_f32_16x16x32_bf16 v[84:87], v[226:229], v[194:197], v[84:87]
	v_mfma_f32_16x16x32_bf16 v[80:83], v[236:239], v[194:197], v[80:83]
	v_mfma_f32_16x16x32_bf16 v[68:71], v[226:229], v[204:207], v[68:71]
	v_mfma_f32_16x16x32_bf16 v[64:67], v[236:239], v[204:207], v[64:67]
	s_mov_b32 m0, s65
	v_lshl_add_u64 v[212:213], v[240:241], 0, s[80:81]
	s_barrier
	ds_read_b128 v[144:147], v203 offset:49152
	ds_read_b128 v[148:151], v203 offset:50176
	ds_read_b128 v[152:155], v203 offset:51200
	ds_read_b128 v[186:189], v203 offset:52224
	ds_read_b128 v[190:193], v203 offset:53248
	ds_read_b128 v[194:197], v203 offset:54272
	ds_read_b128 v[198:201], v203 offset:55296
	ds_read_b128 v[204:207], v203 offset:56320
	global_load_lds_dwordx4 v[212:213], off
	v_lshl_add_u64 v[212:213], v[242:243], 0, s[80:81]
	s_mov_b32 m0, s70
	s_nop 0
	global_load_lds_dwordx4 v[212:213], off
	s_barrier
	s_waitcnt lgkmcnt(0)
	s_waitcnt lgkmcnt(0)
	v_mfma_f32_16x16x32_bf16 v[60:63], v[128:131], v[144:147], v[60:63]
	v_mfma_f32_16x16x32_bf16 v[56:59], v[136:139], v[144:147], v[56:59]
	v_mfma_f32_16x16x32_bf16 v[44:47], v[128:131], v[152:155], v[44:47]
	v_mfma_f32_16x16x32_bf16 v[40:43], v[136:139], v[152:155], v[40:43]
	v_mfma_f32_16x16x32_bf16 v[28:31], v[128:131], v[190:193], v[28:31]
	v_mfma_f32_16x16x32_bf16 v[24:27], v[136:139], v[190:193], v[24:27]
	v_mfma_f32_16x16x32_bf16 v[12:15], v[128:131], v[198:201], v[12:15]
	v_mfma_f32_16x16x32_bf16 v[8:11], v[136:139], v[198:201], v[8:11]
	v_mfma_f32_16x16x32_bf16 v[60:63], v[132:135], v[148:151], v[60:63]
	v_mfma_f32_16x16x32_bf16 v[56:59], v[140:143], v[148:151], v[56:59]
	v_mfma_f32_16x16x32_bf16 v[44:47], v[132:135], v[186:189], v[44:47]
	v_mfma_f32_16x16x32_bf16 v[40:43], v[140:143], v[186:189], v[40:43]
	v_mfma_f32_16x16x32_bf16 v[28:31], v[132:135], v[194:197], v[28:31]
	v_mfma_f32_16x16x32_bf16 v[24:27], v[140:143], v[194:197], v[24:27]
	v_mfma_f32_16x16x32_bf16 v[12:15], v[132:135], v[204:207], v[12:15]
	v_mfma_f32_16x16x32_bf16 v[8:11], v[140:143], v[204:207], v[8:11]
	s_barrier
	s_add_u32 s48, vcc_lo, 0x40080
	s_addc_u32 s49, vcc_hi, 0
	s_add_i32 s74, s75, s7
	v_lshl_add_u64 v[128:129], s[48:49], 0, v[174:175]
	s_mov_b32 m0, s74
	s_nop 0
	global_load_lds_dwordx4 v[128:129], off
	v_lshl_add_u64 v[128:129], s[48:49], 0, v[156:157]
	s_add_i32 m0, s74, 0x2000
	s_nop 0
	global_load_lds_dwordx4 v[128:129], off
	s_waitcnt vmcnt(6)
	s_barrier
	v_mfma_f32_16x16x32_bf16 v[52:55], v[208:211], v[144:147], v[52:55]
	v_mfma_f32_16x16x32_bf16 v[48:51], v[232:235], v[144:147], v[48:51]
	v_mfma_f32_16x16x32_bf16 v[36:39], v[208:211], v[152:155], v[36:39]
	v_mfma_f32_16x16x32_bf16 v[32:35], v[232:235], v[152:155], v[32:35]
	v_mfma_f32_16x16x32_bf16 v[20:23], v[208:211], v[190:193], v[20:23]
	v_mfma_f32_16x16x32_bf16 v[16:19], v[232:235], v[190:193], v[16:19]
	v_mfma_f32_16x16x32_bf16 v[4:7], v[208:211], v[198:201], v[4:7]
	v_mfma_f32_16x16x32_bf16 v[0:3], v[232:235], v[198:201], v[0:3]
	v_mfma_f32_16x16x32_bf16 v[52:55], v[226:229], v[148:151], v[52:55]
	v_mfma_f32_16x16x32_bf16 v[48:51], v[236:239], v[148:151], v[48:51]
	v_mfma_f32_16x16x32_bf16 v[36:39], v[226:229], v[186:189], v[36:39]
	v_mfma_f32_16x16x32_bf16 v[32:35], v[236:239], v[186:189], v[32:35]
	v_mfma_f32_16x16x32_bf16 v[20:23], v[226:229], v[194:197], v[20:23]
	v_mfma_f32_16x16x32_bf16 v[16:19], v[236:239], v[194:197], v[16:19]
	v_mfma_f32_16x16x32_bf16 v[4:7], v[226:229], v[204:207], v[4:7]
	v_mfma_f32_16x16x32_bf16 v[0:3], v[236:239], v[204:207], v[0:3]
	s_add_i32 s73, s73, 2
	s_add_u32 s34, s34, 0x100
	s_addc_u32 s35, s35, 0
	s_add_u32 s52, s52, 0x100
	s_addc_u32 s72, s72, 0
	s_cmp_gt_u32 s73, 13
	s_barrier
	s_cbranch_scc0 .LBB0_863
	s_cmp_lt_u32 s101, 0x100
	s_cbranch_scc0 .Lxa_6
	s_barrier

; #define PG8_STAGE(bufoff, gbase, voff) do { _Pragma("unroll") for (int _i = 0; _i < 2; ++_i) \
;     __builtin_amdgcn_global_load_lds((const unsigned*)((const char*)(gbase) + (voff)[_i]), (LAS unsigned*)(lds + (bufoff) + ldsw + _i * 8192), 16, 0, 0); } while (0)
; #define PG8_LDA(dst, b, h) do { _Pragma("unroll") for (int m = 0; m < 4; ++m) _Pragma("unroll") for (int k = 0; k < 2; ++k) dst[m][k] = *(const LAS bf16x8*)(lds + PG8_SA(b, h) + aoff + m * 2048 + k * 1024); } while (0)
; #define PG8_LDB(dst, b, h) do { _Pragma("unroll") for (int n = 0; n < 2; ++n) _Pragma("unroll") for (int k = 0; k < 2; ++k) dst[n][k] = *(const LAS bf16x8*)(lds + PG8_SB(b, h) + boff + n * 2048 + k * 1024); } while (0)
; #define PG8_MMA(ai, bj, At, Bt) do { __builtin_amdgcn_s_setprio(1); _Pragma("unroll") for (int m = 0; m < 4; ++m) _Pragma("unroll") for (int n = 0; n < 2; ++n) _Pragma("unroll") for (int k = 0; k < 2; ++k) \
;     acc[ai][bj][m][n] = __builtin_amdgcn_mfma_f32_16x16x32_bf16(Bt[n][k], At[m][k], acc[ai][bj][m][n], 0, 0, 0); __builtin_amdgcn_s_setprio(0); } while (0)
; #define PG8_WAIT_L(n) asm volatile("s_waitcnt lgkmcnt(" #n ")" ::: "memory")
; #define PG8_BAR __builtin_amdgcn_s_barrier()
; #define PG8_SCHED __builtin_amdgcn_sched_barrier(0)
; template <class Epi, class Sched>
; __device__ __forceinline__ void gemm_phase(LAS unsigned char* lds, const Gemm g, const Sched& S, const Epi& E) {
;     ...
;     for (int t = 0; t < nt; t += 2) {
;       const bool last = (t == nt - 2);
;       const char* a1 = cA + (size_t)(t + 1) * kstep;
;       const char* a2 = last ? nA : cA + (size_t)(t + 2) * kstep; const char* b2 = last ? nB : cB + (size_t)(t + 2) * kstep;
;       const char* a3 = a2 + kstep; const char* b3 = b2 + kstep;
;       if (last && has_next) S.a_ready(nxt);
;       PG8_LDB(B0, 0, 0); PG8_SCHED; PG8_LDA(At, 0, 0); PG8_STAGE(PG8_SA(1, 1), a1 + hstep, voffA);
;       PG8_WAIT_L(8); PG8_BAR; PG8_WAIT_L(0); PG8_MMA(0, 0, At, B0); PG8_BAR; PG8_SCHED;
;       PG8_LDB(B1, 0, 1); PG8_STAGE(PG8_SB(0, 0), b2, voffB);
;       PG8_BAR; PG8_WAIT_L(0); PG8_MMA(0, 1, At, B1); PG8_BAR;
;       PG8_LDA(At, 0, 1); PG8_STAGE(PG8_SA(0, 0), a2, voffA);
;       PG8_BAR; PG8_WAIT_L(0); PG8_MMA(1, 0, At, B0); PG8_BAR; PG8_SCHED;
.Lxs_e7:
.LBB0_890:
	s_add_u32 s44, s42, 0xfffc0080
	s_addc_u32 s45, s43, -1
	s_add_i32 s74, 0, 0x10000
	v_add_u32_e32 v143, s74, v141
	ds_read_b128 v[144:147], v143
	ds_read_b128 v[148:151], v143 offset:1024
	ds_read_b128 v[152:155], v143 offset:2048
	ds_read_b128 v[156:159], v143 offset:3072
	s_cmp_eq_u32 s73, 12
	s_cselect_b32 s49, s35, s45
	s_cselect_b32 s48, s70, s44
	s_cselect_b32 s45, s23, s72
	s_cselect_b32 s44, s71, s52
	v_lshl_add_u64 v[206:207], s[42:43], 0, v[136:137]
	s_add_i32 m0, s12, 0xc000
	ds_read_b128 v[174:177], v142
	ds_read_b128 v[178:181], v142 offset:1024
	ds_read_b128 v[182:185], v142 offset:2048
	ds_read_b128 v[186:189], v142 offset:3072
	ds_read_b128 v[190:193], v142 offset:4096
	ds_read_b128 v[194:197], v142 offset:5120
	ds_read_b128 v[198:201], v142 offset:6144
	ds_read_b128 v[202:205], v142 offset:7168
	global_load_lds_dwordx4 v[206:207], off
	v_lshl_add_u64 v[206:207], s[42:43], 0, v[138:139]
	s_add_i32 m0, s12, 0xe000
	s_nop 0
	global_load_lds_dwordx4 v[206:207], off
	s_waitcnt lgkmcnt(8)
	s_barrier
	s_waitcnt lgkmcnt(0)
	s_waitcnt lgkmcnt(0)
	v_mfma_f32_16x16x32_bf16 v[124:127], v[144:147], v[174:177], v[124:127]
	v_mfma_f32_16x16x32_bf16 v[120:123], v[152:155], v[174:177], v[120:123]
	v_mfma_f32_16x16x32_bf16 v[116:119], v[144:147], v[182:185], v[116:119]
	v_mfma_f32_16x16x32_bf16 v[112:115], v[152:155], v[182:185], v[112:115]
	v_mfma_f32_16x16x32_bf16 v[100:103], v[144:147], v[190:193], v[100:103]
	v_mfma_f32_16x16x32_bf16 v[96:99], v[152:155], v[190:193], v[96:99]
	v_mfma_f32_16x16x32_bf16 v[84:87], v[144:147], v[198:201], v[84:87]
	v_mfma_f32_16x16x32_bf16 v[80:83], v[152:155], v[198:201], v[80:83]
	v_mfma_f32_16x16x32_bf16 v[124:127], v[148:151], v[178:181], v[124:127]
	v_mfma_f32_16x16x32_bf16 v[120:123], v[156:159], v[178:181], v[120:123]
	v_mfma_f32_16x16x32_bf16 v[116:119], v[148:151], v[186:189], v[116:119]
	v_mfma_f32_16x16x32_bf16 v[112:115], v[156:159], v[186:189], v[112:115]
	v_mfma_f32_16x16x32_bf16 v[100:103], v[148:151], v[194:197], v[100:103]
	v_mfma_f32_16x16x32_bf16 v[96:99], v[156:159], v[194:197], v[96:99]
	v_mfma_f32_16x16x32_bf16 v[84:87], v[148:151], v[202:205], v[84:87]
	v_mfma_f32_16x16x32_bf16 v[80:83], v[156:159], v[202:205], v[80:83]
	s_barrier
	s_add_i32 s76, 0, 0x14000
	s_add_i32 s74, s74, s7
	v_add_u32_e32 v143, s76, v141
	v_lshl_add_u64 v[222:223], s[44:45], 0, v[132:133]
	s_mov_b32 m0, s74
	ds_read_b128 v[206:209], v143
	ds_read_b128 v[210:213], v143 offset:1024
	ds_read_b128 v[226:229], v143 offset:2048
	ds_read_b128 v[232:235], v143 offset:3072
	global_load_lds_dwordx4 v[222:223], off
	v_lshl_add_u64 v[236:237], s[44:45], 0, v[128:129]
	s_add_i32 m0, s74, 0x2000
	s_nop 0
	global_load_lds_dwordx4 v[236:237], off
	s_barrier
	s_waitcnt lgkmcnt(0)
	s_waitcnt lgkmcnt(0)
	v_mfma_f32_16x16x32_bf16 v[108:111], v[206:209], v[174:177], v[108:111]
	v_mfma_f32_16x16x32_bf16 v[104:107], v[226:229], v[174:177], v[104:107]
	v_mfma_f32_16x16x32_bf16 v[92:95], v[206:209], v[182:185], v[92:95]
	v_mfma_f32_16x16x32_bf16 v[88:91], v[226:229], v[182:185], v[88:91]
	v_mfma_f32_16x16x32_bf16 v[76:79], v[206:209], v[190:193], v[76:79]
	v_mfma_f32_16x16x32_bf16 v[72:75], v[226:229], v[190:193], v[72:75]
	v_mfma_f32_16x16x32_bf16 v[68:71], v[206:209], v[198:201], v[68:71]
	v_mfma_f32_16x16x32_bf16 v[64:67], v[226:229], v[198:201], v[64:67]
	v_mfma_f32_16x16x32_bf16 v[108:111], v[210:213], v[178:181], v[108:111]
	v_mfma_f32_16x16x32_bf16 v[104:107], v[232:235], v[178:181], v[104:107]
	v_mfma_f32_16x16x32_bf16 v[92:95], v[210:213], v[186:189], v[92:95]
	v_mfma_f32_16x16x32_bf16 v[88:91], v[232:235], v[186:189], v[88:91]
	v_mfma_f32_16x16x32_bf16 v[76:79], v[210:213], v[194:197], v[76:79]
	v_mfma_f32_16x16x32_bf16 v[72:75], v[232:235], v[194:197], v[72:75]
	v_mfma_f32_16x16x32_bf16 v[68:71], v[210:213], v[202:205], v[68:71]
	v_mfma_f32_16x16x32_bf16 v[64:67], v[232:235], v[202:205], v[64:67]
	s_mov_b32 m0, s12
	v_lshl_add_u64 v[238:239], s[48:49], 0, v[134:135]
	s_barrier
	ds_read_b128 v[174:177], v142 offset:16384
	ds_read_b128 v[178:181], v142 offset:17408
	ds_read_b128 v[182:185], v142 offset:18432
	ds_read_b128 v[186:189], v142 offset:19456
	ds_read_b128 v[190:193], v142 offset:20480
	ds_read_b128 v[194:197], v142 offset:21504
	ds_read_b128 v[198:201], v142 offset:22528
	ds_read_b128 v[202:205], v142 offset:23552
	global_load_lds_dwordx4 v[238:239], off
	v_lshl_add_u64 v[240:241], s[48:49], 0, v[130:131]
	s_mov_b32 m0, s13
	s_nop 0
	global_load_lds_dwordx4 v[240:241], off
	s_barrier
	s_waitcnt lgkmcnt(0)
	s_waitcnt lgkmcnt(0)
	v_mfma_f32_16x16x32_bf16 v[60:63], v[144:147], v[174:177], v[60:63]
	v_mfma_f32_16x16x32_bf16 v[56:59], v[152:155], v[174:177], v[56:59]
	v_mfma_f32_16x16x32_bf16 v[52:55], v[144:147], v[182:185], v[52:55]
	v_mfma_f32_16x16x32_bf16 v[48:51], v[152:155], v[182:185], v[48:51]
	v_mfma_f32_16x16x32_bf16 v[36:39], v[144:147], v[190:193], v[36:39]
	v_mfma_f32_16x16x32_bf16 v[32:35], v[152:155], v[190:193], v[32:35]
	v_mfma_f32_16x16x32_bf16 v[20:23], v[144:147], v[198:201], v[20:23]
	v_mfma_f32_16x16x32_bf16 v[16:19], v[152:155], v[198:201], v[16:19]
	v_mfma_f32_16x16x32_bf16 v[60:63], v[148:151], v[178:181], v[60:63]
	v_mfma_f32_16x16x32_bf16 v[56:59], v[156:159], v[178:181], v[56:59]
	v_mfma_f32_16x16x32_bf16 v[52:55], v[148:151], v[186:189], v[52:55]
	v_mfma_f32_16x16x32_bf16 v[48:51], v[156:159], v[186:189], v[48:51]
	v_mfma_f32_16x16x32_bf16 v[36:39], v[148:151], v[194:197], v[36:39]
	v_mfma_f32_16x16x32_bf16 v[32:35], v[156:159], v[194:197], v[32:35]
	v_mfma_f32_16x16x32_bf16 v[20:23], v[148:151], v[202:205], v[20:23]
	v_mfma_f32_16x16x32_bf16 v[16:19], v[156:159], v[202:205], v[16:19]
	s_barrier
; #define PG8_STAGE(bufoff, gbase, voff) do { _Pragma("unroll") for (int _i = 0; _i < 2; ++_i) \
;     __builtin_amdgcn_global_load_lds((const unsigned*)((const char*)(gbase) + (voff)[_i]), (LAS unsigned*)(lds + (bufoff) + ldsw + _i * 8192), 16, 0, 0); } while (0)
; #define PG8_LDA(dst, b, h) do { _Pragma("unroll") for (int m = 0; m < 4; ++m) _Pragma("unroll") for (int k = 0; k < 2; ++k) dst[m][k] = *(const LAS bf16x8*)(lds + PG8_SA(b, h) + aoff + m * 2048 + k * 1024); } while (0)
; #define PG8_LDB(dst, b, h) do { _Pragma("unroll") for (int n = 0; n < 2; ++n) _Pragma("unroll") for (int k = 0; k < 2; ++k) dst[n][k] = *(const LAS bf16x8*)(lds + PG8_SB(b, h) + boff + n * 2048 + k * 1024); } while (0)
; #define PG8_MMA(ai, bj, At, Bt) do { __builtin_amdgcn_s_setprio(1); _Pragma("unroll") for (int m = 0; m < 4; ++m) _Pragma("unroll") for (int n = 0; n < 2; ++n) _Pragma("unroll") for (int k = 0; k < 2; ++k) \
;     acc[ai][bj][m][n] = __builtin_amdgcn_mfma_f32_16x16x32_bf16(Bt[n][k], At[m][k], acc[ai][bj][m][n], 0, 0, 0); __builtin_amdgcn_s_setprio(0); } while (0)
; #define PG8_WAIT_V(n) asm volatile("s_waitcnt vmcnt(" #n ")" ::: "memory")
; #define PG8_WAIT_L(n) asm volatile("s_waitcnt lgkmcnt(" #n ")" ::: "memory")
; #define PG8_BAR __builtin_amdgcn_s_barrier()
; #define PG8_SCHED __builtin_amdgcn_sched_barrier(0)
; template <class Epi, class Sched>
; __device__ __forceinline__ void gemm_phase(LAS unsigned char* lds, const Gemm g, const Sched& S, const Epi& E) {
;     ...
;       PG8_STAGE(PG8_SB(0, 1), b2 + hstep, voffB);
;       PG8_WAIT_V(6); PG8_BAR; PG8_MMA(1, 1, At, B1); PG8_BAR;
;       PG8_LDB(B0, 1, 0); PG8_SCHED; PG8_LDA(At, 1, 0); PG8_STAGE(PG8_SA(0, 1), a2 + hstep, voffA);
;       PG8_WAIT_L(8); PG8_BAR; PG8_WAIT_L(0); PG8_MMA(0, 0, At, B0); PG8_BAR; PG8_SCHED;
;       PG8_LDB(B1, 1, 1); PG8_STAGE(PG8_SB(1, 0), b3, voffB);
	s_add_u32 s74, s44, 0x40000
	s_addc_u32 s75, s45, 0
	s_add_i32 s76, s76, s7
	v_lshl_add_u64 v[144:145], s[74:75], 0, v[132:133]
	s_mov_b32 m0, s76
	s_nop 0
	global_load_lds_dwordx4 v[144:145], off
	v_lshl_add_u64 v[144:145], s[74:75], 0, v[128:129]
	s_add_i32 m0, s76, 0x2000
	s_nop 0
	global_load_lds_dwordx4 v[144:145], off
	s_waitcnt vmcnt(6)
	s_barrier
	v_mfma_f32_16x16x32_bf16 v[44:47], v[206:209], v[174:177], v[44:47]
	v_mfma_f32_16x16x32_bf16 v[40:43], v[226:229], v[174:177], v[40:43]
	v_mfma_f32_16x16x32_bf16 v[28:31], v[206:209], v[182:185], v[28:31]
	v_mfma_f32_16x16x32_bf16 v[24:27], v[226:229], v[182:185], v[24:27]
	v_mfma_f32_16x16x32_bf16 v[12:15], v[206:209], v[190:193], v[12:15]
	v_mfma_f32_16x16x32_bf16 v[8:11], v[226:229], v[190:193], v[8:11]
	v_mfma_f32_16x16x32_bf16 v[4:7], v[206:209], v[198:201], v[4:7]
	v_mfma_f32_16x16x32_bf16 v[0:3], v[226:229], v[198:201], v[0:3]
	v_mfma_f32_16x16x32_bf16 v[44:47], v[210:213], v[178:181], v[44:47]
	v_mfma_f32_16x16x32_bf16 v[40:43], v[232:235], v[178:181], v[40:43]
	v_mfma_f32_16x16x32_bf16 v[28:31], v[210:213], v[186:189], v[28:31]
	v_mfma_f32_16x16x32_bf16 v[24:27], v[232:235], v[186:189], v[24:27]
	v_mfma_f32_16x16x32_bf16 v[12:15], v[210:213], v[194:197], v[12:15]
	v_mfma_f32_16x16x32_bf16 v[8:11], v[232:235], v[194:197], v[8:11]
	v_mfma_f32_16x16x32_bf16 v[4:7], v[210:213], v[202:205], v[4:7]
	v_mfma_f32_16x16x32_bf16 v[0:3], v[232:235], v[202:205], v[0:3]
	s_add_i32 s74, 0, 0x18000
	v_add_u32_e32 v143, s74, v141
	s_barrier
	ds_read_b128 v[144:147], v143
	ds_read_b128 v[148:151], v143 offset:1024
	ds_read_b128 v[152:155], v143 offset:2048
	ds_read_b128 v[156:159], v143 offset:3072
	s_add_u32 s48, s48, 0x40000
	s_addc_u32 s49, s49, 0
	s_mov_b32 m0, s51
	v_lshl_add_u64 v[206:207], s[48:49], 0, v[134:135]
	ds_read_b128 v[174:177], v142 offset:32768
	ds_read_b128 v[178:181], v142 offset:33792
	ds_read_b128 v[182:185], v142 offset:34816
	ds_read_b128 v[186:189], v142 offset:35840
	ds_read_b128 v[190:193], v142 offset:36864
	ds_read_b128 v[194:197], v142 offset:37888
	ds_read_b128 v[198:201], v142 offset:38912
	ds_read_b128 v[202:205], v142 offset:39936
	global_load_lds_dwordx4 v[206:207], off
	v_lshl_add_u64 v[206:207], s[48:49], 0, v[130:131]
	s_mov_b32 m0, s62
	s_nop 0
	global_load_lds_dwordx4 v[206:207], off
	s_waitcnt lgkmcnt(8)
	s_barrier
	s_waitcnt lgkmcnt(0)
	s_waitcnt lgkmcnt(0)
	v_mfma_f32_16x16x32_bf16 v[124:127], v[144:147], v[174:177], v[124:127]
	v_mfma_f32_16x16x32_bf16 v[120:123], v[152:155], v[174:177], v[120:123]
	v_mfma_f32_16x16x32_bf16 v[116:119], v[144:147], v[182:185], v[116:119]
	v_mfma_f32_16x16x32_bf16 v[112:115], v[152:155], v[182:185], v[112:115]
	v_mfma_f32_16x16x32_bf16 v[100:103], v[144:147], v[190:193], v[100:103]
	v_mfma_f32_16x16x32_bf16 v[96:99], v[152:155], v[190:193], v[96:99]
	v_mfma_f32_16x16x32_bf16 v[84:87], v[144:147], v[198:201], v[84:87]
	v_mfma_f32_16x16x32_bf16 v[80:83], v[152:155], v[198:201], v[80:83]
	v_mfma_f32_16x16x32_bf16 v[124:127], v[148:151], v[178:181], v[124:127]
	v_mfma_f32_16x16x32_bf16 v[120:123], v[156:159], v[178:181], v[120:123]
	v_mfma_f32_16x16x32_bf16 v[116:119], v[148:151], v[186:189], v[116:119]
	v_mfma_f32_16x16x32_bf16 v[112:115], v[156:159], v[186:189], v[112:115]
	v_mfma_f32_16x16x32_bf16 v[100:103], v[148:151], v[194:197], v[100:103]
	v_mfma_f32_16x16x32_bf16 v[96:99], v[156:159], v[194:197], v[96:99]
	v_mfma_f32_16x16x32_bf16 v[84:87], v[148:151], v[202:205], v[84:87]
	v_mfma_f32_16x16x32_bf16 v[80:83], v[156:159], v[202:205], v[80:83]
	s_barrier
	s_add_i32 s48, 0, 0x1c000
	s_add_i32 s49, s74, s7
	v_add_u32_e32 v143, s48, v141
	v_lshl_add_u64 v[222:223], v[222:223], 0, s[80:81]
	s_mov_b32 m0, s49
	ds_read_b128 v[206:209], v143
	ds_read_b128 v[210:213], v143 offset:1024
	ds_read_b128 v[226:229], v143 offset:2048
	ds_read_b128 v[232:235], v143 offset:3072
	global_load_lds_dwordx4 v[222:223], off
	v_lshl_add_u64 v[222:223], v[236:237], 0, s[80:81]
	s_add_i32 m0, s49, 0x2000
	s_nop 0
	global_load_lds_dwordx4 v[222:223], off
	s_barrier
; #define PG8_STAGE(bufoff, gbase, voff) do { _Pragma("unroll") for (int _i = 0; _i < 2; ++_i) \
;     __builtin_amdgcn_global_load_lds((const unsigned*)((const char*)(gbase) + (voff)[_i]), (LAS unsigned*)(lds + (bufoff) + ldsw + _i * 8192), 16, 0, 0); } while (0)
; #define PG8_LDA(dst, b, h) do { _Pragma("unroll") for (int m = 0; m < 4; ++m) _Pragma("unroll") for (int k = 0; k < 2; ++k) dst[m][k] = *(const LAS bf16x8*)(lds + PG8_SA(b, h) + aoff + m * 2048 + k * 1024); } while (0)
; #define PG8_MMA(ai, bj, At, Bt) do { __builtin_amdgcn_s_setprio(1); _Pragma("unroll") for (int m = 0; m < 4; ++m) _Pragma("unroll") for (int n = 0; n < 2; ++n) _Pragma("unroll") for (int k = 0; k < 2; ++k) \
;     acc[ai][bj][m][n] = __builtin_amdgcn_mfma_f32_16x16x32_bf16(Bt[n][k], At[m][k], acc[ai][bj][m][n], 0, 0, 0); __builtin_amdgcn_s_setprio(0); } while (0)
; #define PG8_WAIT_V(n) asm volatile("s_waitcnt vmcnt(" #n ")" ::: "memory")
; #define PG8_WAIT_L(n) asm volatile("s_waitcnt lgkmcnt(" #n ")" ::: "memory")
; #define PG8_BAR __builtin_amdgcn_s_barrier()
; #define PG8_SCHED __builtin_amdgcn_sched_barrier(0)
; template <class Epi, class Sched>
; __device__ __forceinline__ void gemm_phase(LAS unsigned char* lds, const Gemm g, const Sched& S, const Epi& E) {
;     ...
;       PG8_BAR; PG8_WAIT_L(0); PG8_MMA(0, 1, At, B1); PG8_BAR;
;       PG8_LDA(At, 1, 1); PG8_STAGE(PG8_SA(1, 0), a3, voffA);
;       PG8_BAR; PG8_WAIT_L(0); PG8_MMA(1, 0, At, B0); PG8_BAR; PG8_SCHED;
;       PG8_STAGE(PG8_SB(1, 1), b3 + hstep, voffB);
;       PG8_WAIT_V(6); PG8_BAR; PG8_MMA(1, 1, At, B1); PG8_BAR;
;     }
	s_waitcnt lgkmcnt(0)
	s_waitcnt lgkmcnt(0)
	v_mfma_f32_16x16x32_bf16 v[108:111], v[206:209], v[174:177], v[108:111]
	v_mfma_f32_16x16x32_bf16 v[104:107], v[226:229], v[174:177], v[104:107]
	v_mfma_f32_16x16x32_bf16 v[92:95], v[206:209], v[182:185], v[92:95]
	v_mfma_f32_16x16x32_bf16 v[88:91], v[226:229], v[182:185], v[88:91]
	v_mfma_f32_16x16x32_bf16 v[76:79], v[206:209], v[190:193], v[76:79]
	v_mfma_f32_16x16x32_bf16 v[72:75], v[226:229], v[190:193], v[72:75]
	v_mfma_f32_16x16x32_bf16 v[68:71], v[206:209], v[198:201], v[68:71]
	v_mfma_f32_16x16x32_bf16 v[64:67], v[226:229], v[198:201], v[64:67]
	v_mfma_f32_16x16x32_bf16 v[108:111], v[210:213], v[178:181], v[108:111]
	v_mfma_f32_16x16x32_bf16 v[104:107], v[232:235], v[178:181], v[104:107]
	v_mfma_f32_16x16x32_bf16 v[92:95], v[210:213], v[186:189], v[92:95]
	v_mfma_f32_16x16x32_bf16 v[88:91], v[232:235], v[186:189], v[88:91]
	v_mfma_f32_16x16x32_bf16 v[76:79], v[210:213], v[194:197], v[76:79]
	v_mfma_f32_16x16x32_bf16 v[72:75], v[232:235], v[194:197], v[72:75]
	v_mfma_f32_16x16x32_bf16 v[68:71], v[210:213], v[202:205], v[68:71]
	v_mfma_f32_16x16x32_bf16 v[64:67], v[232:235], v[202:205], v[64:67]
	s_mov_b32 m0, s63
	v_lshl_add_u64 v[222:223], v[238:239], 0, s[80:81]
	s_barrier
	ds_read_b128 v[174:177], v142 offset:49152
	ds_read_b128 v[178:181], v142 offset:50176
	ds_read_b128 v[182:185], v142 offset:51200
	ds_read_b128 v[186:189], v142 offset:52224
	ds_read_b128 v[190:193], v142 offset:53248
	ds_read_b128 v[194:197], v142 offset:54272
	ds_read_b128 v[198:201], v142 offset:55296
	ds_read_b128 v[202:205], v142 offset:56320
	global_load_lds_dwordx4 v[222:223], off
	v_lshl_add_u64 v[222:223], v[240:241], 0, s[80:81]
	s_mov_b32 m0, s64
	s_nop 0
	global_load_lds_dwordx4 v[222:223], off
	s_barrier
	s_waitcnt lgkmcnt(0)
	s_waitcnt lgkmcnt(0)
	v_mfma_f32_16x16x32_bf16 v[60:63], v[144:147], v[174:177], v[60:63]
	v_mfma_f32_16x16x32_bf16 v[56:59], v[152:155], v[174:177], v[56:59]
	v_mfma_f32_16x16x32_bf16 v[52:55], v[144:147], v[182:185], v[52:55]
	v_mfma_f32_16x16x32_bf16 v[48:51], v[152:155], v[182:185], v[48:51]
	v_mfma_f32_16x16x32_bf16 v[36:39], v[144:147], v[190:193], v[36:39]
	v_mfma_f32_16x16x32_bf16 v[32:35], v[152:155], v[190:193], v[32:35]
	v_mfma_f32_16x16x32_bf16 v[20:23], v[144:147], v[198:201], v[20:23]
	v_mfma_f32_16x16x32_bf16 v[16:19], v[152:155], v[198:201], v[16:19]
	v_mfma_f32_16x16x32_bf16 v[60:63], v[148:151], v[178:181], v[60:63]
	v_mfma_f32_16x16x32_bf16 v[56:59], v[156:159], v[178:181], v[56:59]
	v_mfma_f32_16x16x32_bf16 v[52:55], v[148:151], v[186:189], v[52:55]
	v_mfma_f32_16x16x32_bf16 v[48:51], v[156:159], v[186:189], v[48:51]
	v_mfma_f32_16x16x32_bf16 v[36:39], v[148:151], v[194:197], v[36:39]
	v_mfma_f32_16x16x32_bf16 v[32:35], v[156:159], v[194:197], v[32:35]
	v_mfma_f32_16x16x32_bf16 v[20:23], v[148:151], v[202:205], v[20:23]
	v_mfma_f32_16x16x32_bf16 v[16:19], v[156:159], v[202:205], v[16:19]
	s_barrier
	s_add_u32 s44, s44, 0x40080
	s_addc_u32 s45, s45, 0
	s_add_i32 s48, s48, s7
	v_lshl_add_u64 v[144:145], s[44:45], 0, v[132:133]
	s_mov_b32 m0, s48
	s_nop 0
	global_load_lds_dwordx4 v[144:145], off
	v_lshl_add_u64 v[144:145], s[44:45], 0, v[128:129]
	s_add_i32 m0, s48, 0x2000
	s_nop 0
	global_load_lds_dwordx4 v[144:145], off
	s_waitcnt vmcnt(6)
	s_barrier
	v_mfma_f32_16x16x32_bf16 v[44:47], v[206:209], v[174:177], v[44:47]
	v_mfma_f32_16x16x32_bf16 v[40:43], v[226:229], v[174:177], v[40:43]
	v_mfma_f32_16x16x32_bf16 v[28:31], v[206:209], v[182:185], v[28:31]
	v_mfma_f32_16x16x32_bf16 v[24:27], v[226:229], v[182:185], v[24:27]
	v_mfma_f32_16x16x32_bf16 v[12:15], v[206:209], v[190:193], v[12:15]
	v_mfma_f32_16x16x32_bf16 v[8:11], v[226:229], v[190:193], v[8:11]
	v_mfma_f32_16x16x32_bf16 v[4:7], v[206:209], v[198:201], v[4:7]
	v_mfma_f32_16x16x32_bf16 v[0:3], v[226:229], v[198:201], v[0:3]
	v_mfma_f32_16x16x32_bf16 v[44:47], v[210:213], v[178:181], v[44:47]
	v_mfma_f32_16x16x32_bf16 v[40:43], v[232:235], v[178:181], v[40:43]
	v_mfma_f32_16x16x32_bf16 v[28:31], v[210:213], v[186:189], v[28:31]
	v_mfma_f32_16x16x32_bf16 v[24:27], v[232:235], v[186:189], v[24:27]
	v_mfma_f32_16x16x32_bf16 v[12:15], v[210:213], v[194:197], v[12:15]
	v_mfma_f32_16x16x32_bf16 v[8:11], v[232:235], v[194:197], v[8:11]
	v_mfma_f32_16x16x32_bf16 v[4:7], v[210:213], v[202:205], v[4:7]
	v_mfma_f32_16x16x32_bf16 v[0:3], v[232:235], v[202:205], v[0:3]
	s_add_i32 s73, s73, 2
	s_add_u32 s42, s42, 0x100
	s_addc_u32 s43, s43, 0
	s_add_u32 s52, s52, 0x100
	s_addc_u32 s72, s72, 0
	s_cmp_gt_u32 s73, 13
	s_barrier
	s_cbranch_scc0 .LBB0_890
	s_cmp_lt_u32 s101, 0x100
	s_cbranch_scc0 .Lxa_7
	s_barrier

; #define PG8_STAGE(bufoff, gbase, voff) do { _Pragma("unroll") for (int _i = 0; _i < 2; ++_i) \
;     __builtin_amdgcn_global_load_lds((const unsigned*)((const char*)(gbase) + (voff)[_i]), (LAS unsigned*)(lds + (bufoff) + ldsw + _i * 8192), 16, 0, 0); } while (0)
; #define PG8_LDA(dst, b, h) do { _Pragma("unroll") for (int m = 0; m < 4; ++m) _Pragma("unroll") for (int k = 0; k < 2; ++k) dst[m][k] = *(const LAS bf16x8*)(lds + PG8_SA(b, h) + aoff + m * 2048 + k * 1024); } while (0)
; #define PG8_LDB(dst, b, h) do { _Pragma("unroll") for (int n = 0; n < 2; ++n) _Pragma("unroll") for (int k = 0; k < 2; ++k) dst[n][k] = *(const LAS bf16x8*)(lds + PG8_SB(b, h) + boff + n * 2048 + k * 1024); } while (0)
; #define PG8_MMA(ai, bj, At, Bt) do { __builtin_amdgcn_s_setprio(1); _Pragma("unroll") for (int m = 0; m < 4; ++m) _Pragma("unroll") for (int n = 0; n < 2; ++n) _Pragma("unroll") for (int k = 0; k < 2; ++k) \
;     acc[ai][bj][m][n] = __builtin_amdgcn_mfma_f32_16x16x32_bf16(Bt[n][k], At[m][k], acc[ai][bj][m][n], 0, 0, 0); __builtin_amdgcn_s_setprio(0); } while (0)
; #define PG8_WAIT_L(n) asm volatile("s_waitcnt lgkmcnt(" #n ")" ::: "memory")
; #define PG8_BAR __builtin_amdgcn_s_barrier()
; #define PG8_SCHED __builtin_amdgcn_sched_barrier(0)
; template <class Epi, class Sched>
; __device__ __forceinline__ void gemm_phase(LAS unsigned char* lds, const Gemm g, const Sched& S, const Epi& E) {
;     ...
;     for (int t = 0; t < nt; t += 2) {
;       const bool last = (t == nt - 2);
;       const char* a1 = cA + (size_t)(t + 1) * kstep;
;       const char* a2 = last ? nA : cA + (size_t)(t + 2) * kstep; const char* b2 = last ? nB : cB + (size_t)(t + 2) * kstep;
;       const char* a3 = a2 + kstep; const char* b3 = b2 + kstep;
;       if (last && has_next) S.a_ready(nxt);
;       PG8_LDB(B0, 0, 0); PG8_SCHED; PG8_LDA(At, 0, 0); PG8_STAGE(PG8_SA(1, 1), a1 + hstep, voffA);
;       PG8_WAIT_L(8); PG8_BAR; PG8_WAIT_L(0); PG8_MMA(0, 0, At, B0); PG8_BAR; PG8_SCHED;
;       PG8_LDB(B1, 0, 1); PG8_STAGE(PG8_SB(0, 0), b2, voffB);
;       PG8_BAR; PG8_WAIT_L(0); PG8_MMA(0, 1, At, B1); PG8_BAR;
;       PG8_LDA(At, 0, 1); PG8_STAGE(PG8_SA(0, 0), a2, voffA);
;       PG8_BAR; PG8_WAIT_L(0); PG8_MMA(1, 0, At, B0); PG8_BAR; PG8_SCHED;
.Lxs_e8:
.LBB0_968:
	s_add_u32 s44, s42, 0xfffc0080
	s_addc_u32 s45, s43, -1
	s_add_i32 s74, 0, 0x10000
	v_add_u32_e32 v140, s74, v143
	ds_read_b128 v[146:149], v140
	ds_read_b128 v[150:153], v140 offset:1024
	ds_read_b128 v[154:157], v140 offset:2048
	ds_read_b128 v[174:177], v140 offset:3072
	s_cmp_eq_u32 s73, 12
	s_cselect_b32 s49, s35, s45
	s_cselect_b32 s48, s71, s44
	s_cselect_b32 s45, s23, s72
	s_cselect_b32 s44, vcc_lo, s52
	v_lshl_add_u64 v[140:141], s[42:43], 0, v[136:137]
	s_add_i32 m0, s12, 0xc000
	ds_read_b128 v[178:181], v145
	ds_read_b128 v[182:185], v145 offset:1024
	ds_read_b128 v[186:189], v145 offset:2048
	ds_read_b128 v[190:193], v145 offset:3072
	ds_read_b128 v[194:197], v145 offset:4096
	ds_read_b128 v[198:201], v145 offset:5120
	ds_read_b128 v[202:205], v145 offset:6144
	ds_read_b128 v[206:209], v145 offset:7168
	global_load_lds_dwordx4 v[140:141], off
	v_lshl_add_u64 v[140:141], s[42:43], 0, v[138:139]
	s_add_i32 m0, s12, 0xe000
	s_nop 0
	global_load_lds_dwordx4 v[140:141], off
	s_waitcnt lgkmcnt(8)
	s_barrier
	s_waitcnt lgkmcnt(0)
	s_waitcnt lgkmcnt(0)
	v_mfma_f32_16x16x32_bf16 v[124:127], v[146:149], v[178:181], v[124:127]
	v_mfma_f32_16x16x32_bf16 v[120:123], v[154:157], v[178:181], v[120:123]
	v_mfma_f32_16x16x32_bf16 v[116:119], v[146:149], v[186:189], v[116:119]
	v_mfma_f32_16x16x32_bf16 v[108:111], v[154:157], v[186:189], v[108:111]
	v_mfma_f32_16x16x32_bf16 v[96:99], v[146:149], v[194:197], v[96:99]
	v_mfma_f32_16x16x32_bf16 v[88:91], v[154:157], v[194:197], v[88:91]
	v_mfma_f32_16x16x32_bf16 v[84:87], v[146:149], v[202:205], v[84:87]
	v_mfma_f32_16x16x32_bf16 v[76:79], v[154:157], v[202:205], v[76:79]
	v_mfma_f32_16x16x32_bf16 v[124:127], v[150:153], v[182:185], v[124:127]
	v_mfma_f32_16x16x32_bf16 v[120:123], v[174:177], v[182:185], v[120:123]
	v_mfma_f32_16x16x32_bf16 v[116:119], v[150:153], v[190:193], v[116:119]
	v_mfma_f32_16x16x32_bf16 v[108:111], v[174:177], v[190:193], v[108:111]
	v_mfma_f32_16x16x32_bf16 v[96:99], v[150:153], v[198:201], v[96:99]
	v_mfma_f32_16x16x32_bf16 v[88:91], v[174:177], v[198:201], v[88:91]
	v_mfma_f32_16x16x32_bf16 v[84:87], v[150:153], v[206:209], v[84:87]
	v_mfma_f32_16x16x32_bf16 v[76:79], v[174:177], v[206:209], v[76:79]
	s_barrier
	s_add_i32 s76, 0, 0x14000
	v_add_u32_e32 v140, s76, v143
	s_add_i32 s74, s74, s7
	ds_read_b128 v[210:213], v140
	ds_read_b128 v[226:229], v140 offset:1024
	ds_read_b128 v[232:235], v140 offset:2048
	ds_read_b128 v[236:239], v140 offset:3072
	v_lshl_add_u64 v[140:141], s[44:45], 0, v[132:133]
	s_mov_b32 m0, s74
	v_lshl_add_u64 v[158:159], s[44:45], 0, v[128:129]
	global_load_lds_dwordx4 v[140:141], off
	s_add_i32 m0, s74, 0x2000
	s_nop 0
	global_load_lds_dwordx4 v[158:159], off
	s_barrier
	s_waitcnt lgkmcnt(0)
	s_waitcnt lgkmcnt(0)
	v_mfma_f32_16x16x32_bf16 v[112:115], v[210:213], v[178:181], v[112:115]
	v_mfma_f32_16x16x32_bf16 v[104:107], v[232:235], v[178:181], v[104:107]
	v_mfma_f32_16x16x32_bf16 v[100:103], v[210:213], v[186:189], v[100:103]
	v_mfma_f32_16x16x32_bf16 v[92:95], v[232:235], v[186:189], v[92:95]
	v_mfma_f32_16x16x32_bf16 v[80:83], v[210:213], v[194:197], v[80:83]
	v_mfma_f32_16x16x32_bf16 v[72:75], v[232:235], v[194:197], v[72:75]
	v_mfma_f32_16x16x32_bf16 v[68:71], v[210:213], v[202:205], v[68:71]
	v_mfma_f32_16x16x32_bf16 v[64:67], v[232:235], v[202:205], v[64:67]
	v_mfma_f32_16x16x32_bf16 v[112:115], v[226:229], v[182:185], v[112:115]
	v_mfma_f32_16x16x32_bf16 v[104:107], v[236:239], v[182:185], v[104:107]
	v_mfma_f32_16x16x32_bf16 v[100:103], v[226:229], v[190:193], v[100:103]
	v_mfma_f32_16x16x32_bf16 v[92:95], v[236:239], v[190:193], v[92:95]
	v_mfma_f32_16x16x32_bf16 v[80:83], v[226:229], v[198:201], v[80:83]
	v_mfma_f32_16x16x32_bf16 v[72:75], v[236:239], v[198:201], v[72:75]
	v_mfma_f32_16x16x32_bf16 v[68:71], v[226:229], v[206:209], v[68:71]
	v_mfma_f32_16x16x32_bf16 v[64:67], v[236:239], v[206:209], v[64:67]
	s_mov_b32 m0, s12
	v_lshl_add_u64 v[222:223], s[48:49], 0, v[134:135]
	s_barrier
	ds_read_b128 v[178:181], v145 offset:16384
	ds_read_b128 v[182:185], v145 offset:17408
	ds_read_b128 v[186:189], v145 offset:18432
	ds_read_b128 v[190:193], v145 offset:19456
	ds_read_b128 v[194:197], v145 offset:20480
	ds_read_b128 v[198:201], v145 offset:21504
	ds_read_b128 v[202:205], v145 offset:22528
	ds_read_b128 v[206:209], v145 offset:23552
	global_load_lds_dwordx4 v[222:223], off
	v_lshl_add_u64 v[240:241], s[48:49], 0, v[130:131]
	s_mov_b32 m0, s13
	s_nop 0
	global_load_lds_dwordx4 v[240:241], off
	s_barrier
	s_waitcnt lgkmcnt(0)
	s_waitcnt lgkmcnt(0)
	v_mfma_f32_16x16x32_bf16 v[60:63], v[146:149], v[178:181], v[60:63]
	v_mfma_f32_16x16x32_bf16 v[56:59], v[154:157], v[178:181], v[56:59]
	v_mfma_f32_16x16x32_bf16 v[52:55], v[146:149], v[186:189], v[52:55]
	v_mfma_f32_16x16x32_bf16 v[44:47], v[154:157], v[186:189], v[44:47]
	v_mfma_f32_16x16x32_bf16 v[32:35], v[146:149], v[194:197], v[32:35]
	v_mfma_f32_16x16x32_bf16 v[24:27], v[154:157], v[194:197], v[24:27]
	v_mfma_f32_16x16x32_bf16 v[20:23], v[146:149], v[202:205], v[20:23]
	v_mfma_f32_16x16x32_bf16 v[12:15], v[154:157], v[202:205], v[12:15]
	v_mfma_f32_16x16x32_bf16 v[60:63], v[150:153], v[182:185], v[60:63]
	v_mfma_f32_16x16x32_bf16 v[56:59], v[174:177], v[182:185], v[56:59]
	v_mfma_f32_16x16x32_bf16 v[52:55], v[150:153], v[190:193], v[52:55]
	v_mfma_f32_16x16x32_bf16 v[44:47], v[174:177], v[190:193], v[44:47]
	v_mfma_f32_16x16x32_bf16 v[32:35], v[150:153], v[198:201], v[32:35]
	v_mfma_f32_16x16x32_bf16 v[24:27], v[174:177], v[198:201], v[24:27]
	v_mfma_f32_16x16x32_bf16 v[20:23], v[150:153], v[206:209], v[20:23]
	v_mfma_f32_16x16x32_bf16 v[12:15], v[174:177], v[206:209], v[12:15]
	s_barrier
; #define PG8_STAGE(bufoff, gbase, voff) do { _Pragma("unroll") for (int _i = 0; _i < 2; ++_i) \
;     __builtin_amdgcn_global_load_lds((const unsigned*)((const char*)(gbase) + (voff)[_i]), (LAS unsigned*)(lds + (bufoff) + ldsw + _i * 8192), 16, 0, 0); } while (0)
; #define PG8_LDA(dst, b, h) do { _Pragma("unroll") for (int m = 0; m < 4; ++m) _Pragma("unroll") for (int k = 0; k < 2; ++k) dst[m][k] = *(const LAS bf16x8*)(lds + PG8_SA(b, h) + aoff + m * 2048 + k * 1024); } while (0)
; #define PG8_LDB(dst, b, h) do { _Pragma("unroll") for (int n = 0; n < 2; ++n) _Pragma("unroll") for (int k = 0; k < 2; ++k) dst[n][k] = *(const LAS bf16x8*)(lds + PG8_SB(b, h) + boff + n * 2048 + k * 1024); } while (0)
; #define PG8_MMA(ai, bj, At, Bt) do { __builtin_amdgcn_s_setprio(1); _Pragma("unroll") for (int m = 0; m < 4; ++m) _Pragma("unroll") for (int n = 0; n < 2; ++n) _Pragma("unroll") for (int k = 0; k < 2; ++k) \
;     acc[ai][bj][m][n] = __builtin_amdgcn_mfma_f32_16x16x32_bf16(Bt[n][k], At[m][k], acc[ai][bj][m][n], 0, 0, 0); __builtin_amdgcn_s_setprio(0); } while (0)
; #define PG8_WAIT_V(n) asm volatile("s_waitcnt vmcnt(" #n ")" ::: "memory")
; #define PG8_WAIT_L(n) asm volatile("s_waitcnt lgkmcnt(" #n ")" ::: "memory")
; #define PG8_BAR __builtin_amdgcn_s_barrier()
; #define PG8_SCHED __builtin_amdgcn_sched_barrier(0)
; template <class Epi, class Sched>
; __device__ __forceinline__ void gemm_phase(LAS unsigned char* lds, const Gemm g, const Sched& S, const Epi& E) {
;     ...
;       PG8_STAGE(PG8_SB(0, 1), b2 + hstep, voffB);
;       PG8_WAIT_V(6); PG8_BAR; PG8_MMA(1, 1, At, B1); PG8_BAR;
;       PG8_LDB(B0, 1, 0); PG8_SCHED; PG8_LDA(At, 1, 0); PG8_STAGE(PG8_SA(0, 1), a2 + hstep, voffA);
;       PG8_WAIT_L(8); PG8_BAR; PG8_WAIT_L(0); PG8_MMA(0, 0, At, B0); PG8_BAR; PG8_SCHED;
;       PG8_LDB(B1, 1, 1); PG8_STAGE(PG8_SB(1, 0), b3, voffB);
;       PG8_BAR; PG8_WAIT_L(0); PG8_MMA(0, 1, At, B1); PG8_BAR;
	s_add_u32 s74, s44, 0x40000
	s_addc_u32 s75, s45, 0
	s_add_i32 s76, s76, s7
	v_lshl_add_u64 v[146:147], s[74:75], 0, v[132:133]
	s_mov_b32 m0, s76
	s_nop 0
	global_load_lds_dwordx4 v[146:147], off
	v_lshl_add_u64 v[146:147], s[74:75], 0, v[128:129]
	s_add_i32 m0, s76, 0x2000
	s_nop 0
	global_load_lds_dwordx4 v[146:147], off
	s_waitcnt vmcnt(6)
	s_barrier
	v_mfma_f32_16x16x32_bf16 v[48:51], v[210:213], v[178:181], v[48:51]
	v_mfma_f32_16x16x32_bf16 v[40:43], v[232:235], v[178:181], v[40:43]
	v_mfma_f32_16x16x32_bf16 v[36:39], v[210:213], v[186:189], v[36:39]
	v_mfma_f32_16x16x32_bf16 v[28:31], v[232:235], v[186:189], v[28:31]
	v_mfma_f32_16x16x32_bf16 v[16:19], v[210:213], v[194:197], v[16:19]
	v_mfma_f32_16x16x32_bf16 v[8:11], v[232:235], v[194:197], v[8:11]
	v_mfma_f32_16x16x32_bf16 v[4:7], v[210:213], v[202:205], v[4:7]
	v_mfma_f32_16x16x32_bf16 v[0:3], v[232:235], v[202:205], v[0:3]
	v_mfma_f32_16x16x32_bf16 v[48:51], v[226:229], v[182:185], v[48:51]
	v_mfma_f32_16x16x32_bf16 v[40:43], v[236:239], v[182:185], v[40:43]
	v_mfma_f32_16x16x32_bf16 v[36:39], v[226:229], v[190:193], v[36:39]
	v_mfma_f32_16x16x32_bf16 v[28:31], v[236:239], v[190:193], v[28:31]
	v_mfma_f32_16x16x32_bf16 v[16:19], v[226:229], v[198:201], v[16:19]
	v_mfma_f32_16x16x32_bf16 v[8:11], v[236:239], v[198:201], v[8:11]
	v_mfma_f32_16x16x32_bf16 v[4:7], v[226:229], v[206:209], v[4:7]
	v_mfma_f32_16x16x32_bf16 v[0:3], v[236:239], v[206:209], v[0:3]
	s_add_i32 s74, 0, 0x18000
	v_add_u32_e32 v174, s74, v143
	s_barrier
	ds_read_b128 v[146:149], v174
	ds_read_b128 v[150:153], v174 offset:1024
	ds_read_b128 v[154:157], v174 offset:2048
	ds_read_b128 v[174:177], v174 offset:3072
	s_add_u32 s48, s48, 0x40000
	s_addc_u32 s49, s49, 0
	s_mov_b32 m0, s51
	v_lshl_add_u64 v[210:211], s[48:49], 0, v[134:135]
	ds_read_b128 v[178:181], v145 offset:32768
	ds_read_b128 v[182:185], v145 offset:33792
	ds_read_b128 v[186:189], v145 offset:34816
	ds_read_b128 v[190:193], v145 offset:35840
	ds_read_b128 v[194:197], v145 offset:36864
	ds_read_b128 v[198:201], v145 offset:37888
	ds_read_b128 v[202:205], v145 offset:38912
	ds_read_b128 v[206:209], v145 offset:39936
	global_load_lds_dwordx4 v[210:211], off
	v_lshl_add_u64 v[210:211], s[48:49], 0, v[130:131]
	s_mov_b32 m0, s62
	s_nop 0
	global_load_lds_dwordx4 v[210:211], off
	s_waitcnt lgkmcnt(8)
	s_barrier
	s_waitcnt lgkmcnt(0)
	s_waitcnt lgkmcnt(0)
	v_mfma_f32_16x16x32_bf16 v[124:127], v[146:149], v[178:181], v[124:127]
	v_mfma_f32_16x16x32_bf16 v[120:123], v[154:157], v[178:181], v[120:123]
	v_mfma_f32_16x16x32_bf16 v[116:119], v[146:149], v[186:189], v[116:119]
	v_mfma_f32_16x16x32_bf16 v[108:111], v[154:157], v[186:189], v[108:111]
	v_mfma_f32_16x16x32_bf16 v[96:99], v[146:149], v[194:197], v[96:99]
	v_mfma_f32_16x16x32_bf16 v[88:91], v[154:157], v[194:197], v[88:91]
	v_mfma_f32_16x16x32_bf16 v[84:87], v[146:149], v[202:205], v[84:87]
	v_mfma_f32_16x16x32_bf16 v[76:79], v[154:157], v[202:205], v[76:79]
	v_mfma_f32_16x16x32_bf16 v[124:127], v[150:153], v[182:185], v[124:127]
	v_mfma_f32_16x16x32_bf16 v[120:123], v[174:177], v[182:185], v[120:123]
	v_mfma_f32_16x16x32_bf16 v[116:119], v[150:153], v[190:193], v[116:119]
	v_mfma_f32_16x16x32_bf16 v[108:111], v[174:177], v[190:193], v[108:111]
	v_mfma_f32_16x16x32_bf16 v[96:99], v[150:153], v[198:201], v[96:99]
	v_mfma_f32_16x16x32_bf16 v[88:91], v[174:177], v[198:201], v[88:91]
	v_mfma_f32_16x16x32_bf16 v[84:87], v[150:153], v[206:209], v[84:87]
	v_mfma_f32_16x16x32_bf16 v[76:79], v[174:177], v[206:209], v[76:79]
	s_barrier
	s_add_i32 s48, 0, 0x1c000
	s_add_i32 s49, s74, s7
	v_add_u32_e32 v225, s48, v143
	v_lshl_add_u64 v[140:141], v[140:141], 0, s[80:81]
	s_mov_b32 m0, s49
	ds_read_b128 v[210:213], v225
	ds_read_b128 v[226:229], v225 offset:1024
	ds_read_b128 v[232:235], v225 offset:2048
	ds_read_b128 v[236:239], v225 offset:3072
	global_load_lds_dwordx4 v[140:141], off
	v_lshl_add_u64 v[140:141], v[158:159], 0, s[80:81]
	s_add_i32 m0, s49, 0x2000
	s_nop 0
	global_load_lds_dwordx4 v[140:141], off
	s_barrier
; #define PG8_STAGE(bufoff, gbase, voff) do { _Pragma("unroll") for (int _i = 0; _i < 2; ++_i) \
;     __builtin_amdgcn_global_load_lds((const unsigned*)((const char*)(gbase) + (voff)[_i]), (LAS unsigned*)(lds + (bufoff) + ldsw + _i * 8192), 16, 0, 0); } while (0)
; #define PG8_LDA(dst, b, h) do { _Pragma("unroll") for (int m = 0; m < 4; ++m) _Pragma("unroll") for (int k = 0; k < 2; ++k) dst[m][k] = *(const LAS bf16x8*)(lds + PG8_SA(b, h) + aoff + m * 2048 + k * 1024); } while (0)
; #define PG8_MMA(ai, bj, At, Bt) do { __builtin_amdgcn_s_setprio(1); _Pragma("unroll") for (int m = 0; m < 4; ++m) _Pragma("unroll") for (int n = 0; n < 2; ++n) _Pragma("unroll") for (int k = 0; k < 2; ++k) \
;     acc[ai][bj][m][n] = __builtin_amdgcn_mfma_f32_16x16x32_bf16(Bt[n][k], At[m][k], acc[ai][bj][m][n], 0, 0, 0); __builtin_amdgcn_s_setprio(0); } while (0)
; #define PG8_WAIT_V(n) asm volatile("s_waitcnt vmcnt(" #n ")" ::: "memory")
; #define PG8_WAIT_L(n) asm volatile("s_waitcnt lgkmcnt(" #n ")" ::: "memory")
; #define PG8_BAR __builtin_amdgcn_s_barrier()
; #define PG8_SCHED __builtin_amdgcn_sched_barrier(0)
; template <class Epi, class Sched>
; __device__ __forceinline__ void gemm_phase(LAS unsigned char* lds, const Gemm g, const Sched& S, const Epi& E) {
;     ...
;       PG8_BAR; PG8_WAIT_L(0); PG8_MMA(0, 1, At, B1); PG8_BAR;
;       PG8_LDA(At, 1, 1); PG8_STAGE(PG8_SA(1, 0), a3, voffA);
;       PG8_BAR; PG8_WAIT_L(0); PG8_MMA(1, 0, At, B0); PG8_BAR; PG8_SCHED;
;       PG8_STAGE(PG8_SB(1, 1), b3 + hstep, voffB);
;       PG8_WAIT_V(6); PG8_BAR; PG8_MMA(1, 1, At, B1); PG8_BAR;
;     }
	s_waitcnt lgkmcnt(0)
	s_waitcnt lgkmcnt(0)
	v_mfma_f32_16x16x32_bf16 v[112:115], v[210:213], v[178:181], v[112:115]
	v_mfma_f32_16x16x32_bf16 v[104:107], v[232:235], v[178:181], v[104:107]
	v_mfma_f32_16x16x32_bf16 v[100:103], v[210:213], v[186:189], v[100:103]
	v_mfma_f32_16x16x32_bf16 v[92:95], v[232:235], v[186:189], v[92:95]
	v_mfma_f32_16x16x32_bf16 v[80:83], v[210:213], v[194:197], v[80:83]
	v_mfma_f32_16x16x32_bf16 v[72:75], v[232:235], v[194:197], v[72:75]
	v_mfma_f32_16x16x32_bf16 v[68:71], v[210:213], v[202:205], v[68:71]
	v_mfma_f32_16x16x32_bf16 v[64:67], v[232:235], v[202:205], v[64:67]
	v_mfma_f32_16x16x32_bf16 v[112:115], v[226:229], v[182:185], v[112:115]
	v_mfma_f32_16x16x32_bf16 v[104:107], v[236:239], v[182:185], v[104:107]
	v_mfma_f32_16x16x32_bf16 v[100:103], v[226:229], v[190:193], v[100:103]
	v_mfma_f32_16x16x32_bf16 v[92:95], v[236:239], v[190:193], v[92:95]
	v_mfma_f32_16x16x32_bf16 v[80:83], v[226:229], v[198:201], v[80:83]
	v_mfma_f32_16x16x32_bf16 v[72:75], v[236:239], v[198:201], v[72:75]
	v_mfma_f32_16x16x32_bf16 v[68:71], v[226:229], v[206:209], v[68:71]
	v_mfma_f32_16x16x32_bf16 v[64:67], v[236:239], v[206:209], v[64:67]
	s_mov_b32 m0, s63
	v_lshl_add_u64 v[140:141], v[222:223], 0, s[80:81]
	s_barrier
	ds_read_b128 v[178:181], v145 offset:49152
	ds_read_b128 v[182:185], v145 offset:50176
	ds_read_b128 v[186:189], v145 offset:51200
	ds_read_b128 v[190:193], v145 offset:52224
	ds_read_b128 v[194:197], v145 offset:53248
	ds_read_b128 v[198:201], v145 offset:54272
	ds_read_b128 v[202:205], v145 offset:55296
	ds_read_b128 v[206:209], v145 offset:56320
	global_load_lds_dwordx4 v[140:141], off
	v_lshl_add_u64 v[140:141], v[240:241], 0, s[80:81]
	s_mov_b32 m0, s64
	s_nop 0
	global_load_lds_dwordx4 v[140:141], off
	s_barrier
	s_waitcnt lgkmcnt(0)
	s_waitcnt lgkmcnt(0)
	v_mfma_f32_16x16x32_bf16 v[60:63], v[146:149], v[178:181], v[60:63]
	v_mfma_f32_16x16x32_bf16 v[56:59], v[154:157], v[178:181], v[56:59]
	v_mfma_f32_16x16x32_bf16 v[52:55], v[146:149], v[186:189], v[52:55]
	v_mfma_f32_16x16x32_bf16 v[44:47], v[154:157], v[186:189], v[44:47]
	v_mfma_f32_16x16x32_bf16 v[32:35], v[146:149], v[194:197], v[32:35]
	v_mfma_f32_16x16x32_bf16 v[24:27], v[154:157], v[194:197], v[24:27]
	v_mfma_f32_16x16x32_bf16 v[20:23], v[146:149], v[202:205], v[20:23]
	v_mfma_f32_16x16x32_bf16 v[12:15], v[154:157], v[202:205], v[12:15]
	v_mfma_f32_16x16x32_bf16 v[60:63], v[150:153], v[182:185], v[60:63]
	v_mfma_f32_16x16x32_bf16 v[56:59], v[174:177], v[182:185], v[56:59]
	v_mfma_f32_16x16x32_bf16 v[52:55], v[150:153], v[190:193], v[52:55]
	v_mfma_f32_16x16x32_bf16 v[44:47], v[174:177], v[190:193], v[44:47]
	v_mfma_f32_16x16x32_bf16 v[32:35], v[150:153], v[198:201], v[32:35]
	v_mfma_f32_16x16x32_bf16 v[24:27], v[174:177], v[198:201], v[24:27]
	v_mfma_f32_16x16x32_bf16 v[20:23], v[150:153], v[206:209], v[20:23]
	v_mfma_f32_16x16x32_bf16 v[12:15], v[174:177], v[206:209], v[12:15]
	s_barrier
	s_add_u32 s44, s44, 0x40080
	s_addc_u32 s45, s45, 0
	s_add_i32 s48, s48, s7
	v_lshl_add_u64 v[140:141], s[44:45], 0, v[132:133]
	s_mov_b32 m0, s48
	s_nop 0
	global_load_lds_dwordx4 v[140:141], off
	v_lshl_add_u64 v[140:141], s[44:45], 0, v[128:129]
	s_add_i32 m0, s48, 0x2000
	s_nop 0
	global_load_lds_dwordx4 v[140:141], off
	s_waitcnt vmcnt(6)
	s_barrier
	v_mfma_f32_16x16x32_bf16 v[48:51], v[210:213], v[178:181], v[48:51]
	v_mfma_f32_16x16x32_bf16 v[40:43], v[232:235], v[178:181], v[40:43]
	v_mfma_f32_16x16x32_bf16 v[36:39], v[210:213], v[186:189], v[36:39]
	v_mfma_f32_16x16x32_bf16 v[28:31], v[232:235], v[186:189], v[28:31]
	v_mfma_f32_16x16x32_bf16 v[16:19], v[210:213], v[194:197], v[16:19]
	v_mfma_f32_16x16x32_bf16 v[8:11], v[232:235], v[194:197], v[8:11]
	v_mfma_f32_16x16x32_bf16 v[4:7], v[210:213], v[202:205], v[4:7]
	v_mfma_f32_16x16x32_bf16 v[0:3], v[232:235], v[202:205], v[0:3]
	v_mfma_f32_16x16x32_bf16 v[48:51], v[226:229], v[182:185], v[48:51]
	v_mfma_f32_16x16x32_bf16 v[40:43], v[236:239], v[182:185], v[40:43]
	v_mfma_f32_16x16x32_bf16 v[36:39], v[226:229], v[190:193], v[36:39]
	v_mfma_f32_16x16x32_bf16 v[28:31], v[236:239], v[190:193], v[28:31]
	v_mfma_f32_16x16x32_bf16 v[16:19], v[226:229], v[198:201], v[16:19]
	v_mfma_f32_16x16x32_bf16 v[8:11], v[236:239], v[198:201], v[8:11]
	v_mfma_f32_16x16x32_bf16 v[4:7], v[226:229], v[206:209], v[4:7]
	v_mfma_f32_16x16x32_bf16 v[0:3], v[236:239], v[206:209], v[0:3]
	s_add_i32 s73, s73, 2
	s_add_u32 s42, s42, 0x100
	s_addc_u32 s43, s43, 0
	s_add_u32 s52, s52, 0x100
	s_addc_u32 s72, s72, 0
	s_cmp_gt_u32 s73, 13
	s_barrier
	s_cbranch_scc0 .LBB0_968
	s_cmp_lt_u32 s101, 0x100
	s_cbranch_scc0 .Lxa_8
	s_barrier

; #define PG8_STAGE(bufoff, gbase, voff) do { _Pragma("unroll") for (int _i = 0; _i < 2; ++_i) \
;     __builtin_amdgcn_global_load_lds((const unsigned*)((const char*)(gbase) + (voff)[_i]), (LAS unsigned*)(lds + (bufoff) + ldsw + _i * 8192), 16, 0, 0); } while (0)
; #define PG8_LDA(dst, b, h) do { _Pragma("unroll") for (int m = 0; m < 4; ++m) _Pragma("unroll") for (int k = 0; k < 2; ++k) dst[m][k] = *(const LAS bf16x8*)(lds + PG8_SA(b, h) + aoff + m * 2048 + k * 1024); } while (0)
; #define PG8_LDB(dst, b, h) do { _Pragma("unroll") for (int n = 0; n < 2; ++n) _Pragma("unroll") for (int k = 0; k < 2; ++k) dst[n][k] = *(const LAS bf16x8*)(lds + PG8_SB(b, h) + boff + n * 2048 + k * 1024); } while (0)
; #define PG8_MMA(ai, bj, At, Bt) do { __builtin_amdgcn_s_setprio(1); _Pragma("unroll") for (int m = 0; m < 4; ++m) _Pragma("unroll") for (int n = 0; n < 2; ++n) _Pragma("unroll") for (int k = 0; k < 2; ++k) \
;     acc[ai][bj][m][n] = __builtin_amdgcn_mfma_f32_16x16x32_bf16(Bt[n][k], At[m][k], acc[ai][bj][m][n], 0, 0, 0); __builtin_amdgcn_s_setprio(0); } while (0)
; #define PG8_WAIT_L(n) asm volatile("s_waitcnt lgkmcnt(" #n ")" ::: "memory")
; #define PG8_BAR __builtin_amdgcn_s_barrier()
; #define PG8_SCHED __builtin_amdgcn_sched_barrier(0)
; template <class Epi, class Sched>
; __device__ __forceinline__ void gemm_phase(LAS unsigned char* lds, const Gemm g, const Sched& S, const Epi& E) {
;     ...
;       const bool last = (t == nt - 2);
;       const char* a1 = cA + (size_t)(t + 1) * kstep;
;       const char* a2 = last ? nA : cA + (size_t)(t + 2) * kstep; const char* b2 = last ? nB : cB + (size_t)(t + 2) * kstep;
;       const char* a3 = a2 + kstep; const char* b3 = b2 + kstep;
;       if (last && has_next) S.a_ready(nxt);
;       PG8_LDB(B0, 0, 0); PG8_SCHED; PG8_LDA(At, 0, 0); PG8_STAGE(PG8_SA(1, 1), a1 + hstep, voffA);
;       PG8_WAIT_L(8); PG8_BAR; PG8_WAIT_L(0); PG8_MMA(0, 0, At, B0); PG8_BAR; PG8_SCHED;
;       PG8_LDB(B1, 0, 1); PG8_STAGE(PG8_SB(0, 0), b2, voffB);
;       PG8_BAR; PG8_WAIT_L(0); PG8_MMA(0, 1, At, B1); PG8_BAR;
;       PG8_LDA(At, 0, 1); PG8_STAGE(PG8_SA(0, 0), a2, voffA);
;       PG8_BAR; PG8_WAIT_L(0); PG8_MMA(1, 0, At, B0); PG8_BAR; PG8_SCHED;
.Lxs_e10:
.LBB0_1142:
	s_add_u32 s44, s42, 0xfffc0080
	s_addc_u32 s45, s43, -1
	s_add_i32 s74, 0, 0x10000
	v_add_u32_e32 v151, s74, v141
	ds_read_b128 v[152:155], v151
	ds_read_b128 v[156:159], v151 offset:1024
	ds_read_b128 v[174:177], v151 offset:2048
	ds_read_b128 v[178:181], v151 offset:3072
	s_cmp_eq_u32 s73, 12
	s_cselect_b32 s49, s35, s45
	s_cselect_b32 s48, s71, s44
	s_cselect_b32 s45, s23, s72
	s_cselect_b32 s44, vcc_lo, s52
	v_lshl_add_u64 v[222:223], s[42:43], 0, v[136:137]
	s_add_i32 m0, s12, 0xc000
	ds_read_b128 v[182:185], v150
	ds_read_b128 v[186:189], v150 offset:1024
	ds_read_b128 v[190:193], v150 offset:2048
	ds_read_b128 v[194:197], v150 offset:3072
	ds_read_b128 v[198:201], v150 offset:4096
	ds_read_b128 v[202:205], v150 offset:5120
	ds_read_b128 v[206:209], v150 offset:6144
	ds_read_b128 v[210:213], v150 offset:7168
	global_load_lds_dwordx4 v[222:223], off
	v_lshl_add_u64 v[222:223], s[42:43], 0, v[138:139]
	s_add_i32 m0, s12, 0xe000
	s_nop 0
	global_load_lds_dwordx4 v[222:223], off
	s_waitcnt lgkmcnt(8)
	s_barrier
	s_waitcnt lgkmcnt(0)
	s_waitcnt lgkmcnt(0)
	v_mfma_f32_16x16x32_bf16 v[124:127], v[152:155], v[182:185], v[124:127]
	v_mfma_f32_16x16x32_bf16 v[116:119], v[174:177], v[182:185], v[116:119]
	v_mfma_f32_16x16x32_bf16 v[108:111], v[152:155], v[190:193], v[108:111]
	v_mfma_f32_16x16x32_bf16 v[100:103], v[174:177], v[190:193], v[100:103]
	v_mfma_f32_16x16x32_bf16 v[92:95], v[152:155], v[198:201], v[92:95]
	v_mfma_f32_16x16x32_bf16 v[84:87], v[174:177], v[198:201], v[84:87]
	v_mfma_f32_16x16x32_bf16 v[76:79], v[152:155], v[206:209], v[76:79]
	v_mfma_f32_16x16x32_bf16 v[68:71], v[174:177], v[206:209], v[68:71]
	v_mfma_f32_16x16x32_bf16 v[124:127], v[156:159], v[186:189], v[124:127]
	v_mfma_f32_16x16x32_bf16 v[116:119], v[178:181], v[186:189], v[116:119]
	v_mfma_f32_16x16x32_bf16 v[108:111], v[156:159], v[194:197], v[108:111]
	v_mfma_f32_16x16x32_bf16 v[100:103], v[178:181], v[194:197], v[100:103]
	v_mfma_f32_16x16x32_bf16 v[92:95], v[156:159], v[202:205], v[92:95]
	v_mfma_f32_16x16x32_bf16 v[84:87], v[178:181], v[202:205], v[84:87]
	v_mfma_f32_16x16x32_bf16 v[76:79], v[156:159], v[210:213], v[76:79]
	v_mfma_f32_16x16x32_bf16 v[68:71], v[178:181], v[210:213], v[68:71]
	s_barrier
	s_add_i32 s76, 0, 0x14000
	s_add_i32 s74, s74, s7
	v_add_u32_e32 v151, s76, v141
	v_lshl_add_u64 v[222:223], s[44:45], 0, v[132:133]
	s_mov_b32 m0, s74
	ds_read_b128 v[226:229], v151
	ds_read_b128 v[232:235], v151 offset:1024
	ds_read_b128 v[236:239], v151 offset:2048
	ds_read_b128 v[240:243], v151 offset:3072
	global_load_lds_dwordx4 v[222:223], off
	v_lshl_add_u64 v[244:245], s[44:45], 0, v[128:129]
	s_add_i32 m0, s74, 0x2000
	s_nop 0
	global_load_lds_dwordx4 v[244:245], off
	s_barrier
	s_waitcnt lgkmcnt(0)
	s_waitcnt lgkmcnt(0)
	v_mfma_f32_16x16x32_bf16 v[120:123], v[226:229], v[182:185], v[120:123]
	v_mfma_f32_16x16x32_bf16 v[112:115], v[236:239], v[182:185], v[112:115]
	v_mfma_f32_16x16x32_bf16 v[104:107], v[226:229], v[190:193], v[104:107]
	v_mfma_f32_16x16x32_bf16 v[96:99], v[236:239], v[190:193], v[96:99]
	v_mfma_f32_16x16x32_bf16 v[88:91], v[226:229], v[198:201], v[88:91]
	v_mfma_f32_16x16x32_bf16 v[80:83], v[236:239], v[198:201], v[80:83]
	v_mfma_f32_16x16x32_bf16 v[72:75], v[226:229], v[206:209], v[72:75]
	v_mfma_f32_16x16x32_bf16 v[64:67], v[236:239], v[206:209], v[64:67]
	v_mfma_f32_16x16x32_bf16 v[120:123], v[232:235], v[186:189], v[120:123]
	v_mfma_f32_16x16x32_bf16 v[112:115], v[240:243], v[186:189], v[112:115]
	v_mfma_f32_16x16x32_bf16 v[104:107], v[232:235], v[194:197], v[104:107]
	v_mfma_f32_16x16x32_bf16 v[96:99], v[240:243], v[194:197], v[96:99]
	v_mfma_f32_16x16x32_bf16 v[88:91], v[232:235], v[202:205], v[88:91]
	v_mfma_f32_16x16x32_bf16 v[80:83], v[240:243], v[202:205], v[80:83]
	v_mfma_f32_16x16x32_bf16 v[72:75], v[232:235], v[210:213], v[72:75]
	v_mfma_f32_16x16x32_bf16 v[64:67], v[240:243], v[210:213], v[64:67]
	s_mov_b32 m0, s12
	v_lshl_add_u64 v[246:247], s[48:49], 0, v[134:135]
	s_barrier
	ds_read_b128 v[182:185], v150 offset:16384
	ds_read_b128 v[186:189], v150 offset:17408
	ds_read_b128 v[190:193], v150 offset:18432
	ds_read_b128 v[194:197], v150 offset:19456
	ds_read_b128 v[198:201], v150 offset:20480
	ds_read_b128 v[202:205], v150 offset:21504
	ds_read_b128 v[206:209], v150 offset:22528
	ds_read_b128 v[210:213], v150 offset:23552
	global_load_lds_dwordx4 v[246:247], off
	v_lshl_add_u64 v[248:249], s[48:49], 0, v[130:131]
	s_mov_b32 m0, s13
	s_nop 0
	global_load_lds_dwordx4 v[248:249], off
	s_barrier
	s_waitcnt lgkmcnt(0)
	s_waitcnt lgkmcnt(0)
	v_mfma_f32_16x16x32_bf16 v[60:63], v[152:155], v[182:185], v[60:63]
	v_mfma_f32_16x16x32_bf16 v[52:55], v[174:177], v[182:185], v[52:55]
	v_mfma_f32_16x16x32_bf16 v[44:47], v[152:155], v[190:193], v[44:47]
	v_mfma_f32_16x16x32_bf16 v[36:39], v[174:177], v[190:193], v[36:39]
	v_mfma_f32_16x16x32_bf16 v[28:31], v[152:155], v[198:201], v[28:31]
	v_mfma_f32_16x16x32_bf16 v[20:23], v[174:177], v[198:201], v[20:23]
	v_mfma_f32_16x16x32_bf16 v[12:15], v[152:155], v[206:209], v[12:15]
	v_mfma_f32_16x16x32_bf16 v[4:7], v[174:177], v[206:209], v[4:7]
	v_mfma_f32_16x16x32_bf16 v[60:63], v[156:159], v[186:189], v[60:63]
	v_mfma_f32_16x16x32_bf16 v[52:55], v[178:181], v[186:189], v[52:55]
	v_mfma_f32_16x16x32_bf16 v[44:47], v[156:159], v[194:197], v[44:47]
	v_mfma_f32_16x16x32_bf16 v[36:39], v[178:181], v[194:197], v[36:39]
	v_mfma_f32_16x16x32_bf16 v[28:31], v[156:159], v[202:205], v[28:31]
	v_mfma_f32_16x16x32_bf16 v[20:23], v[178:181], v[202:205], v[20:23]
	v_mfma_f32_16x16x32_bf16 v[12:15], v[156:159], v[210:213], v[12:15]
	v_mfma_f32_16x16x32_bf16 v[4:7], v[178:181], v[210:213], v[4:7]
	s_barrier
; #define PG8_STAGE(bufoff, gbase, voff) do { _Pragma("unroll") for (int _i = 0; _i < 2; ++_i) \
;     __builtin_amdgcn_global_load_lds((const unsigned*)((const char*)(gbase) + (voff)[_i]), (LAS unsigned*)(lds + (bufoff) + ldsw + _i * 8192), 16, 0, 0); } while (0)
; #define PG8_LDA(dst, b, h) do { _Pragma("unroll") for (int m = 0; m < 4; ++m) _Pragma("unroll") for (int k = 0; k < 2; ++k) dst[m][k] = *(const LAS bf16x8*)(lds + PG8_SA(b, h) + aoff + m * 2048 + k * 1024); } while (0)
; #define PG8_LDB(dst, b, h) do { _Pragma("unroll") for (int n = 0; n < 2; ++n) _Pragma("unroll") for (int k = 0; k < 2; ++k) dst[n][k] = *(const LAS bf16x8*)(lds + PG8_SB(b, h) + boff + n * 2048 + k * 1024); } while (0)
; #define PG8_MMA(ai, bj, At, Bt) do { __builtin_amdgcn_s_setprio(1); _Pragma("unroll") for (int m = 0; m < 4; ++m) _Pragma("unroll") for (int n = 0; n < 2; ++n) _Pragma("unroll") for (int k = 0; k < 2; ++k) \
;     acc[ai][bj][m][n] = __builtin_amdgcn_mfma_f32_16x16x32_bf16(Bt[n][k], At[m][k], acc[ai][bj][m][n], 0, 0, 0); __builtin_amdgcn_s_setprio(0); } while (0)
; #define PG8_WAIT_V(n) asm volatile("s_waitcnt vmcnt(" #n ")" ::: "memory")
; #define PG8_WAIT_L(n) asm volatile("s_waitcnt lgkmcnt(" #n ")" ::: "memory")
; #define PG8_BAR __builtin_amdgcn_s_barrier()
; #define PG8_SCHED __builtin_amdgcn_sched_barrier(0)
; template <class Epi, class Sched>
; __device__ __forceinline__ void gemm_phase(LAS unsigned char* lds, const Gemm g, const Sched& S, const Epi& E) {
;     ...
;       PG8_STAGE(PG8_SB(0, 1), b2 + hstep, voffB);
;       PG8_WAIT_V(6); PG8_BAR; PG8_MMA(1, 1, At, B1); PG8_BAR;
;       PG8_LDB(B0, 1, 0); PG8_SCHED; PG8_LDA(At, 1, 0); PG8_STAGE(PG8_SA(0, 1), a2 + hstep, voffA);
;       PG8_WAIT_L(8); PG8_BAR; PG8_WAIT_L(0); PG8_MMA(0, 0, At, B0); PG8_BAR; PG8_SCHED;
;       PG8_LDB(B1, 1, 1); PG8_STAGE(PG8_SB(1, 0), b3, voffB);
;       PG8_BAR; PG8_WAIT_L(0); PG8_MMA(0, 1, At, B1); PG8_BAR;
	s_add_u32 s74, s44, 0x40000
	s_addc_u32 s75, s45, 0
	s_add_i32 s76, s76, s7
	v_lshl_add_u64 v[152:153], s[74:75], 0, v[132:133]
	s_mov_b32 m0, s76
	s_nop 0
	global_load_lds_dwordx4 v[152:153], off
	v_lshl_add_u64 v[152:153], s[74:75], 0, v[128:129]
	s_add_i32 m0, s76, 0x2000
	s_nop 0
	global_load_lds_dwordx4 v[152:153], off
	s_waitcnt vmcnt(6)
	s_barrier
	v_mfma_f32_16x16x32_bf16 v[56:59], v[226:229], v[182:185], v[56:59]
	v_mfma_f32_16x16x32_bf16 v[48:51], v[236:239], v[182:185], v[48:51]
	v_mfma_f32_16x16x32_bf16 v[40:43], v[226:229], v[190:193], v[40:43]
	v_mfma_f32_16x16x32_bf16 v[32:35], v[236:239], v[190:193], v[32:35]
	v_mfma_f32_16x16x32_bf16 v[24:27], v[226:229], v[198:201], v[24:27]
	v_mfma_f32_16x16x32_bf16 v[16:19], v[236:239], v[198:201], v[16:19]
	v_mfma_f32_16x16x32_bf16 v[8:11], v[226:229], v[206:209], v[8:11]
	v_mfma_f32_16x16x32_bf16 v[0:3], v[236:239], v[206:209], v[0:3]
	v_mfma_f32_16x16x32_bf16 v[56:59], v[232:235], v[186:189], v[56:59]
	v_mfma_f32_16x16x32_bf16 v[48:51], v[240:243], v[186:189], v[48:51]
	v_mfma_f32_16x16x32_bf16 v[40:43], v[232:235], v[194:197], v[40:43]
	v_mfma_f32_16x16x32_bf16 v[32:35], v[240:243], v[194:197], v[32:35]
	v_mfma_f32_16x16x32_bf16 v[24:27], v[232:235], v[202:205], v[24:27]
	v_mfma_f32_16x16x32_bf16 v[16:19], v[240:243], v[202:205], v[16:19]
	v_mfma_f32_16x16x32_bf16 v[8:11], v[232:235], v[210:213], v[8:11]
	v_mfma_f32_16x16x32_bf16 v[0:3], v[240:243], v[210:213], v[0:3]
	s_add_i32 s74, 0, 0x18000
	v_add_u32_e32 v151, s74, v141
	s_barrier
	ds_read_b128 v[152:155], v151
	ds_read_b128 v[156:159], v151 offset:1024
	ds_read_b128 v[174:177], v151 offset:2048
	ds_read_b128 v[178:181], v151 offset:3072
	s_add_u32 s48, s48, 0x40000
	s_addc_u32 s49, s49, 0
	s_mov_b32 m0, s51
	v_lshl_add_u64 v[226:227], s[48:49], 0, v[134:135]
	ds_read_b128 v[182:185], v150 offset:32768
	ds_read_b128 v[186:189], v150 offset:33792
	ds_read_b128 v[190:193], v150 offset:34816
	ds_read_b128 v[194:197], v150 offset:35840
	ds_read_b128 v[198:201], v150 offset:36864
	ds_read_b128 v[202:205], v150 offset:37888
	ds_read_b128 v[206:209], v150 offset:38912
	ds_read_b128 v[210:213], v150 offset:39936
	global_load_lds_dwordx4 v[226:227], off
	v_lshl_add_u64 v[226:227], s[48:49], 0, v[130:131]
	s_mov_b32 m0, s62
	s_nop 0
	global_load_lds_dwordx4 v[226:227], off
	s_waitcnt lgkmcnt(8)
	s_barrier
	s_waitcnt lgkmcnt(0)
	s_waitcnt lgkmcnt(0)
	v_mfma_f32_16x16x32_bf16 v[124:127], v[152:155], v[182:185], v[124:127]
	v_mfma_f32_16x16x32_bf16 v[116:119], v[174:177], v[182:185], v[116:119]
	v_mfma_f32_16x16x32_bf16 v[108:111], v[152:155], v[190:193], v[108:111]
	v_mfma_f32_16x16x32_bf16 v[100:103], v[174:177], v[190:193], v[100:103]
	v_mfma_f32_16x16x32_bf16 v[92:95], v[152:155], v[198:201], v[92:95]
	v_mfma_f32_16x16x32_bf16 v[84:87], v[174:177], v[198:201], v[84:87]
	v_mfma_f32_16x16x32_bf16 v[76:79], v[152:155], v[206:209], v[76:79]
	v_mfma_f32_16x16x32_bf16 v[68:71], v[174:177], v[206:209], v[68:71]
	v_mfma_f32_16x16x32_bf16 v[124:127], v[156:159], v[186:189], v[124:127]
	v_mfma_f32_16x16x32_bf16 v[116:119], v[178:181], v[186:189], v[116:119]
	v_mfma_f32_16x16x32_bf16 v[108:111], v[156:159], v[194:197], v[108:111]
	v_mfma_f32_16x16x32_bf16 v[100:103], v[178:181], v[194:197], v[100:103]
	v_mfma_f32_16x16x32_bf16 v[92:95], v[156:159], v[202:205], v[92:95]
	v_mfma_f32_16x16x32_bf16 v[84:87], v[178:181], v[202:205], v[84:87]
	v_mfma_f32_16x16x32_bf16 v[76:79], v[156:159], v[210:213], v[76:79]
	v_mfma_f32_16x16x32_bf16 v[68:71], v[178:181], v[210:213], v[68:71]
	s_barrier
	s_add_i32 s48, 0, 0x1c000
	s_add_i32 s49, s74, s7
	v_add_u32_e32 v151, s48, v141
	v_lshl_add_u64 v[222:223], v[222:223], 0, s[80:81]
	s_mov_b32 m0, s49
	ds_read_b128 v[226:229], v151
	ds_read_b128 v[232:235], v151 offset:1024
	ds_read_b128 v[236:239], v151 offset:2048
	ds_read_b128 v[240:243], v151 offset:3072
	global_load_lds_dwordx4 v[222:223], off
	v_lshl_add_u64 v[222:223], v[244:245], 0, s[80:81]
	s_add_i32 m0, s49, 0x2000
	s_nop 0
	global_load_lds_dwordx4 v[222:223], off
	s_barrier
; #define PG8_STAGE(bufoff, gbase, voff) do { _Pragma("unroll") for (int _i = 0; _i < 2; ++_i) \
;     __builtin_amdgcn_global_load_lds((const unsigned*)((const char*)(gbase) + (voff)[_i]), (LAS unsigned*)(lds + (bufoff) + ldsw + _i * 8192), 16, 0, 0); } while (0)
; #define PG8_LDA(dst, b, h) do { _Pragma("unroll") for (int m = 0; m < 4; ++m) _Pragma("unroll") for (int k = 0; k < 2; ++k) dst[m][k] = *(const LAS bf16x8*)(lds + PG8_SA(b, h) + aoff + m * 2048 + k * 1024); } while (0)
; #define PG8_MMA(ai, bj, At, Bt) do { __builtin_amdgcn_s_setprio(1); _Pragma("unroll") for (int m = 0; m < 4; ++m) _Pragma("unroll") for (int n = 0; n < 2; ++n) _Pragma("unroll") for (int k = 0; k < 2; ++k) \
;     acc[ai][bj][m][n] = __builtin_amdgcn_mfma_f32_16x16x32_bf16(Bt[n][k], At[m][k], acc[ai][bj][m][n], 0, 0, 0); __builtin_amdgcn_s_setprio(0); } while (0)
; #define PG8_WAIT_V(n) asm volatile("s_waitcnt vmcnt(" #n ")" ::: "memory")
; #define PG8_WAIT_L(n) asm volatile("s_waitcnt lgkmcnt(" #n ")" ::: "memory")
; #define PG8_BAR __builtin_amdgcn_s_barrier()
; #define PG8_SCHED __builtin_amdgcn_sched_barrier(0)
; template <class Epi, class Sched>
; __device__ __forceinline__ void gemm_phase(LAS unsigned char* lds, const Gemm g, const Sched& S, const Epi& E) {
;     ...
;       PG8_BAR; PG8_WAIT_L(0); PG8_MMA(0, 1, At, B1); PG8_BAR;
;       PG8_LDA(At, 1, 1); PG8_STAGE(PG8_SA(1, 0), a3, voffA);
;       PG8_BAR; PG8_WAIT_L(0); PG8_MMA(1, 0, At, B0); PG8_BAR; PG8_SCHED;
;       PG8_STAGE(PG8_SB(1, 1), b3 + hstep, voffB);
;       PG8_WAIT_V(6); PG8_BAR; PG8_MMA(1, 1, At, B1); PG8_BAR;
;     }
	s_waitcnt lgkmcnt(0)
	s_waitcnt lgkmcnt(0)
	v_mfma_f32_16x16x32_bf16 v[120:123], v[226:229], v[182:185], v[120:123]
	v_mfma_f32_16x16x32_bf16 v[112:115], v[236:239], v[182:185], v[112:115]
	v_mfma_f32_16x16x32_bf16 v[104:107], v[226:229], v[190:193], v[104:107]
	v_mfma_f32_16x16x32_bf16 v[96:99], v[236:239], v[190:193], v[96:99]
	v_mfma_f32_16x16x32_bf16 v[88:91], v[226:229], v[198:201], v[88:91]
	v_mfma_f32_16x16x32_bf16 v[80:83], v[236:239], v[198:201], v[80:83]
	v_mfma_f32_16x16x32_bf16 v[72:75], v[226:229], v[206:209], v[72:75]
	v_mfma_f32_16x16x32_bf16 v[64:67], v[236:239], v[206:209], v[64:67]
	v_mfma_f32_16x16x32_bf16 v[120:123], v[232:235], v[186:189], v[120:123]
	v_mfma_f32_16x16x32_bf16 v[112:115], v[240:243], v[186:189], v[112:115]
	v_mfma_f32_16x16x32_bf16 v[104:107], v[232:235], v[194:197], v[104:107]
	v_mfma_f32_16x16x32_bf16 v[96:99], v[240:243], v[194:197], v[96:99]
	v_mfma_f32_16x16x32_bf16 v[88:91], v[232:235], v[202:205], v[88:91]
	v_mfma_f32_16x16x32_bf16 v[80:83], v[240:243], v[202:205], v[80:83]
	v_mfma_f32_16x16x32_bf16 v[72:75], v[232:235], v[210:213], v[72:75]
	v_mfma_f32_16x16x32_bf16 v[64:67], v[240:243], v[210:213], v[64:67]
	s_mov_b32 m0, s63
	v_lshl_add_u64 v[222:223], v[246:247], 0, s[80:81]
	s_barrier
	ds_read_b128 v[182:185], v150 offset:49152
	ds_read_b128 v[186:189], v150 offset:50176
	ds_read_b128 v[190:193], v150 offset:51200
	ds_read_b128 v[194:197], v150 offset:52224
	ds_read_b128 v[198:201], v150 offset:53248
	ds_read_b128 v[202:205], v150 offset:54272
	ds_read_b128 v[206:209], v150 offset:55296
	ds_read_b128 v[210:213], v150 offset:56320
	global_load_lds_dwordx4 v[222:223], off
	v_lshl_add_u64 v[222:223], v[248:249], 0, s[80:81]
	s_mov_b32 m0, s64
	s_nop 0
	global_load_lds_dwordx4 v[222:223], off
	s_barrier
	s_waitcnt lgkmcnt(0)
	s_waitcnt lgkmcnt(0)
	v_mfma_f32_16x16x32_bf16 v[60:63], v[152:155], v[182:185], v[60:63]
	v_mfma_f32_16x16x32_bf16 v[52:55], v[174:177], v[182:185], v[52:55]
	v_mfma_f32_16x16x32_bf16 v[44:47], v[152:155], v[190:193], v[44:47]
	v_mfma_f32_16x16x32_bf16 v[36:39], v[174:177], v[190:193], v[36:39]
	v_mfma_f32_16x16x32_bf16 v[28:31], v[152:155], v[198:201], v[28:31]
	v_mfma_f32_16x16x32_bf16 v[20:23], v[174:177], v[198:201], v[20:23]
	v_mfma_f32_16x16x32_bf16 v[12:15], v[152:155], v[206:209], v[12:15]
	v_mfma_f32_16x16x32_bf16 v[4:7], v[174:177], v[206:209], v[4:7]
	v_mfma_f32_16x16x32_bf16 v[60:63], v[156:159], v[186:189], v[60:63]
	v_mfma_f32_16x16x32_bf16 v[52:55], v[178:181], v[186:189], v[52:55]
	v_mfma_f32_16x16x32_bf16 v[44:47], v[156:159], v[194:197], v[44:47]
	v_mfma_f32_16x16x32_bf16 v[36:39], v[178:181], v[194:197], v[36:39]
	v_mfma_f32_16x16x32_bf16 v[28:31], v[156:159], v[202:205], v[28:31]
	v_mfma_f32_16x16x32_bf16 v[20:23], v[178:181], v[202:205], v[20:23]
	v_mfma_f32_16x16x32_bf16 v[12:15], v[156:159], v[210:213], v[12:15]
	v_mfma_f32_16x16x32_bf16 v[4:7], v[178:181], v[210:213], v[4:7]
	s_barrier
	s_add_u32 s44, s44, 0x40080
	s_addc_u32 s45, s45, 0
	s_add_i32 s48, s48, s7
	v_lshl_add_u64 v[152:153], s[44:45], 0, v[132:133]
	s_mov_b32 m0, s48
	s_nop 0
	global_load_lds_dwordx4 v[152:153], off
	v_lshl_add_u64 v[152:153], s[44:45], 0, v[128:129]
	s_add_i32 m0, s48, 0x2000
	s_nop 0
	global_load_lds_dwordx4 v[152:153], off
	s_waitcnt vmcnt(6)
	s_barrier
	v_mfma_f32_16x16x32_bf16 v[56:59], v[226:229], v[182:185], v[56:59]
	v_mfma_f32_16x16x32_bf16 v[48:51], v[236:239], v[182:185], v[48:51]
	v_mfma_f32_16x16x32_bf16 v[40:43], v[226:229], v[190:193], v[40:43]
	v_mfma_f32_16x16x32_bf16 v[32:35], v[236:239], v[190:193], v[32:35]
	v_mfma_f32_16x16x32_bf16 v[24:27], v[226:229], v[198:201], v[24:27]
	v_mfma_f32_16x16x32_bf16 v[16:19], v[236:239], v[198:201], v[16:19]
	v_mfma_f32_16x16x32_bf16 v[8:11], v[226:229], v[206:209], v[8:11]
	v_mfma_f32_16x16x32_bf16 v[0:3], v[236:239], v[206:209], v[0:3]
	v_mfma_f32_16x16x32_bf16 v[56:59], v[232:235], v[186:189], v[56:59]
	v_mfma_f32_16x16x32_bf16 v[48:51], v[240:243], v[186:189], v[48:51]
	v_mfma_f32_16x16x32_bf16 v[40:43], v[232:235], v[194:197], v[40:43]
	v_mfma_f32_16x16x32_bf16 v[32:35], v[240:243], v[194:197], v[32:35]
	v_mfma_f32_16x16x32_bf16 v[24:27], v[232:235], v[202:205], v[24:27]
	v_mfma_f32_16x16x32_bf16 v[16:19], v[240:243], v[202:205], v[16:19]
	v_mfma_f32_16x16x32_bf16 v[8:11], v[232:235], v[210:213], v[8:11]
	v_mfma_f32_16x16x32_bf16 v[0:3], v[240:243], v[210:213], v[0:3]
	s_add_i32 s73, s73, 2
	s_add_u32 s42, s42, 0x100
	s_addc_u32 s43, s43, 0
	s_add_u32 s52, s52, 0x100
	s_addc_u32 s72, s72, 0
	s_cmp_gt_u32 s73, 13
	s_barrier
	s_cbranch_scc0 .LBB0_1142
	s_cmp_lt_u32 s101, 0x100
	s_cbranch_scc0 .Lxa_10
	s_barrier

; #define PG8_STAGE(bufoff, gbase, voff) do { _Pragma("unroll") for (int _i = 0; _i < 2; ++_i) \
;     __builtin_amdgcn_global_load_lds((const unsigned*)((const char*)(gbase) + (voff)[_i]), (LAS unsigned*)(lds + (bufoff) + ldsw + _i * 8192), 16, 0, 0); } while (0)
; #define PG8_LDA(dst, b, h) do { _Pragma("unroll") for (int m = 0; m < 4; ++m) _Pragma("unroll") for (int k = 0; k < 2; ++k) dst[m][k] = *(const LAS bf16x8*)(lds + PG8_SA(b, h) + aoff + m * 2048 + k * 1024); } while (0)
; #define PG8_LDB(dst, b, h) do { _Pragma("unroll") for (int n = 0; n < 2; ++n) _Pragma("unroll") for (int k = 0; k < 2; ++k) dst[n][k] = *(const LAS bf16x8*)(lds + PG8_SB(b, h) + boff + n * 2048 + k * 1024); } while (0)
; #define PG8_MMA(ai, bj, At, Bt) do { __builtin_amdgcn_s_setprio(1); _Pragma("unroll") for (int m = 0; m < 4; ++m) _Pragma("unroll") for (int n = 0; n < 2; ++n) _Pragma("unroll") for (int k = 0; k < 2; ++k) \
;     acc[ai][bj][m][n] = __builtin_amdgcn_mfma_f32_16x16x32_bf16(Bt[n][k], At[m][k], acc[ai][bj][m][n], 0, 0, 0); __builtin_amdgcn_s_setprio(0); } while (0)
; #define PG8_WAIT_L(n) asm volatile("s_waitcnt lgkmcnt(" #n ")" ::: "memory")
; #define PG8_BAR __builtin_amdgcn_s_barrier()
; #define PG8_SCHED __builtin_amdgcn_sched_barrier(0)
; template <class Epi, class Sched>
; __device__ __forceinline__ void gemm_phase(LAS unsigned char* lds, const Gemm g, const Sched& S, const Epi& E) {
;     ...
;       const bool last = (t == nt - 2);
;       const char* a1 = cA + (size_t)(t + 1) * kstep;
;       const char* a2 = last ? nA : cA + (size_t)(t + 2) * kstep; const char* b2 = last ? nB : cB + (size_t)(t + 2) * kstep;
;       const char* a3 = a2 + kstep; const char* b3 = b2 + kstep;
;       if (last && has_next) S.a_ready(nxt);
;       PG8_LDB(B0, 0, 0); PG8_SCHED; PG8_LDA(At, 0, 0); PG8_STAGE(PG8_SA(1, 1), a1 + hstep, voffA);
;       PG8_WAIT_L(8); PG8_BAR; PG8_WAIT_L(0); PG8_MMA(0, 0, At, B0); PG8_BAR; PG8_SCHED;
;       PG8_LDB(B1, 0, 1); PG8_STAGE(PG8_SB(0, 0), b2, voffB);
;       PG8_BAR; PG8_WAIT_L(0); PG8_MMA(0, 1, At, B1); PG8_BAR;
;       PG8_LDA(At, 0, 1); PG8_STAGE(PG8_SA(0, 0), a2, voffA);
;       PG8_BAR; PG8_WAIT_L(0); PG8_MMA(1, 0, At, B0); PG8_BAR; PG8_SCHED;
.Lxs_e11:
.LBB0_1215:
	s_add_u32 s42, s34, 0x100
	s_addc_u32 s43, s35, 0
	s_add_i32 s74, 0, 0x10000
	v_add_u32_e32 v140, s74, v202
	ds_read_b128 v[128:131], v140
	ds_read_b128 v[132:135], v140 offset:1024
	ds_read_b128 v[136:139], v140 offset:2048
	ds_read_b128 v[140:143], v140 offset:3072
	s_cmp_eq_u32 s73, 40
	s_cselect_b32 s49, s23, s43
	s_cselect_b32 s48, s22, s42
	s_cselect_b32 s45, s41, s72
	s_cselect_b32 s44, s40, s52
	v_lshl_add_u64 v[208:209], s[34:35], 0, v[182:183]
	s_add_i32 m0, s51, 0xc000
	ds_read_b128 v[144:147], v203
	ds_read_b128 v[148:151], v203 offset:1024
	ds_read_b128 v[152:155], v203 offset:2048
	ds_read_b128 v[186:189], v203 offset:3072
	ds_read_b128 v[190:193], v203 offset:4096
	ds_read_b128 v[194:197], v203 offset:5120
	ds_read_b128 v[198:201], v203 offset:6144
	ds_read_b128 v[204:207], v203 offset:7168
	global_load_lds_dwordx4 v[208:209], off
	v_lshl_add_u64 v[208:209], s[34:35], 0, v[184:185]
	s_add_i32 m0, s51, 0xe000
	s_nop 0
	global_load_lds_dwordx4 v[208:209], off
	s_waitcnt lgkmcnt(8)
	s_barrier
	s_waitcnt lgkmcnt(0)
	s_waitcnt lgkmcnt(0)
	v_mfma_f32_16x16x32_bf16 v[124:127], v[128:131], v[144:147], v[124:127]
	v_mfma_f32_16x16x32_bf16 v[120:123], v[136:139], v[144:147], v[120:123]
	v_mfma_f32_16x16x32_bf16 v[108:111], v[128:131], v[152:155], v[108:111]
	v_mfma_f32_16x16x32_bf16 v[104:107], v[136:139], v[152:155], v[104:107]
	v_mfma_f32_16x16x32_bf16 v[92:95], v[128:131], v[190:193], v[92:95]
	v_mfma_f32_16x16x32_bf16 v[88:91], v[136:139], v[190:193], v[88:91]
	v_mfma_f32_16x16x32_bf16 v[76:79], v[128:131], v[198:201], v[76:79]
	v_mfma_f32_16x16x32_bf16 v[72:75], v[136:139], v[198:201], v[72:75]
	v_mfma_f32_16x16x32_bf16 v[124:127], v[132:135], v[148:151], v[124:127]
	v_mfma_f32_16x16x32_bf16 v[120:123], v[140:143], v[148:151], v[120:123]
	v_mfma_f32_16x16x32_bf16 v[108:111], v[132:135], v[186:189], v[108:111]
	v_mfma_f32_16x16x32_bf16 v[104:107], v[140:143], v[186:189], v[104:107]
	v_mfma_f32_16x16x32_bf16 v[92:95], v[132:135], v[194:197], v[92:95]
	v_mfma_f32_16x16x32_bf16 v[88:91], v[140:143], v[194:197], v[88:91]
	v_mfma_f32_16x16x32_bf16 v[76:79], v[132:135], v[204:207], v[76:79]
	v_mfma_f32_16x16x32_bf16 v[72:75], v[140:143], v[204:207], v[72:75]
	s_barrier
	s_add_i32 s75, 0, 0x14000
	s_add_i32 s34, s74, s7
	v_add_u32_e32 v160, s75, v202
	v_lshl_add_u64 v[212:213], s[44:45], 0, v[174:175]
	s_mov_b32 m0, s34
	ds_read_b128 v[208:211], v160
	ds_read_b128 v[226:229], v160 offset:1024
	ds_read_b128 v[232:235], v160 offset:2048
	ds_read_b128 v[236:239], v160 offset:3072
	global_load_lds_dwordx4 v[212:213], off
	v_lshl_add_u64 v[222:223], s[44:45], 0, v[156:157]
	s_add_i32 m0, s34, 0x2000
	s_nop 0
	global_load_lds_dwordx4 v[222:223], off
	s_barrier
	s_waitcnt lgkmcnt(0)
	s_waitcnt lgkmcnt(0)
	v_mfma_f32_16x16x32_bf16 v[116:119], v[208:211], v[144:147], v[116:119]
	v_mfma_f32_16x16x32_bf16 v[112:115], v[232:235], v[144:147], v[112:115]
	v_mfma_f32_16x16x32_bf16 v[100:103], v[208:211], v[152:155], v[100:103]
	v_mfma_f32_16x16x32_bf16 v[96:99], v[232:235], v[152:155], v[96:99]
	v_mfma_f32_16x16x32_bf16 v[84:87], v[208:211], v[190:193], v[84:87]
	v_mfma_f32_16x16x32_bf16 v[80:83], v[232:235], v[190:193], v[80:83]
	v_mfma_f32_16x16x32_bf16 v[68:71], v[208:211], v[198:201], v[68:71]
	v_mfma_f32_16x16x32_bf16 v[64:67], v[232:235], v[198:201], v[64:67]
	v_mfma_f32_16x16x32_bf16 v[116:119], v[226:229], v[148:151], v[116:119]
	v_mfma_f32_16x16x32_bf16 v[112:115], v[236:239], v[148:151], v[112:115]
	v_mfma_f32_16x16x32_bf16 v[100:103], v[226:229], v[186:189], v[100:103]
	v_mfma_f32_16x16x32_bf16 v[96:99], v[236:239], v[186:189], v[96:99]
	v_mfma_f32_16x16x32_bf16 v[84:87], v[226:229], v[194:197], v[84:87]
	v_mfma_f32_16x16x32_bf16 v[80:83], v[236:239], v[194:197], v[80:83]
	v_mfma_f32_16x16x32_bf16 v[68:71], v[226:229], v[204:207], v[68:71]
	v_mfma_f32_16x16x32_bf16 v[64:67], v[236:239], v[204:207], v[64:67]
	s_mov_b32 m0, s51
	v_lshl_add_u64 v[240:241], s[48:49], 0, v[176:177]
	s_barrier
	ds_read_b128 v[144:147], v203 offset:16384
	ds_read_b128 v[148:151], v203 offset:17408
	ds_read_b128 v[152:155], v203 offset:18432
	ds_read_b128 v[186:189], v203 offset:19456
	ds_read_b128 v[190:193], v203 offset:20480
	ds_read_b128 v[194:197], v203 offset:21504
	ds_read_b128 v[198:201], v203 offset:22528
	ds_read_b128 v[204:207], v203 offset:23552
	global_load_lds_dwordx4 v[240:241], off
	v_lshl_add_u64 v[242:243], s[48:49], 0, v[158:159]
	s_mov_b32 m0, s62
	s_nop 0
	global_load_lds_dwordx4 v[242:243], off
	s_barrier
	s_waitcnt lgkmcnt(0)
	s_waitcnt lgkmcnt(0)
	v_mfma_f32_16x16x32_bf16 v[60:63], v[128:131], v[144:147], v[60:63]
	v_mfma_f32_16x16x32_bf16 v[56:59], v[136:139], v[144:147], v[56:59]
	v_mfma_f32_16x16x32_bf16 v[44:47], v[128:131], v[152:155], v[44:47]
	v_mfma_f32_16x16x32_bf16 v[40:43], v[136:139], v[152:155], v[40:43]
	v_mfma_f32_16x16x32_bf16 v[28:31], v[128:131], v[190:193], v[28:31]
	v_mfma_f32_16x16x32_bf16 v[24:27], v[136:139], v[190:193], v[24:27]
	v_mfma_f32_16x16x32_bf16 v[12:15], v[128:131], v[198:201], v[12:15]
	v_mfma_f32_16x16x32_bf16 v[8:11], v[136:139], v[198:201], v[8:11]
	v_mfma_f32_16x16x32_bf16 v[60:63], v[132:135], v[148:151], v[60:63]
	v_mfma_f32_16x16x32_bf16 v[56:59], v[140:143], v[148:151], v[56:59]
	v_mfma_f32_16x16x32_bf16 v[44:47], v[132:135], v[186:189], v[44:47]
	v_mfma_f32_16x16x32_bf16 v[40:43], v[140:143], v[186:189], v[40:43]
	v_mfma_f32_16x16x32_bf16 v[28:31], v[132:135], v[194:197], v[28:31]
	v_mfma_f32_16x16x32_bf16 v[24:27], v[140:143], v[194:197], v[24:27]
	v_mfma_f32_16x16x32_bf16 v[12:15], v[132:135], v[204:207], v[12:15]
	v_mfma_f32_16x16x32_bf16 v[8:11], v[140:143], v[204:207], v[8:11]
	s_barrier
; #define PG8_STAGE(bufoff, gbase, voff) do { _Pragma("unroll") for (int _i = 0; _i < 2; ++_i) \
;     __builtin_amdgcn_global_load_lds((const unsigned*)((const char*)(gbase) + (voff)[_i]), (LAS unsigned*)(lds + (bufoff) + ldsw + _i * 8192), 16, 0, 0); } while (0)
; #define PG8_LDA(dst, b, h) do { _Pragma("unroll") for (int m = 0; m < 4; ++m) _Pragma("unroll") for (int k = 0; k < 2; ++k) dst[m][k] = *(const LAS bf16x8*)(lds + PG8_SA(b, h) + aoff + m * 2048 + k * 1024); } while (0)
; #define PG8_LDB(dst, b, h) do { _Pragma("unroll") for (int n = 0; n < 2; ++n) _Pragma("unroll") for (int k = 0; k < 2; ++k) dst[n][k] = *(const LAS bf16x8*)(lds + PG8_SB(b, h) + boff + n * 2048 + k * 1024); } while (0)
; #define PG8_MMA(ai, bj, At, Bt) do { __builtin_amdgcn_s_setprio(1); _Pragma("unroll") for (int m = 0; m < 4; ++m) _Pragma("unroll") for (int n = 0; n < 2; ++n) _Pragma("unroll") for (int k = 0; k < 2; ++k) \
;     acc[ai][bj][m][n] = __builtin_amdgcn_mfma_f32_16x16x32_bf16(Bt[n][k], At[m][k], acc[ai][bj][m][n], 0, 0, 0); __builtin_amdgcn_s_setprio(0); } while (0)
; #define PG8_WAIT_V(n) asm volatile("s_waitcnt vmcnt(" #n ")" ::: "memory")
; #define PG8_WAIT_L(n) asm volatile("s_waitcnt lgkmcnt(" #n ")" ::: "memory")
; #define PG8_BAR __builtin_amdgcn_s_barrier()
; #define PG8_SCHED __builtin_amdgcn_sched_barrier(0)
; template <class Epi, class Sched>
; __device__ __forceinline__ void gemm_phase(LAS unsigned char* lds, const Gemm g, const Sched& S, const Epi& E) {
;     ...
;       PG8_STAGE(PG8_SB(0, 1), b2 + hstep, voffB);
;       PG8_WAIT_V(6); PG8_BAR; PG8_MMA(1, 1, At, B1); PG8_BAR;
;       PG8_LDB(B0, 1, 0); PG8_SCHED; PG8_LDA(At, 1, 0); PG8_STAGE(PG8_SA(0, 1), a2 + hstep, voffA);
;       PG8_WAIT_L(8); PG8_BAR; PG8_WAIT_L(0); PG8_MMA(0, 0, At, B0); PG8_BAR; PG8_SCHED;
;       PG8_LDB(B1, 1, 1); PG8_STAGE(PG8_SB(1, 0), b3, voffB);
;       PG8_BAR; PG8_WAIT_L(0); PG8_MMA(0, 1, At, B1); PG8_BAR;
	s_add_u32 s34, s44, 0xb0000
	s_addc_u32 s35, s45, 0
	s_add_i32 s74, s75, s7
	v_lshl_add_u64 v[128:129], s[34:35], 0, v[174:175]
	s_mov_b32 m0, s74
	s_nop 0
	global_load_lds_dwordx4 v[128:129], off
	v_lshl_add_u64 v[128:129], s[34:35], 0, v[156:157]
	s_add_i32 m0, s74, 0x2000
	s_nop 0
	global_load_lds_dwordx4 v[128:129], off
	s_waitcnt vmcnt(6)
	s_barrier
	v_mfma_f32_16x16x32_bf16 v[52:55], v[208:211], v[144:147], v[52:55]
	v_mfma_f32_16x16x32_bf16 v[48:51], v[232:235], v[144:147], v[48:51]
	v_mfma_f32_16x16x32_bf16 v[36:39], v[208:211], v[152:155], v[36:39]
	v_mfma_f32_16x16x32_bf16 v[32:35], v[232:235], v[152:155], v[32:35]
	v_mfma_f32_16x16x32_bf16 v[20:23], v[208:211], v[190:193], v[20:23]
	v_mfma_f32_16x16x32_bf16 v[16:19], v[232:235], v[190:193], v[16:19]
	v_mfma_f32_16x16x32_bf16 v[4:7], v[208:211], v[198:201], v[4:7]
	v_mfma_f32_16x16x32_bf16 v[0:3], v[232:235], v[198:201], v[0:3]
	v_mfma_f32_16x16x32_bf16 v[52:55], v[226:229], v[148:151], v[52:55]
	v_mfma_f32_16x16x32_bf16 v[48:51], v[236:239], v[148:151], v[48:51]
	v_mfma_f32_16x16x32_bf16 v[36:39], v[226:229], v[186:189], v[36:39]
	v_mfma_f32_16x16x32_bf16 v[32:35], v[236:239], v[186:189], v[32:35]
	v_mfma_f32_16x16x32_bf16 v[20:23], v[226:229], v[194:197], v[20:23]
	v_mfma_f32_16x16x32_bf16 v[16:19], v[236:239], v[194:197], v[16:19]
	v_mfma_f32_16x16x32_bf16 v[4:7], v[226:229], v[204:207], v[4:7]
	v_mfma_f32_16x16x32_bf16 v[0:3], v[236:239], v[204:207], v[0:3]
	s_add_i32 s74, 0, 0x18000
	v_add_u32_e32 v140, s74, v202
	s_barrier
	ds_read_b128 v[128:131], v140
	ds_read_b128 v[132:135], v140 offset:1024
	ds_read_b128 v[136:139], v140 offset:2048
	ds_read_b128 v[140:143], v140 offset:3072
	s_add_u32 s34, s48, 0xb0000
	s_addc_u32 s35, s49, 0
	s_mov_b32 m0, s63
	v_lshl_add_u64 v[208:209], s[34:35], 0, v[176:177]
	ds_read_b128 v[144:147], v203 offset:32768
	ds_read_b128 v[148:151], v203 offset:33792
	ds_read_b128 v[152:155], v203 offset:34816
	ds_read_b128 v[186:189], v203 offset:35840
	ds_read_b128 v[190:193], v203 offset:36864
	ds_read_b128 v[194:197], v203 offset:37888
	ds_read_b128 v[198:201], v203 offset:38912
	ds_read_b128 v[204:207], v203 offset:39936
	global_load_lds_dwordx4 v[208:209], off
	v_lshl_add_u64 v[208:209], s[34:35], 0, v[158:159]
	s_mov_b32 m0, s64
	s_nop 0
	global_load_lds_dwordx4 v[208:209], off
	s_waitcnt lgkmcnt(8)
	s_barrier
	s_waitcnt lgkmcnt(0)
	s_waitcnt lgkmcnt(0)
	v_mfma_f32_16x16x32_bf16 v[124:127], v[128:131], v[144:147], v[124:127]
	v_mfma_f32_16x16x32_bf16 v[120:123], v[136:139], v[144:147], v[120:123]
	v_mfma_f32_16x16x32_bf16 v[108:111], v[128:131], v[152:155], v[108:111]
	v_mfma_f32_16x16x32_bf16 v[104:107], v[136:139], v[152:155], v[104:107]
	v_mfma_f32_16x16x32_bf16 v[92:95], v[128:131], v[190:193], v[92:95]
	v_mfma_f32_16x16x32_bf16 v[88:91], v[136:139], v[190:193], v[88:91]
	v_mfma_f32_16x16x32_bf16 v[76:79], v[128:131], v[198:201], v[76:79]
	v_mfma_f32_16x16x32_bf16 v[72:75], v[136:139], v[198:201], v[72:75]
	v_mfma_f32_16x16x32_bf16 v[124:127], v[132:135], v[148:151], v[124:127]
	v_mfma_f32_16x16x32_bf16 v[120:123], v[140:143], v[148:151], v[120:123]
	v_mfma_f32_16x16x32_bf16 v[108:111], v[132:135], v[186:189], v[108:111]
	v_mfma_f32_16x16x32_bf16 v[104:107], v[140:143], v[186:189], v[104:107]
	v_mfma_f32_16x16x32_bf16 v[92:95], v[132:135], v[194:197], v[92:95]
	v_mfma_f32_16x16x32_bf16 v[88:91], v[140:143], v[194:197], v[88:91]
	v_mfma_f32_16x16x32_bf16 v[76:79], v[132:135], v[204:207], v[76:79]
	v_mfma_f32_16x16x32_bf16 v[72:75], v[140:143], v[204:207], v[72:75]
	s_barrier
	s_add_i32 s48, 0, 0x1c000
	s_add_i32 s34, s74, s7
	v_add_u32_e32 v160, s48, v202
	v_lshl_add_u64 v[212:213], v[212:213], 0, s[80:81]
	s_mov_b32 m0, s34
	ds_read_b128 v[208:211], v160
	ds_read_b128 v[226:229], v160 offset:1024
	ds_read_b128 v[232:235], v160 offset:2048
	ds_read_b128 v[236:239], v160 offset:3072
	global_load_lds_dwordx4 v[212:213], off
	v_lshl_add_u64 v[212:213], v[222:223], 0, s[80:81]
	s_add_i32 m0, s34, 0x2000
	s_nop 0
	global_load_lds_dwordx4 v[212:213], off
	s_barrier
; #define PG8_STAGE(bufoff, gbase, voff) do { _Pragma("unroll") for (int _i = 0; _i < 2; ++_i) \
;     __builtin_amdgcn_global_load_lds((const unsigned*)((const char*)(gbase) + (voff)[_i]), (LAS unsigned*)(lds + (bufoff) + ldsw + _i * 8192), 16, 0, 0); } while (0)
; #define PG8_LDA(dst, b, h) do { _Pragma("unroll") for (int m = 0; m < 4; ++m) _Pragma("unroll") for (int k = 0; k < 2; ++k) dst[m][k] = *(const LAS bf16x8*)(lds + PG8_SA(b, h) + aoff + m * 2048 + k * 1024); } while (0)
; #define PG8_MMA(ai, bj, At, Bt) do { __builtin_amdgcn_s_setprio(1); _Pragma("unroll") for (int m = 0; m < 4; ++m) _Pragma("unroll") for (int n = 0; n < 2; ++n) _Pragma("unroll") for (int k = 0; k < 2; ++k) \
;     acc[ai][bj][m][n] = __builtin_amdgcn_mfma_f32_16x16x32_bf16(Bt[n][k], At[m][k], acc[ai][bj][m][n], 0, 0, 0); __builtin_amdgcn_s_setprio(0); } while (0)
; #define PG8_WAIT_V(n) asm volatile("s_waitcnt vmcnt(" #n ")" ::: "memory")
; #define PG8_WAIT_L(n) asm volatile("s_waitcnt lgkmcnt(" #n ")" ::: "memory")
; #define PG8_BAR __builtin_amdgcn_s_barrier()
; #define PG8_SCHED __builtin_amdgcn_sched_barrier(0)
; template <class Epi, class Sched>
; __device__ __forceinline__ void gemm_phase(LAS unsigned char* lds, const Gemm g, const Sched& S, const Epi& E) {
;     ...
;       PG8_BAR; PG8_WAIT_L(0); PG8_MMA(0, 1, At, B1); PG8_BAR;
;       PG8_LDA(At, 1, 1); PG8_STAGE(PG8_SA(1, 0), a3, voffA);
;       PG8_BAR; PG8_WAIT_L(0); PG8_MMA(1, 0, At, B0); PG8_BAR; PG8_SCHED;
;       PG8_STAGE(PG8_SB(1, 1), b3 + hstep, voffB);
;       PG8_WAIT_V(6); PG8_BAR; PG8_MMA(1, 1, At, B1); PG8_BAR;
;     }
	s_waitcnt lgkmcnt(0)
	s_waitcnt lgkmcnt(0)
	v_mfma_f32_16x16x32_bf16 v[116:119], v[208:211], v[144:147], v[116:119]
	v_mfma_f32_16x16x32_bf16 v[112:115], v[232:235], v[144:147], v[112:115]
	v_mfma_f32_16x16x32_bf16 v[100:103], v[208:211], v[152:155], v[100:103]
	v_mfma_f32_16x16x32_bf16 v[96:99], v[232:235], v[152:155], v[96:99]
	v_mfma_f32_16x16x32_bf16 v[84:87], v[208:211], v[190:193], v[84:87]
	v_mfma_f32_16x16x32_bf16 v[80:83], v[232:235], v[190:193], v[80:83]
	v_mfma_f32_16x16x32_bf16 v[68:71], v[208:211], v[198:201], v[68:71]
	v_mfma_f32_16x16x32_bf16 v[64:67], v[232:235], v[198:201], v[64:67]
	v_mfma_f32_16x16x32_bf16 v[116:119], v[226:229], v[148:151], v[116:119]
	v_mfma_f32_16x16x32_bf16 v[112:115], v[236:239], v[148:151], v[112:115]
	v_mfma_f32_16x16x32_bf16 v[100:103], v[226:229], v[186:189], v[100:103]
	v_mfma_f32_16x16x32_bf16 v[96:99], v[236:239], v[186:189], v[96:99]
	v_mfma_f32_16x16x32_bf16 v[84:87], v[226:229], v[194:197], v[84:87]
	v_mfma_f32_16x16x32_bf16 v[80:83], v[236:239], v[194:197], v[80:83]
	v_mfma_f32_16x16x32_bf16 v[68:71], v[226:229], v[204:207], v[68:71]
	v_mfma_f32_16x16x32_bf16 v[64:67], v[236:239], v[204:207], v[64:67]
	s_mov_b32 m0, s65
	v_lshl_add_u64 v[212:213], v[240:241], 0, s[80:81]
	s_barrier
	ds_read_b128 v[144:147], v203 offset:49152
	ds_read_b128 v[148:151], v203 offset:50176
	ds_read_b128 v[152:155], v203 offset:51200
	ds_read_b128 v[186:189], v203 offset:52224
	ds_read_b128 v[190:193], v203 offset:53248
	ds_read_b128 v[194:197], v203 offset:54272
	ds_read_b128 v[198:201], v203 offset:55296
	ds_read_b128 v[204:207], v203 offset:56320
	global_load_lds_dwordx4 v[212:213], off
	v_lshl_add_u64 v[212:213], v[242:243], 0, s[80:81]
	s_mov_b32 m0, s70
	s_nop 0
	global_load_lds_dwordx4 v[212:213], off
	s_barrier
	s_waitcnt lgkmcnt(0)
	s_waitcnt lgkmcnt(0)
	v_mfma_f32_16x16x32_bf16 v[60:63], v[128:131], v[144:147], v[60:63]
	v_mfma_f32_16x16x32_bf16 v[56:59], v[136:139], v[144:147], v[56:59]
	v_mfma_f32_16x16x32_bf16 v[44:47], v[128:131], v[152:155], v[44:47]
	v_mfma_f32_16x16x32_bf16 v[40:43], v[136:139], v[152:155], v[40:43]
	v_mfma_f32_16x16x32_bf16 v[28:31], v[128:131], v[190:193], v[28:31]
	v_mfma_f32_16x16x32_bf16 v[24:27], v[136:139], v[190:193], v[24:27]
	v_mfma_f32_16x16x32_bf16 v[12:15], v[128:131], v[198:201], v[12:15]
	v_mfma_f32_16x16x32_bf16 v[8:11], v[136:139], v[198:201], v[8:11]
	v_mfma_f32_16x16x32_bf16 v[60:63], v[132:135], v[148:151], v[60:63]
	v_mfma_f32_16x16x32_bf16 v[56:59], v[140:143], v[148:151], v[56:59]
	v_mfma_f32_16x16x32_bf16 v[44:47], v[132:135], v[186:189], v[44:47]
	v_mfma_f32_16x16x32_bf16 v[40:43], v[140:143], v[186:189], v[40:43]
	v_mfma_f32_16x16x32_bf16 v[28:31], v[132:135], v[194:197], v[28:31]
	v_mfma_f32_16x16x32_bf16 v[24:27], v[140:143], v[194:197], v[24:27]
	v_mfma_f32_16x16x32_bf16 v[12:15], v[132:135], v[204:207], v[12:15]
	v_mfma_f32_16x16x32_bf16 v[8:11], v[140:143], v[204:207], v[8:11]
	s_barrier
	s_add_u32 s34, s44, 0xb0080
	s_addc_u32 s35, s45, 0
	s_add_i32 s44, s48, s7
	v_lshl_add_u64 v[128:129], s[34:35], 0, v[174:175]
	s_mov_b32 m0, s44
	s_nop 0
	global_load_lds_dwordx4 v[128:129], off
	v_lshl_add_u64 v[128:129], s[34:35], 0, v[156:157]
	s_add_i32 m0, s44, 0x2000
	s_nop 0
	global_load_lds_dwordx4 v[128:129], off
	s_waitcnt vmcnt(6)
	s_barrier
	v_mfma_f32_16x16x32_bf16 v[52:55], v[208:211], v[144:147], v[52:55]
	v_mfma_f32_16x16x32_bf16 v[48:51], v[232:235], v[144:147], v[48:51]
	v_mfma_f32_16x16x32_bf16 v[36:39], v[208:211], v[152:155], v[36:39]
	v_mfma_f32_16x16x32_bf16 v[32:35], v[232:235], v[152:155], v[32:35]
	v_mfma_f32_16x16x32_bf16 v[20:23], v[208:211], v[190:193], v[20:23]
	v_mfma_f32_16x16x32_bf16 v[16:19], v[232:235], v[190:193], v[16:19]
	v_mfma_f32_16x16x32_bf16 v[4:7], v[208:211], v[198:201], v[4:7]
	v_mfma_f32_16x16x32_bf16 v[0:3], v[232:235], v[198:201], v[0:3]
	v_mfma_f32_16x16x32_bf16 v[52:55], v[226:229], v[148:151], v[52:55]
	v_mfma_f32_16x16x32_bf16 v[48:51], v[236:239], v[148:151], v[48:51]
	v_mfma_f32_16x16x32_bf16 v[36:39], v[226:229], v[186:189], v[36:39]
	v_mfma_f32_16x16x32_bf16 v[32:35], v[236:239], v[186:189], v[32:35]
	v_mfma_f32_16x16x32_bf16 v[20:23], v[226:229], v[194:197], v[20:23]
	v_mfma_f32_16x16x32_bf16 v[16:19], v[236:239], v[194:197], v[16:19]
	v_mfma_f32_16x16x32_bf16 v[4:7], v[226:229], v[204:207], v[4:7]
	v_mfma_f32_16x16x32_bf16 v[0:3], v[236:239], v[204:207], v[0:3]
	s_add_i32 s73, s73, 2
	s_add_u32 s52, s52, 0x100
	s_addc_u32 s72, s72, 0
	s_cmp_gt_u32 s73, 41
	s_mov_b64 s[34:35], s[42:43]
	s_barrier
	s_cbranch_scc0 .LBB0_1215
	s_cmp_lt_u32 s101, 0x100
	s_cbranch_scc0 .Lxa_11
	s_barrier
